# early barrier K2 + removed redundant lgkmcnt waits and mid-segment setprio pair in MFMA segments
# baseline (speedup 1.0000x reference)
.LBB0_344:
	ds_read_b128 v[148:151], v143
	ds_read_b128 v[152:155], v143 offset:1024
	ds_read_b128 v[156:159], v143 offset:2048
	ds_read_b128 v[160:163], v143 offset:3072
	ds_read_b128 v[164:167], v144
	ds_read_b128 v[168:171], v144 offset:1024
	ds_read_b128 v[172:175], v144 offset:2048
	ds_read_b128 v[176:179], v144 offset:3072
	s_cmp_eq_u32 s81, 28
	s_cselect_b32 s21, s9, s78
	s_cselect_b32 s20, s76, s77
	s_cselect_b32 s23, s11, s80
	s_cselect_b32 s22, s75, s79
	ds_read_b128 v[180:183], v145
	ds_read_b128 v[184:187], v145 offset:1024
	ds_read_b128 v[188:191], v145 offset:2048
	ds_read_b128 v[192:195], v145 offset:3072
	ds_read_b128 v[196:199], v145 offset:4096
	ds_read_b128 v[200:203], v145 offset:5120
	ds_read_b128 v[204:207], v145 offset:6144
	ds_read_b128 v[208:211], v145 offset:7168
	s_add_u32 s82, s18, 0xfff80000
	s_addc_u32 s83, s19, -1
	s_mov_b32 s86, m0
	s_mov_b32 m0, s64
	s_nop 0
	global_load_lds_dwordx4 v138, s[82:83]
	s_mov_b32 m0, s86
	s_nop 0
	s_mov_b32 s86, m0
	s_mov_b32 m0, s67
	s_nop 0
	global_load_lds_dwordx4 v140, s[82:83]
	s_mov_b32 m0, s86
	s_mov_b32 s82, m0
	s_mov_b32 m0, s65
	s_nop 0
	global_load_lds_dwordx4 v138, s[18:19]
	s_mov_b32 m0, s82
	s_nop 0
	s_mov_b32 s82, m0
	s_mov_b32 m0, s73
	s_nop 0
	global_load_lds_dwordx4 v140, s[18:19]
	s_mov_b32 m0, s82
	s_waitcnt vmcnt(8)
	s_waitcnt lgkmcnt(0)
	s_barrier
	s_setprio 1
	v_mfma_f32_16x16x32_bf16 v[126:129], v[148:151], v[180:183], v[126:129]
	v_mfma_f32_16x16x32_bf16 v[122:125], v[156:159], v[180:183], v[122:125]
	v_mfma_f32_16x16x32_bf16 v[110:113], v[148:151], v[188:191], v[110:113]
	v_mfma_f32_16x16x32_bf16 v[106:109], v[156:159], v[188:191], v[106:109]
	v_mfma_f32_16x16x32_bf16 v[94:97], v[148:151], v[196:199], v[94:97]
	v_mfma_f32_16x16x32_bf16 v[90:93], v[156:159], v[196:199], v[90:93]
	v_mfma_f32_16x16x32_bf16 v[78:81], v[148:151], v[204:207], v[78:81]
	v_mfma_f32_16x16x32_bf16 v[74:77], v[156:159], v[204:207], v[74:77]
	v_mfma_f32_16x16x32_bf16 v[126:129], v[152:155], v[184:187], v[126:129]
	v_mfma_f32_16x16x32_bf16 v[122:125], v[160:163], v[184:187], v[122:125]
	v_mfma_f32_16x16x32_bf16 v[110:113], v[152:155], v[192:195], v[110:113]
	v_mfma_f32_16x16x32_bf16 v[106:109], v[160:163], v[192:195], v[106:109]
	v_mfma_f32_16x16x32_bf16 v[94:97], v[152:155], v[200:203], v[94:97]
	v_mfma_f32_16x16x32_bf16 v[90:93], v[160:163], v[200:203], v[90:93]
	v_mfma_f32_16x16x32_bf16 v[78:81], v[152:155], v[208:211], v[78:81]
	v_mfma_f32_16x16x32_bf16 v[74:77], v[160:163], v[208:211], v[74:77]
	v_mfma_f32_16x16x32_bf16 v[118:121], v[164:167], v[180:183], v[118:121]
	v_mfma_f32_16x16x32_bf16 v[114:117], v[172:175], v[180:183], v[114:117]
	v_mfma_f32_16x16x32_bf16 v[102:105], v[164:167], v[188:191], v[102:105]
	v_mfma_f32_16x16x32_bf16 v[98:101], v[172:175], v[188:191], v[98:101]
	v_mfma_f32_16x16x32_bf16 v[86:89], v[164:167], v[196:199], v[86:89]
	v_mfma_f32_16x16x32_bf16 v[82:85], v[172:175], v[196:199], v[82:85]
	v_mfma_f32_16x16x32_bf16 v[70:73], v[164:167], v[204:207], v[70:73]
	v_mfma_f32_16x16x32_bf16 v[66:69], v[172:175], v[204:207], v[66:69]
	v_mfma_f32_16x16x32_bf16 v[118:121], v[168:171], v[184:187], v[118:121]
	v_mfma_f32_16x16x32_bf16 v[114:117], v[176:179], v[184:187], v[114:117]
	v_mfma_f32_16x16x32_bf16 v[102:105], v[168:171], v[192:195], v[102:105]
	v_mfma_f32_16x16x32_bf16 v[98:101], v[176:179], v[192:195], v[98:101]
	v_mfma_f32_16x16x32_bf16 v[86:89], v[168:171], v[200:203], v[86:89]
	v_mfma_f32_16x16x32_bf16 v[82:85], v[176:179], v[200:203], v[82:85]
	s_setprio 2
	s_barrier
	v_mfma_f32_16x16x32_bf16 v[70:73], v[168:171], v[208:211], v[70:73]
	v_mfma_f32_16x16x32_bf16 v[66:69], v[176:179], v[208:211], v[66:69]
	s_setprio 0
	ds_read_b128 v[180:183], v145 offset:16384
	ds_read_b128 v[184:187], v145 offset:17408
	ds_read_b128 v[188:191], v145 offset:18432
	ds_read_b128 v[192:195], v145 offset:19456
	ds_read_b128 v[196:199], v145 offset:20480
	ds_read_b128 v[200:203], v145 offset:21504
	ds_read_b128 v[204:207], v145 offset:22528
	ds_read_b128 v[208:211], v145 offset:23552
	s_mov_b32 s82, m0
	s_mov_b32 m0, s35
	s_nop 0
	global_load_lds_dwordx4 v139, s[20:21]
	s_mov_b32 m0, s82
	s_nop 0
	s_mov_b32 s82, m0
	s_mov_b32 m0, s36
	s_nop 0
	global_load_lds_dwordx4 v141, s[20:21]
	s_mov_b32 m0, s82
	s_add_u32 s82, s20, 0x80000
	s_addc_u32 s83, s21, 0
	s_mov_b32 s86, m0
	s_mov_b32 m0, s37
	s_nop 0
	global_load_lds_dwordx4 v139, s[82:83]
	s_mov_b32 m0, s86
	s_nop 0
	s_mov_b32 s86, m0
	s_mov_b32 m0, s42
	s_nop 0
	global_load_lds_dwordx4 v141, s[82:83]
	s_mov_b32 m0, s86
	s_waitcnt vmcnt(4)
	s_waitcnt lgkmcnt(0)
	s_barrier
	s_setprio 1
	v_mfma_f32_16x16x32_bf16 v[62:65], v[148:151], v[180:183], v[62:65]
	v_mfma_f32_16x16x32_bf16 v[58:61], v[156:159], v[180:183], v[58:61]
	v_mfma_f32_16x16x32_bf16 v[46:49], v[148:151], v[188:191], v[46:49]
	v_mfma_f32_16x16x32_bf16 v[42:45], v[156:159], v[188:191], v[42:45]
	v_mfma_f32_16x16x32_bf16 v[30:33], v[148:151], v[196:199], v[30:33]
	v_mfma_f32_16x16x32_bf16 v[26:29], v[156:159], v[196:199], v[26:29]
	v_mfma_f32_16x16x32_bf16 v[14:17], v[148:151], v[204:207], v[14:17]
	v_mfma_f32_16x16x32_bf16 v[10:13], v[156:159], v[204:207], v[10:13]
	v_mfma_f32_16x16x32_bf16 v[62:65], v[152:155], v[184:187], v[62:65]
	v_mfma_f32_16x16x32_bf16 v[58:61], v[160:163], v[184:187], v[58:61]
	v_mfma_f32_16x16x32_bf16 v[46:49], v[152:155], v[192:195], v[46:49]
	v_mfma_f32_16x16x32_bf16 v[42:45], v[160:163], v[192:195], v[42:45]
	v_mfma_f32_16x16x32_bf16 v[30:33], v[152:155], v[200:203], v[30:33]
	v_mfma_f32_16x16x32_bf16 v[26:29], v[160:163], v[200:203], v[26:29]
	v_mfma_f32_16x16x32_bf16 v[14:17], v[152:155], v[208:211], v[14:17]
	v_mfma_f32_16x16x32_bf16 v[10:13], v[160:163], v[208:211], v[10:13]
	v_mfma_f32_16x16x32_bf16 v[54:57], v[164:167], v[180:183], v[54:57]
	v_mfma_f32_16x16x32_bf16 v[50:53], v[172:175], v[180:183], v[50:53]
	v_mfma_f32_16x16x32_bf16 v[38:41], v[164:167], v[188:191], v[38:41]
	v_mfma_f32_16x16x32_bf16 v[34:37], v[172:175], v[188:191], v[34:37]
	v_mfma_f32_16x16x32_bf16 v[22:25], v[164:167], v[196:199], v[22:25]
	v_mfma_f32_16x16x32_bf16 v[18:21], v[172:175], v[196:199], v[18:21]
	v_mfma_f32_16x16x32_bf16 v[6:9], v[164:167], v[204:207], v[6:9]
	v_mfma_f32_16x16x32_bf16 v[2:5], v[172:175], v[204:207], v[2:5]
	v_mfma_f32_16x16x32_bf16 v[54:57], v[168:171], v[184:187], v[54:57]
	v_mfma_f32_16x16x32_bf16 v[50:53], v[176:179], v[184:187], v[50:53]
	v_mfma_f32_16x16x32_bf16 v[38:41], v[168:171], v[192:195], v[38:41]
	v_mfma_f32_16x16x32_bf16 v[34:37], v[176:179], v[192:195], v[34:37]
	v_mfma_f32_16x16x32_bf16 v[22:25], v[168:171], v[200:203], v[22:25]
	v_mfma_f32_16x16x32_bf16 v[18:21], v[176:179], v[200:203], v[18:21]
	s_setprio 2
	s_barrier
	v_mfma_f32_16x16x32_bf16 v[6:9], v[168:171], v[208:211], v[6:9]
	v_mfma_f32_16x16x32_bf16 v[2:5], v[176:179], v[208:211], v[2:5]
	s_setprio 0
	ds_read_b128 v[148:151], v146
	ds_read_b128 v[152:155], v146 offset:1024
	ds_read_b128 v[156:159], v146 offset:2048
	ds_read_b128 v[160:163], v146 offset:3072
	ds_read_b128 v[164:167], v147
	ds_read_b128 v[168:171], v147 offset:1024
	ds_read_b128 v[172:175], v147 offset:2048
	ds_read_b128 v[176:179], v147 offset:3072
	ds_read_b128 v[180:183], v145 offset:32768
	ds_read_b128 v[184:187], v145 offset:33792
	ds_read_b128 v[188:191], v145 offset:34816
	ds_read_b128 v[192:195], v145 offset:35840
	ds_read_b128 v[196:199], v145 offset:36864
	ds_read_b128 v[200:203], v145 offset:37888
	ds_read_b128 v[204:207], v145 offset:38912
	ds_read_b128 v[208:211], v145 offset:39936
	s_mov_b32 s82, m0
	s_mov_b32 m0, s31
	s_nop 0
	global_load_lds_dwordx4 v138, s[22:23]
	s_mov_b32 m0, s82
	s_nop 0
	s_mov_b32 s82, m0
	s_mov_b32 m0, s43
	s_nop 0
	global_load_lds_dwordx4 v140, s[22:23]
	s_mov_b32 m0, s82
	s_add_u32 s22, s22, 0x80000
	s_addc_u32 s23, s23, 0
	s_mov_b32 s82, m0
	s_mov_b32 m0, s46
	s_nop 0
	global_load_lds_dwordx4 v138, s[22:23]
	s_mov_b32 m0, s82
	s_nop 0
	s_mov_b32 s82, m0
	s_mov_b32 m0, s47
	s_nop 0
	global_load_lds_dwordx4 v140, s[22:23]
	s_mov_b32 m0, s82
	s_waitcnt vmcnt(8)
	s_waitcnt lgkmcnt(0)
	s_barrier
	s_setprio 1
	v_mfma_f32_16x16x32_bf16 v[126:129], v[148:151], v[180:183], v[126:129]
	v_mfma_f32_16x16x32_bf16 v[122:125], v[156:159], v[180:183], v[122:125]
	v_mfma_f32_16x16x32_bf16 v[110:113], v[148:151], v[188:191], v[110:113]
	v_mfma_f32_16x16x32_bf16 v[106:109], v[156:159], v[188:191], v[106:109]
	v_mfma_f32_16x16x32_bf16 v[94:97], v[148:151], v[196:199], v[94:97]
	v_mfma_f32_16x16x32_bf16 v[90:93], v[156:159], v[196:199], v[90:93]
	v_mfma_f32_16x16x32_bf16 v[78:81], v[148:151], v[204:207], v[78:81]
	v_mfma_f32_16x16x32_bf16 v[74:77], v[156:159], v[204:207], v[74:77]
	v_mfma_f32_16x16x32_bf16 v[126:129], v[152:155], v[184:187], v[126:129]
	v_mfma_f32_16x16x32_bf16 v[122:125], v[160:163], v[184:187], v[122:125]
	v_mfma_f32_16x16x32_bf16 v[110:113], v[152:155], v[192:195], v[110:113]
	v_mfma_f32_16x16x32_bf16 v[106:109], v[160:163], v[192:195], v[106:109]
	v_mfma_f32_16x16x32_bf16 v[94:97], v[152:155], v[200:203], v[94:97]
	v_mfma_f32_16x16x32_bf16 v[90:93], v[160:163], v[200:203], v[90:93]
	v_mfma_f32_16x16x32_bf16 v[78:81], v[152:155], v[208:211], v[78:81]
	v_mfma_f32_16x16x32_bf16 v[74:77], v[160:163], v[208:211], v[74:77]
	v_mfma_f32_16x16x32_bf16 v[118:121], v[164:167], v[180:183], v[118:121]
	v_mfma_f32_16x16x32_bf16 v[114:117], v[172:175], v[180:183], v[114:117]
	v_mfma_f32_16x16x32_bf16 v[102:105], v[164:167], v[188:191], v[102:105]
	v_mfma_f32_16x16x32_bf16 v[98:101], v[172:175], v[188:191], v[98:101]
	v_mfma_f32_16x16x32_bf16 v[86:89], v[164:167], v[196:199], v[86:89]
	v_mfma_f32_16x16x32_bf16 v[82:85], v[172:175], v[196:199], v[82:85]
	v_mfma_f32_16x16x32_bf16 v[70:73], v[164:167], v[204:207], v[70:73]
	v_mfma_f32_16x16x32_bf16 v[66:69], v[172:175], v[204:207], v[66:69]
	v_mfma_f32_16x16x32_bf16 v[118:121], v[168:171], v[184:187], v[118:121]
	v_mfma_f32_16x16x32_bf16 v[114:117], v[176:179], v[184:187], v[114:117]
	v_mfma_f32_16x16x32_bf16 v[102:105], v[168:171], v[192:195], v[102:105]
	v_mfma_f32_16x16x32_bf16 v[98:101], v[176:179], v[192:195], v[98:101]
	v_mfma_f32_16x16x32_bf16 v[86:89], v[168:171], v[200:203], v[86:89]
	v_mfma_f32_16x16x32_bf16 v[82:85], v[176:179], v[200:203], v[82:85]
	s_setprio 2
	s_barrier
	v_mfma_f32_16x16x32_bf16 v[70:73], v[168:171], v[208:211], v[70:73]
	v_mfma_f32_16x16x32_bf16 v[66:69], v[176:179], v[208:211], v[66:69]
	s_setprio 0
	ds_read_b128 v[180:183], v145 offset:49152
	ds_read_b128 v[184:187], v145 offset:50176
	ds_read_b128 v[188:191], v145 offset:51200
	ds_read_b128 v[192:195], v145 offset:52224
	ds_read_b128 v[196:199], v145 offset:53248
	ds_read_b128 v[200:203], v145 offset:54272
	ds_read_b128 v[204:207], v145 offset:55296
	ds_read_b128 v[208:211], v145 offset:56320
	s_add_u32 s22, s20, 0x80
	s_addc_u32 s23, s21, 0
	s_mov_b32 s82, m0
	s_mov_b32 m0, s48
	s_nop 0
	global_load_lds_dwordx4 v139, s[22:23]
	s_mov_b32 m0, s82
	s_add_u32 s20, s20, 0x80080
	s_mov_b32 s82, m0
	s_mov_b32 m0, s49
	s_nop 0
	global_load_lds_dwordx4 v141, s[22:23]
	s_mov_b32 m0, s82
	s_addc_u32 s21, s21, 0
	s_mov_b32 s22, m0
	s_mov_b32 m0, s56
	s_nop 0
	global_load_lds_dwordx4 v139, s[20:21]
	s_mov_b32 m0, s22
	s_nop 0
	s_mov_b32 s22, m0
	s_mov_b32 m0, s57
	s_nop 0
	global_load_lds_dwordx4 v141, s[20:21]
	s_mov_b32 m0, s22
	s_waitcnt vmcnt(4)
	s_waitcnt lgkmcnt(0)
	s_barrier
	s_setprio 1
	v_mfma_f32_16x16x32_bf16 v[62:65], v[148:151], v[180:183], v[62:65]
	v_mfma_f32_16x16x32_bf16 v[58:61], v[156:159], v[180:183], v[58:61]
	v_mfma_f32_16x16x32_bf16 v[46:49], v[148:151], v[188:191], v[46:49]
	v_mfma_f32_16x16x32_bf16 v[42:45], v[156:159], v[188:191], v[42:45]
	v_mfma_f32_16x16x32_bf16 v[30:33], v[148:151], v[196:199], v[30:33]
	v_mfma_f32_16x16x32_bf16 v[26:29], v[156:159], v[196:199], v[26:29]
	v_mfma_f32_16x16x32_bf16 v[14:17], v[148:151], v[204:207], v[14:17]
	v_mfma_f32_16x16x32_bf16 v[10:13], v[156:159], v[204:207], v[10:13]
	v_mfma_f32_16x16x32_bf16 v[62:65], v[152:155], v[184:187], v[62:65]
	v_mfma_f32_16x16x32_bf16 v[58:61], v[160:163], v[184:187], v[58:61]
	v_mfma_f32_16x16x32_bf16 v[46:49], v[152:155], v[192:195], v[46:49]
	v_mfma_f32_16x16x32_bf16 v[42:45], v[160:163], v[192:195], v[42:45]
	v_mfma_f32_16x16x32_bf16 v[30:33], v[152:155], v[200:203], v[30:33]
	v_mfma_f32_16x16x32_bf16 v[26:29], v[160:163], v[200:203], v[26:29]
	v_mfma_f32_16x16x32_bf16 v[14:17], v[152:155], v[208:211], v[14:17]
	v_mfma_f32_16x16x32_bf16 v[10:13], v[160:163], v[208:211], v[10:13]
	v_mfma_f32_16x16x32_bf16 v[54:57], v[164:167], v[180:183], v[54:57]
	v_mfma_f32_16x16x32_bf16 v[50:53], v[172:175], v[180:183], v[50:53]
	v_mfma_f32_16x16x32_bf16 v[38:41], v[164:167], v[188:191], v[38:41]
	v_mfma_f32_16x16x32_bf16 v[34:37], v[172:175], v[188:191], v[34:37]
	v_mfma_f32_16x16x32_bf16 v[22:25], v[164:167], v[196:199], v[22:25]
	v_mfma_f32_16x16x32_bf16 v[18:21], v[172:175], v[196:199], v[18:21]
	v_mfma_f32_16x16x32_bf16 v[6:9], v[164:167], v[204:207], v[6:9]
	v_mfma_f32_16x16x32_bf16 v[2:5], v[172:175], v[204:207], v[2:5]
	v_mfma_f32_16x16x32_bf16 v[54:57], v[168:171], v[184:187], v[54:57]
	v_mfma_f32_16x16x32_bf16 v[50:53], v[176:179], v[184:187], v[50:53]
	v_mfma_f32_16x16x32_bf16 v[38:41], v[168:171], v[192:195], v[38:41]
	v_mfma_f32_16x16x32_bf16 v[34:37], v[176:179], v[192:195], v[34:37]
	v_mfma_f32_16x16x32_bf16 v[22:25], v[168:171], v[200:203], v[22:25]
	v_mfma_f32_16x16x32_bf16 v[18:21], v[176:179], v[200:203], v[18:21]
	s_setprio 2
	s_barrier
	v_mfma_f32_16x16x32_bf16 v[6:9], v[168:171], v[208:211], v[6:9]
	v_mfma_f32_16x16x32_bf16 v[2:5], v[176:179], v[208:211], v[2:5]
	s_setprio 0
	s_add_i32 s81, s81, 2
	s_add_u32 s77, s77, 0x100
	s_addc_u32 s78, s78, 0
	s_add_u32 s18, s18, 0x100
	s_addc_u32 s19, s19, 0
	s_add_u32 s79, s79, 0x100
	s_addc_u32 s80, s80, 0
	s_cmp_gt_u32 s81, 29
	s_cbranch_scc0 .LBB0_344
	s_and_b64 vcc, exec, s[6:7]
	s_cbranch_vccz .LBB0_347
	s_barrier

.LBB0_473:
	ds_read_b128 v[134:137], v161
	ds_read_b128 v[138:141], v161 offset:1024
	ds_read_b128 v[142:145], v161 offset:2048
	ds_read_b128 v[146:149], v161 offset:3072
	ds_read_b128 v[150:153], v162
	ds_read_b128 v[166:169], v162 offset:1024
	ds_read_b128 v[170:173], v162 offset:2048
	ds_read_b128 v[174:177], v162 offset:3072
	s_cmpk_eq_i32 s82, 0x52
	s_cselect_b32 s23, s11, s79
	s_cselect_b32 s22, s77, s78
	s_cselect_b32 s25, s13, s81
	s_cselect_b32 s24, s76, s80
	ds_read_b128 v[178:181], v163
	ds_read_b128 v[182:185], v163 offset:1024
	ds_read_b128 v[186:189], v163 offset:2048
	ds_read_b128 v[190:193], v163 offset:3072
	ds_read_b128 v[194:197], v163 offset:4096
	ds_read_b128 v[198:201], v163 offset:5120
	ds_read_b128 v[202:205], v163 offset:6144
	ds_read_b128 v[206:209], v163 offset:7168
	s_add_u32 s86, s20, 0xffffc000
	s_addc_u32 s87, s21, -1
	s_mov_b32 s83, m0
	s_mov_b32 m0, s65
	s_nop 0
	global_load_lds_dwordx4 v1, s[86:87]
	s_mov_b32 m0, s83
	s_nop 0
	s_mov_b32 s83, m0
	s_mov_b32 m0, s67
	s_nop 0
	global_load_lds_dwordx4 v157, s[86:87]
	s_mov_b32 m0, s83
	s_nop 0
	s_mov_b32 s83, m0
	s_mov_b32 m0, s66
	s_nop 0
	global_load_lds_dwordx4 v1, s[20:21]
	s_mov_b32 m0, s83
	s_nop 0
	s_mov_b32 s83, m0
	s_mov_b32 m0, s73
	s_nop 0
	global_load_lds_dwordx4 v157, s[20:21]
	s_mov_b32 m0, s83
	s_waitcnt vmcnt(8)
	s_waitcnt lgkmcnt(0)
	s_barrier
	s_setprio 1
	v_mfma_f32_16x16x32_bf16 v[126:129], v[134:137], v[178:181], v[126:129]
	v_mfma_f32_16x16x32_bf16 v[122:125], v[142:145], v[178:181], v[122:125]
	v_mfma_f32_16x16x32_bf16 v[118:121], v[134:137], v[186:189], v[118:121]
	v_mfma_f32_16x16x32_bf16 v[114:117], v[142:145], v[186:189], v[114:117]
	v_mfma_f32_16x16x32_bf16 v[102:105], v[134:137], v[194:197], v[102:105]
	v_mfma_f32_16x16x32_bf16 v[94:97], v[142:145], v[194:197], v[94:97]
	v_mfma_f32_16x16x32_bf16 v[86:89], v[134:137], v[202:205], v[86:89]
	v_mfma_f32_16x16x32_bf16 v[78:81], v[142:145], v[202:205], v[78:81]
	v_mfma_f32_16x16x32_bf16 v[126:129], v[138:141], v[182:185], v[126:129]
	v_mfma_f32_16x16x32_bf16 v[122:125], v[146:149], v[182:185], v[122:125]
	v_mfma_f32_16x16x32_bf16 v[118:121], v[138:141], v[190:193], v[118:121]
	v_mfma_f32_16x16x32_bf16 v[114:117], v[146:149], v[190:193], v[114:117]
	v_mfma_f32_16x16x32_bf16 v[102:105], v[138:141], v[198:201], v[102:105]
	v_mfma_f32_16x16x32_bf16 v[94:97], v[146:149], v[198:201], v[94:97]
	v_mfma_f32_16x16x32_bf16 v[86:89], v[138:141], v[206:209], v[86:89]
	v_mfma_f32_16x16x32_bf16 v[78:81], v[146:149], v[206:209], v[78:81]
	v_mfma_f32_16x16x32_bf16 v[110:113], v[150:153], v[178:181], v[110:113]
	v_mfma_f32_16x16x32_bf16 v[106:109], v[170:173], v[178:181], v[106:109]
	v_mfma_f32_16x16x32_bf16 v[98:101], v[150:153], v[186:189], v[98:101]
	v_mfma_f32_16x16x32_bf16 v[90:93], v[170:173], v[186:189], v[90:93]
	v_mfma_f32_16x16x32_bf16 v[82:85], v[150:153], v[194:197], v[82:85]
	v_mfma_f32_16x16x32_bf16 v[74:77], v[170:173], v[194:197], v[74:77]
	v_mfma_f32_16x16x32_bf16 v[70:73], v[150:153], v[202:205], v[70:73]
	v_mfma_f32_16x16x32_bf16 v[66:69], v[170:173], v[202:205], v[66:69]
	v_mfma_f32_16x16x32_bf16 v[110:113], v[166:169], v[182:185], v[110:113]
	v_mfma_f32_16x16x32_bf16 v[106:109], v[174:177], v[182:185], v[106:109]
	v_mfma_f32_16x16x32_bf16 v[98:101], v[166:169], v[190:193], v[98:101]
	v_mfma_f32_16x16x32_bf16 v[90:93], v[174:177], v[190:193], v[90:93]
	v_mfma_f32_16x16x32_bf16 v[82:85], v[166:169], v[198:201], v[82:85]
	v_mfma_f32_16x16x32_bf16 v[74:77], v[174:177], v[198:201], v[74:77]
	s_setprio 2
	s_barrier
	v_mfma_f32_16x16x32_bf16 v[70:73], v[166:169], v[206:209], v[70:73]
	v_mfma_f32_16x16x32_bf16 v[66:69], v[174:177], v[206:209], v[66:69]
	s_setprio 0
	ds_read_b128 v[178:181], v163 offset:16384
	ds_read_b128 v[182:185], v163 offset:17408
	ds_read_b128 v[186:189], v163 offset:18432
	ds_read_b128 v[190:193], v163 offset:19456
	ds_read_b128 v[194:197], v163 offset:20480
	ds_read_b128 v[198:201], v163 offset:21504
	ds_read_b128 v[202:205], v163 offset:22528
	ds_read_b128 v[206:209], v163 offset:23552
	s_mov_b32 s83, m0
	s_mov_b32 m0, s19
	s_nop 0
	global_load_lds_dwordx4 v156, s[22:23]
	s_mov_b32 m0, s83
	s_add_u32 s86, s22, 0x4000
	s_mov_b32 s83, m0
	s_mov_b32 m0, s35
	s_nop 0
	global_load_lds_dwordx4 v158, s[22:23]
	s_mov_b32 m0, s83
	s_addc_u32 s87, s23, 0
	s_mov_b32 s83, m0
	s_mov_b32 m0, s36
	s_nop 0
	global_load_lds_dwordx4 v156, s[86:87]
	s_mov_b32 m0, s83
	s_nop 0
	s_mov_b32 s83, m0
	s_mov_b32 m0, s37
	s_nop 0
	global_load_lds_dwordx4 v158, s[86:87]
	s_mov_b32 m0, s83
	s_waitcnt vmcnt(4)
	s_waitcnt lgkmcnt(0)
	s_barrier
	s_setprio 1
	v_mfma_f32_16x16x32_bf16 v[62:65], v[134:137], v[178:181], v[62:65]
	v_mfma_f32_16x16x32_bf16 v[58:61], v[142:145], v[178:181], v[58:61]
	v_mfma_f32_16x16x32_bf16 v[54:57], v[134:137], v[186:189], v[54:57]
	v_mfma_f32_16x16x32_bf16 v[46:49], v[142:145], v[186:189], v[46:49]
	v_mfma_f32_16x16x32_bf16 v[38:41], v[134:137], v[194:197], v[38:41]
	v_mfma_f32_16x16x32_bf16 v[30:33], v[142:145], v[194:197], v[30:33]
	v_mfma_f32_16x16x32_bf16 v[22:25], v[134:137], v[202:205], v[22:25]
	v_mfma_f32_16x16x32_bf16 v[14:17], v[142:145], v[202:205], v[14:17]
	v_mfma_f32_16x16x32_bf16 v[62:65], v[138:141], v[182:185], v[62:65]
	v_mfma_f32_16x16x32_bf16 v[58:61], v[146:149], v[182:185], v[58:61]
	v_mfma_f32_16x16x32_bf16 v[54:57], v[138:141], v[190:193], v[54:57]
	v_mfma_f32_16x16x32_bf16 v[46:49], v[146:149], v[190:193], v[46:49]
	v_mfma_f32_16x16x32_bf16 v[38:41], v[138:141], v[198:201], v[38:41]
	v_mfma_f32_16x16x32_bf16 v[30:33], v[146:149], v[198:201], v[30:33]
	v_mfma_f32_16x16x32_bf16 v[22:25], v[138:141], v[206:209], v[22:25]
	v_mfma_f32_16x16x32_bf16 v[14:17], v[146:149], v[206:209], v[14:17]
	v_mfma_f32_16x16x32_bf16 v[50:53], v[150:153], v[178:181], v[50:53]
	v_mfma_f32_16x16x32_bf16 v[42:45], v[170:173], v[178:181], v[42:45]
	v_mfma_f32_16x16x32_bf16 v[34:37], v[150:153], v[186:189], v[34:37]
	v_mfma_f32_16x16x32_bf16 v[26:29], v[170:173], v[186:189], v[26:29]
	v_mfma_f32_16x16x32_bf16 v[18:21], v[150:153], v[194:197], v[18:21]
	v_mfma_f32_16x16x32_bf16 v[10:13], v[170:173], v[194:197], v[10:13]
	v_mfma_f32_16x16x32_bf16 v[6:9], v[150:153], v[202:205], v[6:9]
	v_mfma_f32_16x16x32_bf16 v[2:5], v[170:173], v[202:205], v[2:5]
	v_mfma_f32_16x16x32_bf16 v[50:53], v[166:169], v[182:185], v[50:53]
	v_mfma_f32_16x16x32_bf16 v[42:45], v[174:177], v[182:185], v[42:45]
	v_mfma_f32_16x16x32_bf16 v[34:37], v[166:169], v[190:193], v[34:37]
	v_mfma_f32_16x16x32_bf16 v[26:29], v[174:177], v[190:193], v[26:29]
	v_mfma_f32_16x16x32_bf16 v[18:21], v[166:169], v[198:201], v[18:21]
	v_mfma_f32_16x16x32_bf16 v[10:13], v[174:177], v[198:201], v[10:13]
	s_setprio 2
	s_barrier
	v_mfma_f32_16x16x32_bf16 v[6:9], v[166:169], v[206:209], v[6:9]
	v_mfma_f32_16x16x32_bf16 v[2:5], v[174:177], v[206:209], v[2:5]
	s_setprio 0
	ds_read_b128 v[134:137], v164
	ds_read_b128 v[138:141], v164 offset:1024
	ds_read_b128 v[142:145], v164 offset:2048
	ds_read_b128 v[146:149], v164 offset:3072
	ds_read_b128 v[150:153], v165
	ds_read_b128 v[166:169], v165 offset:1024
	ds_read_b128 v[170:173], v165 offset:2048
	ds_read_b128 v[174:177], v165 offset:3072
	ds_read_b128 v[178:181], v163 offset:32768
	ds_read_b128 v[182:185], v163 offset:33792
	ds_read_b128 v[186:189], v163 offset:34816
	ds_read_b128 v[190:193], v163 offset:35840
	ds_read_b128 v[194:197], v163 offset:36864
	ds_read_b128 v[198:201], v163 offset:37888
	ds_read_b128 v[202:205], v163 offset:38912
	ds_read_b128 v[206:209], v163 offset:39936
	s_mov_b32 s83, m0
	s_mov_b32 m0, s34
	s_nop 0
	global_load_lds_dwordx4 v1, s[24:25]
	s_mov_b32 m0, s83
	s_nop 0
	s_mov_b32 s83, m0
	s_mov_b32 m0, s42
	s_nop 0
	global_load_lds_dwordx4 v157, s[24:25]
	s_mov_b32 m0, s83
	s_add_u32 s24, s24, 0x4000
	s_addc_u32 s25, s25, 0
	s_mov_b32 s83, m0
	s_mov_b32 m0, s43
	s_nop 0
	global_load_lds_dwordx4 v1, s[24:25]
	s_mov_b32 m0, s83
	s_nop 0
	s_mov_b32 s83, m0
	s_mov_b32 m0, s46
	s_nop 0
	global_load_lds_dwordx4 v157, s[24:25]
	s_mov_b32 m0, s83
	s_waitcnt vmcnt(8)
	s_waitcnt lgkmcnt(0)
	s_barrier
	s_setprio 1
	v_mfma_f32_16x16x32_bf16 v[126:129], v[134:137], v[178:181], v[126:129]
	v_mfma_f32_16x16x32_bf16 v[122:125], v[142:145], v[178:181], v[122:125]
	v_mfma_f32_16x16x32_bf16 v[118:121], v[134:137], v[186:189], v[118:121]
	v_mfma_f32_16x16x32_bf16 v[114:117], v[142:145], v[186:189], v[114:117]
	v_mfma_f32_16x16x32_bf16 v[102:105], v[134:137], v[194:197], v[102:105]
	v_mfma_f32_16x16x32_bf16 v[94:97], v[142:145], v[194:197], v[94:97]
	v_mfma_f32_16x16x32_bf16 v[86:89], v[134:137], v[202:205], v[86:89]
	v_mfma_f32_16x16x32_bf16 v[78:81], v[142:145], v[202:205], v[78:81]
	v_mfma_f32_16x16x32_bf16 v[126:129], v[138:141], v[182:185], v[126:129]
	v_mfma_f32_16x16x32_bf16 v[122:125], v[146:149], v[182:185], v[122:125]
	v_mfma_f32_16x16x32_bf16 v[118:121], v[138:141], v[190:193], v[118:121]
	v_mfma_f32_16x16x32_bf16 v[114:117], v[146:149], v[190:193], v[114:117]
	v_mfma_f32_16x16x32_bf16 v[102:105], v[138:141], v[198:201], v[102:105]
	v_mfma_f32_16x16x32_bf16 v[94:97], v[146:149], v[198:201], v[94:97]
	v_mfma_f32_16x16x32_bf16 v[86:89], v[138:141], v[206:209], v[86:89]
	v_mfma_f32_16x16x32_bf16 v[78:81], v[146:149], v[206:209], v[78:81]
	v_mfma_f32_16x16x32_bf16 v[110:113], v[150:153], v[178:181], v[110:113]
	v_mfma_f32_16x16x32_bf16 v[106:109], v[170:173], v[178:181], v[106:109]
	v_mfma_f32_16x16x32_bf16 v[98:101], v[150:153], v[186:189], v[98:101]
	v_mfma_f32_16x16x32_bf16 v[90:93], v[170:173], v[186:189], v[90:93]
	v_mfma_f32_16x16x32_bf16 v[82:85], v[150:153], v[194:197], v[82:85]
	v_mfma_f32_16x16x32_bf16 v[74:77], v[170:173], v[194:197], v[74:77]
	v_mfma_f32_16x16x32_bf16 v[70:73], v[150:153], v[202:205], v[70:73]
	v_mfma_f32_16x16x32_bf16 v[66:69], v[170:173], v[202:205], v[66:69]
	v_mfma_f32_16x16x32_bf16 v[110:113], v[166:169], v[182:185], v[110:113]
	v_mfma_f32_16x16x32_bf16 v[106:109], v[174:177], v[182:185], v[106:109]
	v_mfma_f32_16x16x32_bf16 v[98:101], v[166:169], v[190:193], v[98:101]
	v_mfma_f32_16x16x32_bf16 v[90:93], v[174:177], v[190:193], v[90:93]
	v_mfma_f32_16x16x32_bf16 v[82:85], v[166:169], v[198:201], v[82:85]
	v_mfma_f32_16x16x32_bf16 v[74:77], v[174:177], v[198:201], v[74:77]
	s_setprio 2
	s_barrier
	v_mfma_f32_16x16x32_bf16 v[70:73], v[166:169], v[206:209], v[70:73]
	v_mfma_f32_16x16x32_bf16 v[66:69], v[174:177], v[206:209], v[66:69]
	s_setprio 0
	ds_read_b128 v[178:181], v163 offset:49152
	ds_read_b128 v[182:185], v163 offset:50176
	ds_read_b128 v[186:189], v163 offset:51200
	ds_read_b128 v[190:193], v163 offset:52224
	ds_read_b128 v[194:197], v163 offset:53248
	ds_read_b128 v[198:201], v163 offset:54272
	ds_read_b128 v[202:205], v163 offset:55296
	ds_read_b128 v[206:209], v163 offset:56320
	s_add_u32 s24, s22, 0x40000
	s_addc_u32 s25, s23, 0
	s_mov_b32 s83, m0
	s_mov_b32 m0, s47
	s_nop 0
	global_load_lds_dwordx4 v156, s[24:25]
	s_mov_b32 m0, s83
	s_add_u32 s22, s22, 0x44000
	s_mov_b32 s83, m0
	s_mov_b32 m0, s48
	s_nop 0
	global_load_lds_dwordx4 v158, s[24:25]
	s_mov_b32 m0, s83
	s_addc_u32 s23, s23, 0
	s_mov_b32 s24, m0
	s_mov_b32 m0, s49
	s_nop 0
	global_load_lds_dwordx4 v156, s[22:23]
	s_mov_b32 m0, s24
	s_nop 0
	s_mov_b32 s24, m0
	s_mov_b32 m0, s56
	s_nop 0
	global_load_lds_dwordx4 v158, s[22:23]
	s_mov_b32 m0, s24
	s_waitcnt vmcnt(4)
	s_waitcnt lgkmcnt(0)
	s_barrier
	s_setprio 1
	v_mfma_f32_16x16x32_bf16 v[62:65], v[134:137], v[178:181], v[62:65]
	v_mfma_f32_16x16x32_bf16 v[58:61], v[142:145], v[178:181], v[58:61]
	v_mfma_f32_16x16x32_bf16 v[54:57], v[134:137], v[186:189], v[54:57]
	v_mfma_f32_16x16x32_bf16 v[46:49], v[142:145], v[186:189], v[46:49]
	v_mfma_f32_16x16x32_bf16 v[38:41], v[134:137], v[194:197], v[38:41]
	v_mfma_f32_16x16x32_bf16 v[30:33], v[142:145], v[194:197], v[30:33]
	v_mfma_f32_16x16x32_bf16 v[22:25], v[134:137], v[202:205], v[22:25]
	v_mfma_f32_16x16x32_bf16 v[14:17], v[142:145], v[202:205], v[14:17]
	v_mfma_f32_16x16x32_bf16 v[62:65], v[138:141], v[182:185], v[62:65]
	v_mfma_f32_16x16x32_bf16 v[58:61], v[146:149], v[182:185], v[58:61]
	v_mfma_f32_16x16x32_bf16 v[54:57], v[138:141], v[190:193], v[54:57]
	v_mfma_f32_16x16x32_bf16 v[46:49], v[146:149], v[190:193], v[46:49]
	v_mfma_f32_16x16x32_bf16 v[38:41], v[138:141], v[198:201], v[38:41]
	v_mfma_f32_16x16x32_bf16 v[30:33], v[146:149], v[198:201], v[30:33]
	v_mfma_f32_16x16x32_bf16 v[22:25], v[138:141], v[206:209], v[22:25]
	v_mfma_f32_16x16x32_bf16 v[14:17], v[146:149], v[206:209], v[14:17]
	v_mfma_f32_16x16x32_bf16 v[50:53], v[150:153], v[178:181], v[50:53]
	v_mfma_f32_16x16x32_bf16 v[42:45], v[170:173], v[178:181], v[42:45]
	v_mfma_f32_16x16x32_bf16 v[34:37], v[150:153], v[186:189], v[34:37]
	v_mfma_f32_16x16x32_bf16 v[26:29], v[170:173], v[186:189], v[26:29]
	v_mfma_f32_16x16x32_bf16 v[18:21], v[150:153], v[194:197], v[18:21]
	v_mfma_f32_16x16x32_bf16 v[10:13], v[170:173], v[194:197], v[10:13]
	v_mfma_f32_16x16x32_bf16 v[6:9], v[150:153], v[202:205], v[6:9]
	v_mfma_f32_16x16x32_bf16 v[2:5], v[170:173], v[202:205], v[2:5]
	v_mfma_f32_16x16x32_bf16 v[50:53], v[166:169], v[182:185], v[50:53]
	v_mfma_f32_16x16x32_bf16 v[42:45], v[174:177], v[182:185], v[42:45]
	v_mfma_f32_16x16x32_bf16 v[34:37], v[166:169], v[190:193], v[34:37]
	v_mfma_f32_16x16x32_bf16 v[26:29], v[174:177], v[190:193], v[26:29]
	v_mfma_f32_16x16x32_bf16 v[18:21], v[166:169], v[198:201], v[18:21]
	v_mfma_f32_16x16x32_bf16 v[10:13], v[174:177], v[198:201], v[10:13]
	s_setprio 2
	s_barrier
	v_mfma_f32_16x16x32_bf16 v[6:9], v[166:169], v[206:209], v[6:9]
	v_mfma_f32_16x16x32_bf16 v[2:5], v[174:177], v[206:209], v[2:5]
	s_setprio 0
	s_add_i32 s82, s82, 2
	s_add_u32 s78, s78, 0x80000
	s_addc_u32 s79, s79, 0
	s_add_u32 s20, s20, 0x400000
	s_addc_u32 s21, s21, 0
	s_add_u32 s80, s80, 0x400000
	s_addc_u32 s81, s81, 0
	s_cmpk_gt_u32 s82, 0x53
	s_cbranch_scc0 .LBB0_473
	s_and_b64 vcc, exec, s[8:9]
	s_cbranch_vccz .LBB0_476
	s_barrier

.LBB0_654:
	ds_read_b128 v[130:133], v161
	ds_read_b128 v[138:141], v161 offset:1024
	ds_read_b128 v[142:145], v161 offset:2048
	ds_read_b128 v[146:149], v161 offset:3072
	ds_read_b128 v[150:153], v162
	ds_read_b128 v[168:171], v162 offset:1024
	ds_read_b128 v[172:175], v162 offset:2048
	ds_read_b128 v[176:179], v162 offset:3072
	s_cmp_eq_u32 s74, 28
	s_cselect_b32 s11, s21, s31
	s_cselect_b32 s10, s23, s30
	s_cselect_b32 s29, s7, s73
	s_cselect_b32 s28, s9, s33
	ds_read_b128 v[180:183], v163
	ds_read_b128 v[184:187], v163 offset:1024
	ds_read_b128 v[188:191], v163 offset:2048
	ds_read_b128 v[192:195], v163 offset:3072
	ds_read_b128 v[196:199], v163 offset:4096
	ds_read_b128 v[200:203], v163 offset:5120
	ds_read_b128 v[204:207], v163 offset:6144
	ds_read_b128 v[208:211], v163 offset:7168
	s_add_u32 s76, s4, 0xfff80000
	s_addc_u32 s77, s5, -1
	s_mov_b32 s75, m0
	s_mov_b32 m0, s80
	s_nop 0
	global_load_lds_dwordx4 v1, s[76:77]
	s_mov_b32 m0, s75
	s_nop 0
	s_mov_b32 s75, m0
	s_mov_b32 m0, s82
	s_nop 0
	global_load_lds_dwordx4 v157, s[76:77]
	s_mov_b32 m0, s75
	s_nop 0
	s_mov_b32 s75, m0
	s_mov_b32 m0, s81
	s_nop 0
	global_load_lds_dwordx4 v1, s[4:5]
	s_mov_b32 m0, s75
	s_nop 0
	s_mov_b32 s75, m0
	s_mov_b32 m0, s83
	s_nop 0
	global_load_lds_dwordx4 v157, s[4:5]
	s_mov_b32 m0, s75
	s_waitcnt vmcnt(8)
	s_waitcnt lgkmcnt(0)
	s_barrier
	s_setprio 1
	v_mfma_f32_16x16x32_bf16 v[126:129], v[130:133], v[180:183], v[126:129]
	v_mfma_f32_16x16x32_bf16 v[122:125], v[142:145], v[180:183], v[122:125]
	v_mfma_f32_16x16x32_bf16 v[110:113], v[130:133], v[188:191], v[110:113]
	v_mfma_f32_16x16x32_bf16 v[106:109], v[142:145], v[188:191], v[106:109]
	v_mfma_f32_16x16x32_bf16 v[94:97], v[130:133], v[196:199], v[94:97]
	v_mfma_f32_16x16x32_bf16 v[90:93], v[142:145], v[196:199], v[90:93]
	v_mfma_f32_16x16x32_bf16 v[78:81], v[130:133], v[204:207], v[78:81]
	v_mfma_f32_16x16x32_bf16 v[74:77], v[142:145], v[204:207], v[74:77]
	v_mfma_f32_16x16x32_bf16 v[126:129], v[138:141], v[184:187], v[126:129]
	v_mfma_f32_16x16x32_bf16 v[122:125], v[146:149], v[184:187], v[122:125]
	v_mfma_f32_16x16x32_bf16 v[110:113], v[138:141], v[192:195], v[110:113]
	v_mfma_f32_16x16x32_bf16 v[106:109], v[146:149], v[192:195], v[106:109]
	v_mfma_f32_16x16x32_bf16 v[94:97], v[138:141], v[200:203], v[94:97]
	v_mfma_f32_16x16x32_bf16 v[90:93], v[146:149], v[200:203], v[90:93]
	v_mfma_f32_16x16x32_bf16 v[78:81], v[138:141], v[208:211], v[78:81]
	v_mfma_f32_16x16x32_bf16 v[74:77], v[146:149], v[208:211], v[74:77]
	v_mfma_f32_16x16x32_bf16 v[118:121], v[150:153], v[180:183], v[118:121]
	v_mfma_f32_16x16x32_bf16 v[114:117], v[172:175], v[180:183], v[114:117]
	v_mfma_f32_16x16x32_bf16 v[102:105], v[150:153], v[188:191], v[102:105]
	v_mfma_f32_16x16x32_bf16 v[98:101], v[172:175], v[188:191], v[98:101]
	v_mfma_f32_16x16x32_bf16 v[86:89], v[150:153], v[196:199], v[86:89]
	v_mfma_f32_16x16x32_bf16 v[82:85], v[172:175], v[196:199], v[82:85]
	v_mfma_f32_16x16x32_bf16 v[70:73], v[150:153], v[204:207], v[70:73]
	v_mfma_f32_16x16x32_bf16 v[66:69], v[172:175], v[204:207], v[66:69]
	v_mfma_f32_16x16x32_bf16 v[118:121], v[168:171], v[184:187], v[118:121]
	v_mfma_f32_16x16x32_bf16 v[114:117], v[176:179], v[184:187], v[114:117]
	v_mfma_f32_16x16x32_bf16 v[102:105], v[168:171], v[192:195], v[102:105]
	v_mfma_f32_16x16x32_bf16 v[98:101], v[176:179], v[192:195], v[98:101]
	v_mfma_f32_16x16x32_bf16 v[86:89], v[168:171], v[200:203], v[86:89]
	v_mfma_f32_16x16x32_bf16 v[82:85], v[176:179], v[200:203], v[82:85]
	s_setprio 2
	s_barrier
	v_mfma_f32_16x16x32_bf16 v[70:73], v[168:171], v[208:211], v[70:73]
	v_mfma_f32_16x16x32_bf16 v[66:69], v[176:179], v[208:211], v[66:69]
	s_setprio 0
	ds_read_b128 v[180:183], v163 offset:16384
	ds_read_b128 v[184:187], v163 offset:17408
	ds_read_b128 v[188:191], v163 offset:18432
	ds_read_b128 v[192:195], v163 offset:19456
	ds_read_b128 v[196:199], v163 offset:20480
	ds_read_b128 v[200:203], v163 offset:21504
	ds_read_b128 v[204:207], v163 offset:22528
	ds_read_b128 v[208:211], v163 offset:23552
	s_mov_b32 s75, m0
	s_mov_b32 m0, s43
	s_nop 0
	global_load_lds_dwordx4 v156, s[10:11]
	s_mov_b32 m0, s75
	s_add_u32 s76, s10, 0x80000
	s_mov_b32 s75, m0
	s_mov_b32 m0, s46
	s_nop 0
	global_load_lds_dwordx4 v158, s[10:11]
	s_mov_b32 m0, s75
	s_addc_u32 s77, s11, 0
	s_mov_b32 s75, m0
	s_mov_b32 m0, s47
	s_nop 0
	global_load_lds_dwordx4 v156, s[76:77]
	s_mov_b32 m0, s75
	s_nop 0
	s_mov_b32 s75, m0
	s_mov_b32 m0, s48
	s_nop 0
	global_load_lds_dwordx4 v158, s[76:77]
	s_mov_b32 m0, s75
	s_waitcnt vmcnt(4)
	s_waitcnt lgkmcnt(0)
	s_barrier
	s_setprio 1
	v_mfma_f32_16x16x32_bf16 v[62:65], v[130:133], v[180:183], v[62:65]
	v_mfma_f32_16x16x32_bf16 v[58:61], v[142:145], v[180:183], v[58:61]
	v_mfma_f32_16x16x32_bf16 v[46:49], v[130:133], v[188:191], v[46:49]
	v_mfma_f32_16x16x32_bf16 v[42:45], v[142:145], v[188:191], v[42:45]
	v_mfma_f32_16x16x32_bf16 v[30:33], v[130:133], v[196:199], v[30:33]
	v_mfma_f32_16x16x32_bf16 v[26:29], v[142:145], v[196:199], v[26:29]
	v_mfma_f32_16x16x32_bf16 v[14:17], v[130:133], v[204:207], v[14:17]
	v_mfma_f32_16x16x32_bf16 v[10:13], v[142:145], v[204:207], v[10:13]
	v_mfma_f32_16x16x32_bf16 v[62:65], v[138:141], v[184:187], v[62:65]
	v_mfma_f32_16x16x32_bf16 v[58:61], v[146:149], v[184:187], v[58:61]
	v_mfma_f32_16x16x32_bf16 v[46:49], v[138:141], v[192:195], v[46:49]
	v_mfma_f32_16x16x32_bf16 v[42:45], v[146:149], v[192:195], v[42:45]
	v_mfma_f32_16x16x32_bf16 v[30:33], v[138:141], v[200:203], v[30:33]
	v_mfma_f32_16x16x32_bf16 v[26:29], v[146:149], v[200:203], v[26:29]
	v_mfma_f32_16x16x32_bf16 v[14:17], v[138:141], v[208:211], v[14:17]
	v_mfma_f32_16x16x32_bf16 v[10:13], v[146:149], v[208:211], v[10:13]
	v_mfma_f32_16x16x32_bf16 v[54:57], v[150:153], v[180:183], v[54:57]
	v_mfma_f32_16x16x32_bf16 v[50:53], v[172:175], v[180:183], v[50:53]
	v_mfma_f32_16x16x32_bf16 v[38:41], v[150:153], v[188:191], v[38:41]
	v_mfma_f32_16x16x32_bf16 v[34:37], v[172:175], v[188:191], v[34:37]
	v_mfma_f32_16x16x32_bf16 v[22:25], v[150:153], v[196:199], v[22:25]
	v_mfma_f32_16x16x32_bf16 v[18:21], v[172:175], v[196:199], v[18:21]
	v_mfma_f32_16x16x32_bf16 v[6:9], v[150:153], v[204:207], v[6:9]
	v_mfma_f32_16x16x32_bf16 v[2:5], v[172:175], v[204:207], v[2:5]
	v_mfma_f32_16x16x32_bf16 v[54:57], v[168:171], v[184:187], v[54:57]
	v_mfma_f32_16x16x32_bf16 v[50:53], v[176:179], v[184:187], v[50:53]
	v_mfma_f32_16x16x32_bf16 v[38:41], v[168:171], v[192:195], v[38:41]
	v_mfma_f32_16x16x32_bf16 v[34:37], v[176:179], v[192:195], v[34:37]
	v_mfma_f32_16x16x32_bf16 v[22:25], v[168:171], v[200:203], v[22:25]
	v_mfma_f32_16x16x32_bf16 v[18:21], v[176:179], v[200:203], v[18:21]
	s_setprio 2
	s_barrier
	v_mfma_f32_16x16x32_bf16 v[6:9], v[168:171], v[208:211], v[6:9]
	v_mfma_f32_16x16x32_bf16 v[2:5], v[176:179], v[208:211], v[2:5]
	s_setprio 0
	ds_read_b128 v[130:133], v164
	ds_read_b128 v[138:141], v164 offset:1024
	ds_read_b128 v[142:145], v164 offset:2048
	ds_read_b128 v[146:149], v164 offset:3072
	ds_read_b128 v[150:153], v165
	ds_read_b128 v[168:171], v165 offset:1024
	ds_read_b128 v[172:175], v165 offset:2048
	ds_read_b128 v[176:179], v165 offset:3072
	ds_read_b128 v[180:183], v163 offset:32768
	ds_read_b128 v[184:187], v163 offset:33792
	ds_read_b128 v[188:191], v163 offset:34816
	ds_read_b128 v[192:195], v163 offset:35840
	ds_read_b128 v[196:199], v163 offset:36864
	ds_read_b128 v[200:203], v163 offset:37888
	ds_read_b128 v[204:207], v163 offset:38912
	ds_read_b128 v[208:211], v163 offset:39936
	s_mov_b32 s75, m0
	s_mov_b32 m0, s42
	s_nop 0
	global_load_lds_dwordx4 v1, s[28:29]
	s_mov_b32 m0, s75
	s_nop 0
	s_mov_b32 s75, m0
	s_mov_b32 m0, s49
	s_nop 0
	global_load_lds_dwordx4 v157, s[28:29]
	s_mov_b32 m0, s75
	s_add_u32 s28, s28, 0x80000
	s_addc_u32 s29, s29, 0
	s_mov_b32 s75, m0
	s_mov_b32 m0, s56
	s_nop 0
	global_load_lds_dwordx4 v1, s[28:29]
	s_mov_b32 m0, s75
	s_nop 0
	s_mov_b32 s75, m0
	s_mov_b32 m0, s57
	s_nop 0
	global_load_lds_dwordx4 v157, s[28:29]
	s_mov_b32 m0, s75
	s_waitcnt vmcnt(8)
	s_waitcnt lgkmcnt(0)
	s_barrier
	s_setprio 1
	v_mfma_f32_16x16x32_bf16 v[126:129], v[130:133], v[180:183], v[126:129]
	v_mfma_f32_16x16x32_bf16 v[122:125], v[142:145], v[180:183], v[122:125]
	v_mfma_f32_16x16x32_bf16 v[110:113], v[130:133], v[188:191], v[110:113]
	v_mfma_f32_16x16x32_bf16 v[106:109], v[142:145], v[188:191], v[106:109]
	v_mfma_f32_16x16x32_bf16 v[94:97], v[130:133], v[196:199], v[94:97]
	v_mfma_f32_16x16x32_bf16 v[90:93], v[142:145], v[196:199], v[90:93]
	v_mfma_f32_16x16x32_bf16 v[78:81], v[130:133], v[204:207], v[78:81]
	v_mfma_f32_16x16x32_bf16 v[74:77], v[142:145], v[204:207], v[74:77]
	v_mfma_f32_16x16x32_bf16 v[126:129], v[138:141], v[184:187], v[126:129]
	v_mfma_f32_16x16x32_bf16 v[122:125], v[146:149], v[184:187], v[122:125]
	v_mfma_f32_16x16x32_bf16 v[110:113], v[138:141], v[192:195], v[110:113]
	v_mfma_f32_16x16x32_bf16 v[106:109], v[146:149], v[192:195], v[106:109]
	v_mfma_f32_16x16x32_bf16 v[94:97], v[138:141], v[200:203], v[94:97]
	v_mfma_f32_16x16x32_bf16 v[90:93], v[146:149], v[200:203], v[90:93]
	v_mfma_f32_16x16x32_bf16 v[78:81], v[138:141], v[208:211], v[78:81]
	v_mfma_f32_16x16x32_bf16 v[74:77], v[146:149], v[208:211], v[74:77]
	v_mfma_f32_16x16x32_bf16 v[118:121], v[150:153], v[180:183], v[118:121]
	v_mfma_f32_16x16x32_bf16 v[114:117], v[172:175], v[180:183], v[114:117]
	v_mfma_f32_16x16x32_bf16 v[102:105], v[150:153], v[188:191], v[102:105]
	v_mfma_f32_16x16x32_bf16 v[98:101], v[172:175], v[188:191], v[98:101]
	v_mfma_f32_16x16x32_bf16 v[86:89], v[150:153], v[196:199], v[86:89]
	v_mfma_f32_16x16x32_bf16 v[82:85], v[172:175], v[196:199], v[82:85]
	v_mfma_f32_16x16x32_bf16 v[70:73], v[150:153], v[204:207], v[70:73]
	v_mfma_f32_16x16x32_bf16 v[66:69], v[172:175], v[204:207], v[66:69]
	v_mfma_f32_16x16x32_bf16 v[118:121], v[168:171], v[184:187], v[118:121]
	v_mfma_f32_16x16x32_bf16 v[114:117], v[176:179], v[184:187], v[114:117]
	v_mfma_f32_16x16x32_bf16 v[102:105], v[168:171], v[192:195], v[102:105]
	v_mfma_f32_16x16x32_bf16 v[98:101], v[176:179], v[192:195], v[98:101]
	v_mfma_f32_16x16x32_bf16 v[86:89], v[168:171], v[200:203], v[86:89]
	v_mfma_f32_16x16x32_bf16 v[82:85], v[176:179], v[200:203], v[82:85]
	s_setprio 2
	s_barrier
	v_mfma_f32_16x16x32_bf16 v[70:73], v[168:171], v[208:211], v[70:73]
	v_mfma_f32_16x16x32_bf16 v[66:69], v[176:179], v[208:211], v[66:69]
	s_setprio 0
	ds_read_b128 v[180:183], v163 offset:49152
	ds_read_b128 v[184:187], v163 offset:50176
	ds_read_b128 v[188:191], v163 offset:51200
	ds_read_b128 v[192:195], v163 offset:52224
	ds_read_b128 v[196:199], v163 offset:53248
	ds_read_b128 v[200:203], v163 offset:54272
	ds_read_b128 v[204:207], v163 offset:55296
	ds_read_b128 v[208:211], v163 offset:56320
	s_add_u32 s28, s10, 0x80
	s_addc_u32 s29, s11, 0
	s_mov_b32 s75, m0
	s_mov_b32 m0, s64
	s_nop 0
	global_load_lds_dwordx4 v156, s[28:29]
	s_mov_b32 m0, s75
	s_add_u32 s10, s10, 0x80080
	s_mov_b32 s75, m0
	s_mov_b32 m0, s65
	s_nop 0
	global_load_lds_dwordx4 v158, s[28:29]
	s_mov_b32 m0, s75
	s_addc_u32 s11, s11, 0
	s_mov_b32 s28, m0
	s_mov_b32 m0, s66
	s_nop 0
	global_load_lds_dwordx4 v156, s[10:11]
	s_mov_b32 m0, s28
	s_nop 0
	s_mov_b32 s28, m0
	s_mov_b32 m0, s67
	s_nop 0
	global_load_lds_dwordx4 v158, s[10:11]
	s_mov_b32 m0, s28
	s_waitcnt vmcnt(4)
	s_waitcnt lgkmcnt(0)
	s_barrier
	s_setprio 1
	v_mfma_f32_16x16x32_bf16 v[62:65], v[130:133], v[180:183], v[62:65]
	v_mfma_f32_16x16x32_bf16 v[58:61], v[142:145], v[180:183], v[58:61]
	v_mfma_f32_16x16x32_bf16 v[46:49], v[130:133], v[188:191], v[46:49]
	v_mfma_f32_16x16x32_bf16 v[42:45], v[142:145], v[188:191], v[42:45]
	v_mfma_f32_16x16x32_bf16 v[30:33], v[130:133], v[196:199], v[30:33]
	v_mfma_f32_16x16x32_bf16 v[26:29], v[142:145], v[196:199], v[26:29]
	v_mfma_f32_16x16x32_bf16 v[14:17], v[130:133], v[204:207], v[14:17]
	v_mfma_f32_16x16x32_bf16 v[10:13], v[142:145], v[204:207], v[10:13]
	v_mfma_f32_16x16x32_bf16 v[62:65], v[138:141], v[184:187], v[62:65]
	v_mfma_f32_16x16x32_bf16 v[58:61], v[146:149], v[184:187], v[58:61]
	v_mfma_f32_16x16x32_bf16 v[46:49], v[138:141], v[192:195], v[46:49]
	v_mfma_f32_16x16x32_bf16 v[42:45], v[146:149], v[192:195], v[42:45]
	v_mfma_f32_16x16x32_bf16 v[30:33], v[138:141], v[200:203], v[30:33]
	v_mfma_f32_16x16x32_bf16 v[26:29], v[146:149], v[200:203], v[26:29]
	v_mfma_f32_16x16x32_bf16 v[14:17], v[138:141], v[208:211], v[14:17]
	v_mfma_f32_16x16x32_bf16 v[10:13], v[146:149], v[208:211], v[10:13]
	v_mfma_f32_16x16x32_bf16 v[54:57], v[150:153], v[180:183], v[54:57]
	v_mfma_f32_16x16x32_bf16 v[50:53], v[172:175], v[180:183], v[50:53]
	v_mfma_f32_16x16x32_bf16 v[38:41], v[150:153], v[188:191], v[38:41]
	v_mfma_f32_16x16x32_bf16 v[34:37], v[172:175], v[188:191], v[34:37]
	v_mfma_f32_16x16x32_bf16 v[22:25], v[150:153], v[196:199], v[22:25]
	v_mfma_f32_16x16x32_bf16 v[18:21], v[172:175], v[196:199], v[18:21]
	v_mfma_f32_16x16x32_bf16 v[6:9], v[150:153], v[204:207], v[6:9]
	v_mfma_f32_16x16x32_bf16 v[2:5], v[172:175], v[204:207], v[2:5]
	v_mfma_f32_16x16x32_bf16 v[54:57], v[168:171], v[184:187], v[54:57]
	v_mfma_f32_16x16x32_bf16 v[50:53], v[176:179], v[184:187], v[50:53]
	v_mfma_f32_16x16x32_bf16 v[38:41], v[168:171], v[192:195], v[38:41]
	v_mfma_f32_16x16x32_bf16 v[34:37], v[176:179], v[192:195], v[34:37]
	v_mfma_f32_16x16x32_bf16 v[22:25], v[168:171], v[200:203], v[22:25]
	v_mfma_f32_16x16x32_bf16 v[18:21], v[176:179], v[200:203], v[18:21]
	s_setprio 2
	s_barrier
	v_mfma_f32_16x16x32_bf16 v[6:9], v[168:171], v[208:211], v[6:9]
	v_mfma_f32_16x16x32_bf16 v[2:5], v[176:179], v[208:211], v[2:5]
	s_setprio 0
	s_add_i32 s74, s74, 2
	s_add_u32 s30, s30, 0x100
	s_addc_u32 s31, s31, 0
	s_add_u32 s4, s4, 0x100
	s_addc_u32 s5, s5, 0
	s_add_u32 s33, s33, 0x100
	s_addc_u32 s73, s73, 0
	s_cmp_gt_u32 s74, 29
	s_cbranch_scc0 .LBB0_654
	s_and_b64 vcc, exec, s[18:19]
	s_cbranch_vccz .LBB0_657
	s_barrier

.LBB0_1053:
	ds_read_b128 v[130:133], v181
	ds_read_b128 v[134:137], v181 offset:1024
	ds_read_b128 v[138:141], v181 offset:2048
	ds_read_b128 v[142:145], v181 offset:3072
	ds_read_b128 v[146:149], v182
	ds_read_b128 v[150:153], v182 offset:1024
	ds_read_b128 v[154:157], v182 offset:2048
	ds_read_b128 v[158:161], v182 offset:3072
	s_cmp_eq_u32 s78, 28
	s_cselect_b32 s23, s11, s75
	s_cselect_b32 s22, s73, s74
	s_cselect_b32 s25, s13, s77
	s_cselect_b32 s24, s67, s76
	ds_read_b128 v[166:169], v183
	ds_read_b128 v[170:173], v183 offset:1024
	ds_read_b128 v[186:189], v183 offset:2048
	ds_read_b128 v[190:193], v183 offset:3072
	ds_read_b128 v[194:197], v183 offset:4096
	ds_read_b128 v[198:201], v183 offset:5120
	ds_read_b128 v[202:205], v183 offset:6144
	ds_read_b128 v[206:209], v183 offset:7168
	s_add_u32 s80, s20, 0xfff80000
	s_addc_u32 s81, s21, -1
	s_mov_b32 s79, m0
	s_mov_b32 m0, s58
	s_nop 0
	global_load_lds_dwordx4 v1, s[80:81]
	s_mov_b32 m0, s79
	s_nop 0
	s_mov_b32 s79, m0
	s_mov_b32 m0, s64
	s_nop 0
	global_load_lds_dwordx4 v177, s[80:81]
	s_mov_b32 m0, s79
	s_nop 0
	s_mov_b32 s79, m0
	s_mov_b32 m0, s59
	s_nop 0
	global_load_lds_dwordx4 v1, s[20:21]
	s_mov_b32 m0, s79
	s_nop 0
	s_mov_b32 s79, m0
	s_mov_b32 m0, s65
	s_nop 0
	global_load_lds_dwordx4 v177, s[20:21]
	s_mov_b32 m0, s79
	s_waitcnt vmcnt(8)
	s_waitcnt lgkmcnt(0)
	s_barrier
	s_setprio 1
	v_mfma_f32_16x16x32_bf16 v[126:129], v[130:133], v[166:169], v[126:129]
	v_mfma_f32_16x16x32_bf16 v[122:125], v[138:141], v[166:169], v[122:125]
	v_mfma_f32_16x16x32_bf16 v[118:121], v[130:133], v[186:189], v[118:121]
	v_mfma_f32_16x16x32_bf16 v[114:117], v[138:141], v[186:189], v[114:117]
	v_mfma_f32_16x16x32_bf16 v[94:97], v[130:133], v[194:197], v[94:97]
	v_mfma_f32_16x16x32_bf16 v[90:93], v[138:141], v[194:197], v[90:93]
	v_mfma_f32_16x16x32_bf16 v[86:89], v[130:133], v[202:205], v[86:89]
	v_mfma_f32_16x16x32_bf16 v[78:81], v[138:141], v[202:205], v[78:81]
	v_mfma_f32_16x16x32_bf16 v[126:129], v[134:137], v[170:173], v[126:129]
	v_mfma_f32_16x16x32_bf16 v[122:125], v[142:145], v[170:173], v[122:125]
	v_mfma_f32_16x16x32_bf16 v[118:121], v[134:137], v[190:193], v[118:121]
	v_mfma_f32_16x16x32_bf16 v[114:117], v[142:145], v[190:193], v[114:117]
	v_mfma_f32_16x16x32_bf16 v[94:97], v[134:137], v[198:201], v[94:97]
	v_mfma_f32_16x16x32_bf16 v[90:93], v[142:145], v[198:201], v[90:93]
	v_mfma_f32_16x16x32_bf16 v[86:89], v[134:137], v[206:209], v[86:89]
	v_mfma_f32_16x16x32_bf16 v[78:81], v[142:145], v[206:209], v[78:81]
	v_mfma_f32_16x16x32_bf16 v[110:113], v[146:149], v[166:169], v[110:113]
	v_mfma_f32_16x16x32_bf16 v[106:109], v[154:157], v[166:169], v[106:109]
	v_mfma_f32_16x16x32_bf16 v[102:105], v[146:149], v[186:189], v[102:105]
	v_mfma_f32_16x16x32_bf16 v[98:101], v[154:157], v[186:189], v[98:101]
	v_mfma_f32_16x16x32_bf16 v[82:85], v[146:149], v[194:197], v[82:85]
	v_mfma_f32_16x16x32_bf16 v[74:77], v[154:157], v[194:197], v[74:77]
	v_mfma_f32_16x16x32_bf16 v[70:73], v[146:149], v[202:205], v[70:73]
	v_mfma_f32_16x16x32_bf16 v[66:69], v[154:157], v[202:205], v[66:69]
	v_mfma_f32_16x16x32_bf16 v[110:113], v[150:153], v[170:173], v[110:113]
	v_mfma_f32_16x16x32_bf16 v[106:109], v[158:161], v[170:173], v[106:109]
	v_mfma_f32_16x16x32_bf16 v[102:105], v[150:153], v[190:193], v[102:105]
	v_mfma_f32_16x16x32_bf16 v[98:101], v[158:161], v[190:193], v[98:101]
	v_mfma_f32_16x16x32_bf16 v[82:85], v[150:153], v[198:201], v[82:85]
	v_mfma_f32_16x16x32_bf16 v[74:77], v[158:161], v[198:201], v[74:77]
	s_setprio 2
	s_barrier
	v_mfma_f32_16x16x32_bf16 v[70:73], v[150:153], v[206:209], v[70:73]
	v_mfma_f32_16x16x32_bf16 v[66:69], v[158:161], v[206:209], v[66:69]
	s_setprio 0
	ds_read_b128 v[166:169], v183 offset:16384
	ds_read_b128 v[170:173], v183 offset:17408
	ds_read_b128 v[186:189], v183 offset:18432
	ds_read_b128 v[190:193], v183 offset:19456
	ds_read_b128 v[194:197], v183 offset:20480
	ds_read_b128 v[198:201], v183 offset:21504
	ds_read_b128 v[202:205], v183 offset:22528
	ds_read_b128 v[206:209], v183 offset:23552
	s_mov_b32 s79, m0
	s_mov_b32 m0, s35
	s_nop 0
	global_load_lds_dwordx4 v176, s[22:23]
	s_mov_b32 m0, s79
	s_add_u32 s80, s22, 0x80000
	s_mov_b32 s79, m0
	s_mov_b32 m0, s36
	s_nop 0
	global_load_lds_dwordx4 v178, s[22:23]
	s_mov_b32 m0, s79
	s_addc_u32 s81, s23, 0
	s_mov_b32 s79, m0
	s_mov_b32 m0, s37
	s_nop 0
	global_load_lds_dwordx4 v176, s[80:81]
	s_mov_b32 m0, s79
	s_nop 0
	s_mov_b32 s79, m0
	s_mov_b32 m0, s40
	s_nop 0
	global_load_lds_dwordx4 v178, s[80:81]
	s_mov_b32 m0, s79
	s_waitcnt vmcnt(4)
	s_waitcnt lgkmcnt(0)
	s_barrier
	s_setprio 1
	v_mfma_f32_16x16x32_bf16 v[62:65], v[130:133], v[166:169], v[62:65]
	v_mfma_f32_16x16x32_bf16 v[58:61], v[138:141], v[166:169], v[58:61]
	v_mfma_f32_16x16x32_bf16 v[46:49], v[130:133], v[186:189], v[46:49]
	v_mfma_f32_16x16x32_bf16 v[42:45], v[138:141], v[186:189], v[42:45]
	v_mfma_f32_16x16x32_bf16 v[30:33], v[130:133], v[194:197], v[30:33]
	v_mfma_f32_16x16x32_bf16 v[26:29], v[138:141], v[194:197], v[26:29]
	v_mfma_f32_16x16x32_bf16 v[14:17], v[130:133], v[202:205], v[14:17]
	v_mfma_f32_16x16x32_bf16 v[10:13], v[138:141], v[202:205], v[10:13]
	v_mfma_f32_16x16x32_bf16 v[62:65], v[134:137], v[170:173], v[62:65]
	v_mfma_f32_16x16x32_bf16 v[58:61], v[142:145], v[170:173], v[58:61]
	v_mfma_f32_16x16x32_bf16 v[46:49], v[134:137], v[190:193], v[46:49]
	v_mfma_f32_16x16x32_bf16 v[42:45], v[142:145], v[190:193], v[42:45]
	v_mfma_f32_16x16x32_bf16 v[30:33], v[134:137], v[198:201], v[30:33]
	v_mfma_f32_16x16x32_bf16 v[26:29], v[142:145], v[198:201], v[26:29]
	v_mfma_f32_16x16x32_bf16 v[14:17], v[134:137], v[206:209], v[14:17]
	v_mfma_f32_16x16x32_bf16 v[10:13], v[142:145], v[206:209], v[10:13]
	v_mfma_f32_16x16x32_bf16 v[54:57], v[146:149], v[166:169], v[54:57]
	v_mfma_f32_16x16x32_bf16 v[50:53], v[154:157], v[166:169], v[50:53]
	v_mfma_f32_16x16x32_bf16 v[38:41], v[146:149], v[186:189], v[38:41]
	v_mfma_f32_16x16x32_bf16 v[34:37], v[154:157], v[186:189], v[34:37]
	v_mfma_f32_16x16x32_bf16 v[22:25], v[146:149], v[194:197], v[22:25]
	v_mfma_f32_16x16x32_bf16 v[18:21], v[154:157], v[194:197], v[18:21]
	v_mfma_f32_16x16x32_bf16 v[6:9], v[146:149], v[202:205], v[6:9]
	v_mfma_f32_16x16x32_bf16 v[2:5], v[154:157], v[202:205], v[2:5]
	v_mfma_f32_16x16x32_bf16 v[54:57], v[150:153], v[170:173], v[54:57]
	v_mfma_f32_16x16x32_bf16 v[50:53], v[158:161], v[170:173], v[50:53]
	v_mfma_f32_16x16x32_bf16 v[38:41], v[150:153], v[190:193], v[38:41]
	v_mfma_f32_16x16x32_bf16 v[34:37], v[158:161], v[190:193], v[34:37]
	v_mfma_f32_16x16x32_bf16 v[22:25], v[150:153], v[198:201], v[22:25]
	v_mfma_f32_16x16x32_bf16 v[18:21], v[158:161], v[198:201], v[18:21]
	s_setprio 2
	s_barrier
	v_mfma_f32_16x16x32_bf16 v[6:9], v[150:153], v[206:209], v[6:9]
	v_mfma_f32_16x16x32_bf16 v[2:5], v[158:161], v[206:209], v[2:5]
	s_setprio 0
	ds_read_b128 v[130:133], v184
	ds_read_b128 v[134:137], v184 offset:1024
	ds_read_b128 v[138:141], v184 offset:2048
	ds_read_b128 v[142:145], v184 offset:3072
	ds_read_b128 v[146:149], v185
	ds_read_b128 v[150:153], v185 offset:1024
	ds_read_b128 v[154:157], v185 offset:2048
	ds_read_b128 v[158:161], v185 offset:3072
	ds_read_b128 v[166:169], v183 offset:32768
	ds_read_b128 v[170:173], v183 offset:33792
	ds_read_b128 v[186:189], v183 offset:34816
	ds_read_b128 v[190:193], v183 offset:35840
	ds_read_b128 v[194:197], v183 offset:36864
	ds_read_b128 v[198:201], v183 offset:37888
	ds_read_b128 v[202:205], v183 offset:38912
	ds_read_b128 v[206:209], v183 offset:39936
	s_mov_b32 s79, m0
	s_mov_b32 m0, s34
	s_nop 0
	global_load_lds_dwordx4 v1, s[24:25]
	s_mov_b32 m0, s79
	s_nop 0
	s_mov_b32 s79, m0
	s_mov_b32 m0, s41
	s_nop 0
	global_load_lds_dwordx4 v177, s[24:25]
	s_mov_b32 m0, s79
	s_add_u32 s24, s24, 0x80000
	s_addc_u32 s25, s25, 0
	s_mov_b32 s79, m0
	s_mov_b32 m0, s42
	s_nop 0
	global_load_lds_dwordx4 v1, s[24:25]
	s_mov_b32 m0, s79
	s_nop 0
	s_mov_b32 s79, m0
	s_mov_b32 m0, s43
	s_nop 0
	global_load_lds_dwordx4 v177, s[24:25]
	s_mov_b32 m0, s79
	s_waitcnt vmcnt(8)
	s_waitcnt lgkmcnt(0)
	s_barrier
	s_setprio 1
	v_mfma_f32_16x16x32_bf16 v[126:129], v[130:133], v[166:169], v[126:129]
	v_mfma_f32_16x16x32_bf16 v[122:125], v[138:141], v[166:169], v[122:125]
	v_mfma_f32_16x16x32_bf16 v[118:121], v[130:133], v[186:189], v[118:121]
	v_mfma_f32_16x16x32_bf16 v[114:117], v[138:141], v[186:189], v[114:117]
	v_mfma_f32_16x16x32_bf16 v[94:97], v[130:133], v[194:197], v[94:97]
	v_mfma_f32_16x16x32_bf16 v[90:93], v[138:141], v[194:197], v[90:93]
	v_mfma_f32_16x16x32_bf16 v[86:89], v[130:133], v[202:205], v[86:89]
	v_mfma_f32_16x16x32_bf16 v[78:81], v[138:141], v[202:205], v[78:81]
	v_mfma_f32_16x16x32_bf16 v[126:129], v[134:137], v[170:173], v[126:129]
	v_mfma_f32_16x16x32_bf16 v[122:125], v[142:145], v[170:173], v[122:125]
	v_mfma_f32_16x16x32_bf16 v[118:121], v[134:137], v[190:193], v[118:121]
	v_mfma_f32_16x16x32_bf16 v[114:117], v[142:145], v[190:193], v[114:117]
	v_mfma_f32_16x16x32_bf16 v[94:97], v[134:137], v[198:201], v[94:97]
	v_mfma_f32_16x16x32_bf16 v[90:93], v[142:145], v[198:201], v[90:93]
	v_mfma_f32_16x16x32_bf16 v[86:89], v[134:137], v[206:209], v[86:89]
	v_mfma_f32_16x16x32_bf16 v[78:81], v[142:145], v[206:209], v[78:81]
	v_mfma_f32_16x16x32_bf16 v[110:113], v[146:149], v[166:169], v[110:113]
	v_mfma_f32_16x16x32_bf16 v[106:109], v[154:157], v[166:169], v[106:109]
	v_mfma_f32_16x16x32_bf16 v[102:105], v[146:149], v[186:189], v[102:105]
	v_mfma_f32_16x16x32_bf16 v[98:101], v[154:157], v[186:189], v[98:101]
	v_mfma_f32_16x16x32_bf16 v[82:85], v[146:149], v[194:197], v[82:85]
	v_mfma_f32_16x16x32_bf16 v[74:77], v[154:157], v[194:197], v[74:77]
	v_mfma_f32_16x16x32_bf16 v[70:73], v[146:149], v[202:205], v[70:73]
	v_mfma_f32_16x16x32_bf16 v[66:69], v[154:157], v[202:205], v[66:69]
	v_mfma_f32_16x16x32_bf16 v[110:113], v[150:153], v[170:173], v[110:113]
	v_mfma_f32_16x16x32_bf16 v[106:109], v[158:161], v[170:173], v[106:109]
	v_mfma_f32_16x16x32_bf16 v[102:105], v[150:153], v[190:193], v[102:105]
	v_mfma_f32_16x16x32_bf16 v[98:101], v[158:161], v[190:193], v[98:101]
	v_mfma_f32_16x16x32_bf16 v[82:85], v[150:153], v[198:201], v[82:85]
	v_mfma_f32_16x16x32_bf16 v[74:77], v[158:161], v[198:201], v[74:77]
	s_setprio 2
	s_barrier
	v_mfma_f32_16x16x32_bf16 v[70:73], v[150:153], v[206:209], v[70:73]
	v_mfma_f32_16x16x32_bf16 v[66:69], v[158:161], v[206:209], v[66:69]
	s_setprio 0
	ds_read_b128 v[166:169], v183 offset:49152
	ds_read_b128 v[170:173], v183 offset:50176
	ds_read_b128 v[186:189], v183 offset:51200
	ds_read_b128 v[190:193], v183 offset:52224
	ds_read_b128 v[194:197], v183 offset:53248
	ds_read_b128 v[198:201], v183 offset:54272
	ds_read_b128 v[202:205], v183 offset:55296
	ds_read_b128 v[206:209], v183 offset:56320
	s_add_u32 s24, s22, 0x80
	s_addc_u32 s25, s23, 0
	s_mov_b32 s79, m0
	s_mov_b32 m0, s46
	s_nop 0
	global_load_lds_dwordx4 v176, s[24:25]
	s_mov_b32 m0, s79
	s_add_u32 s22, s22, 0x80080
	s_mov_b32 s79, m0
	s_mov_b32 m0, s47
	s_nop 0
	global_load_lds_dwordx4 v178, s[24:25]
	s_mov_b32 m0, s79
	s_addc_u32 s23, s23, 0
	s_mov_b32 s24, m0
	s_mov_b32 m0, s48
	s_nop 0
	global_load_lds_dwordx4 v176, s[22:23]
	s_mov_b32 m0, s24
	s_nop 0
	s_mov_b32 s24, m0
	s_mov_b32 m0, s49
	s_nop 0
	global_load_lds_dwordx4 v178, s[22:23]
	s_mov_b32 m0, s24
	s_waitcnt vmcnt(4)
	s_waitcnt lgkmcnt(0)
	s_barrier
	s_setprio 1
	v_mfma_f32_16x16x32_bf16 v[62:65], v[130:133], v[166:169], v[62:65]
	v_mfma_f32_16x16x32_bf16 v[58:61], v[138:141], v[166:169], v[58:61]
	v_mfma_f32_16x16x32_bf16 v[46:49], v[130:133], v[186:189], v[46:49]
	v_mfma_f32_16x16x32_bf16 v[42:45], v[138:141], v[186:189], v[42:45]
	v_mfma_f32_16x16x32_bf16 v[30:33], v[130:133], v[194:197], v[30:33]
	v_mfma_f32_16x16x32_bf16 v[26:29], v[138:141], v[194:197], v[26:29]
	v_mfma_f32_16x16x32_bf16 v[14:17], v[130:133], v[202:205], v[14:17]
	v_mfma_f32_16x16x32_bf16 v[10:13], v[138:141], v[202:205], v[10:13]
	v_mfma_f32_16x16x32_bf16 v[62:65], v[134:137], v[170:173], v[62:65]
	v_mfma_f32_16x16x32_bf16 v[58:61], v[142:145], v[170:173], v[58:61]
	v_mfma_f32_16x16x32_bf16 v[46:49], v[134:137], v[190:193], v[46:49]
	v_mfma_f32_16x16x32_bf16 v[42:45], v[142:145], v[190:193], v[42:45]
	v_mfma_f32_16x16x32_bf16 v[30:33], v[134:137], v[198:201], v[30:33]
	v_mfma_f32_16x16x32_bf16 v[26:29], v[142:145], v[198:201], v[26:29]
	v_mfma_f32_16x16x32_bf16 v[14:17], v[134:137], v[206:209], v[14:17]
	v_mfma_f32_16x16x32_bf16 v[10:13], v[142:145], v[206:209], v[10:13]
	v_mfma_f32_16x16x32_bf16 v[54:57], v[146:149], v[166:169], v[54:57]
	v_mfma_f32_16x16x32_bf16 v[50:53], v[154:157], v[166:169], v[50:53]
	v_mfma_f32_16x16x32_bf16 v[38:41], v[146:149], v[186:189], v[38:41]
	v_mfma_f32_16x16x32_bf16 v[34:37], v[154:157], v[186:189], v[34:37]
	v_mfma_f32_16x16x32_bf16 v[22:25], v[146:149], v[194:197], v[22:25]
	v_mfma_f32_16x16x32_bf16 v[18:21], v[154:157], v[194:197], v[18:21]
	v_mfma_f32_16x16x32_bf16 v[6:9], v[146:149], v[202:205], v[6:9]
	v_mfma_f32_16x16x32_bf16 v[2:5], v[154:157], v[202:205], v[2:5]
	v_mfma_f32_16x16x32_bf16 v[54:57], v[150:153], v[170:173], v[54:57]
	v_mfma_f32_16x16x32_bf16 v[50:53], v[158:161], v[170:173], v[50:53]
	v_mfma_f32_16x16x32_bf16 v[38:41], v[150:153], v[190:193], v[38:41]
	v_mfma_f32_16x16x32_bf16 v[34:37], v[158:161], v[190:193], v[34:37]
	v_mfma_f32_16x16x32_bf16 v[22:25], v[150:153], v[198:201], v[22:25]
	v_mfma_f32_16x16x32_bf16 v[18:21], v[158:161], v[198:201], v[18:21]
	s_setprio 2
	s_barrier
	v_mfma_f32_16x16x32_bf16 v[6:9], v[150:153], v[206:209], v[6:9]
	v_mfma_f32_16x16x32_bf16 v[2:5], v[158:161], v[206:209], v[2:5]
	s_setprio 0
	s_add_i32 s78, s78, 2
	s_add_u32 s74, s74, 0x100
	s_addc_u32 s75, s75, 0
	s_add_u32 s20, s20, 0x100
	s_addc_u32 s21, s21, 0
	s_add_u32 s76, s76, 0x100
	s_addc_u32 s77, s77, 0
	s_cmp_gt_u32 s78, 29
	s_cbranch_scc0 .LBB0_1053
	s_and_b64 vcc, exec, s[8:9]
	s_cbranch_vccz .LBB0_1056
	s_barrier

.LBB0_1224:
	ds_read_b128 v[148:151], v143
	ds_read_b128 v[152:155], v143 offset:1024
	ds_read_b128 v[156:159], v143 offset:2048
	ds_read_b128 v[160:163], v143 offset:3072
	ds_read_b128 v[164:167], v144
	ds_read_b128 v[168:171], v144 offset:1024
	ds_read_b128 v[172:175], v144 offset:2048
	ds_read_b128 v[176:179], v144 offset:3072
	s_cmp_eq_u32 s77, 28
	s_cselect_b32 s21, s9, s74
	s_cselect_b32 s20, s67, s73
	s_cselect_b32 s23, s11, s76
	s_cselect_b32 s22, s66, s75
	ds_read_b128 v[180:183], v145
	ds_read_b128 v[184:187], v145 offset:1024
	ds_read_b128 v[188:191], v145 offset:2048
	ds_read_b128 v[192:195], v145 offset:3072
	ds_read_b128 v[196:199], v145 offset:4096
	ds_read_b128 v[200:203], v145 offset:5120
	ds_read_b128 v[204:207], v145 offset:6144
	ds_read_b128 v[208:211], v145 offset:7168
	s_add_u32 s78, s18, 0xfff80000
	s_addc_u32 s79, s19, -1
	s_mov_b32 s80, m0
	s_mov_b32 m0, s56
	s_nop 0
	global_load_lds_dwordx4 v138, s[78:79]
	s_mov_b32 m0, s80
	s_nop 0
	s_mov_b32 s80, m0
	s_mov_b32 m0, s59
	s_nop 0
	global_load_lds_dwordx4 v140, s[78:79]
	s_mov_b32 m0, s80
	s_mov_b32 s78, m0
	s_mov_b32 m0, s57
	s_nop 0
	global_load_lds_dwordx4 v138, s[18:19]
	s_mov_b32 m0, s78
	s_nop 0
	s_mov_b32 s78, m0
	s_mov_b32 m0, s64
	s_nop 0
	global_load_lds_dwordx4 v140, s[18:19]
	s_mov_b32 m0, s78
	s_waitcnt vmcnt(8)
	s_waitcnt lgkmcnt(0)
	s_barrier
	s_setprio 1
	v_mfma_f32_16x16x32_bf16 v[126:129], v[148:151], v[180:183], v[126:129]
	v_mfma_f32_16x16x32_bf16 v[122:125], v[156:159], v[180:183], v[122:125]
	v_mfma_f32_16x16x32_bf16 v[110:113], v[148:151], v[188:191], v[110:113]
	v_mfma_f32_16x16x32_bf16 v[106:109], v[156:159], v[188:191], v[106:109]
	v_mfma_f32_16x16x32_bf16 v[94:97], v[148:151], v[196:199], v[94:97]
	v_mfma_f32_16x16x32_bf16 v[90:93], v[156:159], v[196:199], v[90:93]
	v_mfma_f32_16x16x32_bf16 v[78:81], v[148:151], v[204:207], v[78:81]
	v_mfma_f32_16x16x32_bf16 v[74:77], v[156:159], v[204:207], v[74:77]
	v_mfma_f32_16x16x32_bf16 v[126:129], v[152:155], v[184:187], v[126:129]
	v_mfma_f32_16x16x32_bf16 v[122:125], v[160:163], v[184:187], v[122:125]
	v_mfma_f32_16x16x32_bf16 v[110:113], v[152:155], v[192:195], v[110:113]
	v_mfma_f32_16x16x32_bf16 v[106:109], v[160:163], v[192:195], v[106:109]
	v_mfma_f32_16x16x32_bf16 v[94:97], v[152:155], v[200:203], v[94:97]
	v_mfma_f32_16x16x32_bf16 v[90:93], v[160:163], v[200:203], v[90:93]
	v_mfma_f32_16x16x32_bf16 v[78:81], v[152:155], v[208:211], v[78:81]
	v_mfma_f32_16x16x32_bf16 v[74:77], v[160:163], v[208:211], v[74:77]
	v_mfma_f32_16x16x32_bf16 v[118:121], v[164:167], v[180:183], v[118:121]
	v_mfma_f32_16x16x32_bf16 v[114:117], v[172:175], v[180:183], v[114:117]
	v_mfma_f32_16x16x32_bf16 v[102:105], v[164:167], v[188:191], v[102:105]
	v_mfma_f32_16x16x32_bf16 v[98:101], v[172:175], v[188:191], v[98:101]
	v_mfma_f32_16x16x32_bf16 v[86:89], v[164:167], v[196:199], v[86:89]
	v_mfma_f32_16x16x32_bf16 v[82:85], v[172:175], v[196:199], v[82:85]
	v_mfma_f32_16x16x32_bf16 v[70:73], v[164:167], v[204:207], v[70:73]
	v_mfma_f32_16x16x32_bf16 v[66:69], v[172:175], v[204:207], v[66:69]
	v_mfma_f32_16x16x32_bf16 v[118:121], v[168:171], v[184:187], v[118:121]
	v_mfma_f32_16x16x32_bf16 v[114:117], v[176:179], v[184:187], v[114:117]
	v_mfma_f32_16x16x32_bf16 v[102:105], v[168:171], v[192:195], v[102:105]
	v_mfma_f32_16x16x32_bf16 v[98:101], v[176:179], v[192:195], v[98:101]
	v_mfma_f32_16x16x32_bf16 v[86:89], v[168:171], v[200:203], v[86:89]
	v_mfma_f32_16x16x32_bf16 v[82:85], v[176:179], v[200:203], v[82:85]
	s_setprio 2
	s_barrier
	v_mfma_f32_16x16x32_bf16 v[70:73], v[168:171], v[208:211], v[70:73]
	v_mfma_f32_16x16x32_bf16 v[66:69], v[176:179], v[208:211], v[66:69]
	s_setprio 0
	ds_read_b128 v[180:183], v145 offset:16384
	ds_read_b128 v[184:187], v145 offset:17408
	ds_read_b128 v[188:191], v145 offset:18432
	ds_read_b128 v[192:195], v145 offset:19456
	ds_read_b128 v[196:199], v145 offset:20480
	ds_read_b128 v[200:203], v145 offset:21504
	ds_read_b128 v[204:207], v145 offset:22528
	ds_read_b128 v[208:211], v145 offset:23552
	s_mov_b32 s78, m0
	s_mov_b32 m0, s35
	s_nop 0
	global_load_lds_dwordx4 v139, s[20:21]
	s_mov_b32 m0, s78
	s_nop 0
	s_mov_b32 s78, m0
	s_mov_b32 m0, s36
	s_nop 0
	global_load_lds_dwordx4 v141, s[20:21]
	s_mov_b32 m0, s78
	s_add_u32 s78, s20, 0x80000
	s_addc_u32 s79, s21, 0
	s_mov_b32 s80, m0
	s_mov_b32 m0, s37
	s_nop 0
	global_load_lds_dwordx4 v139, s[78:79]
	s_mov_b32 m0, s80
	s_nop 0
	s_mov_b32 s80, m0
	s_mov_b32 m0, s40
	s_nop 0
	global_load_lds_dwordx4 v141, s[78:79]
	s_mov_b32 m0, s80
	s_waitcnt vmcnt(4)
	s_waitcnt lgkmcnt(0)
	s_barrier
	s_setprio 1
	v_mfma_f32_16x16x32_bf16 v[62:65], v[148:151], v[180:183], v[62:65]
	v_mfma_f32_16x16x32_bf16 v[58:61], v[156:159], v[180:183], v[58:61]
	v_mfma_f32_16x16x32_bf16 v[46:49], v[148:151], v[188:191], v[46:49]
	v_mfma_f32_16x16x32_bf16 v[42:45], v[156:159], v[188:191], v[42:45]
	v_mfma_f32_16x16x32_bf16 v[30:33], v[148:151], v[196:199], v[30:33]
	v_mfma_f32_16x16x32_bf16 v[26:29], v[156:159], v[196:199], v[26:29]
	v_mfma_f32_16x16x32_bf16 v[14:17], v[148:151], v[204:207], v[14:17]
	v_mfma_f32_16x16x32_bf16 v[10:13], v[156:159], v[204:207], v[10:13]
	v_mfma_f32_16x16x32_bf16 v[62:65], v[152:155], v[184:187], v[62:65]
	v_mfma_f32_16x16x32_bf16 v[58:61], v[160:163], v[184:187], v[58:61]
	v_mfma_f32_16x16x32_bf16 v[46:49], v[152:155], v[192:195], v[46:49]
	v_mfma_f32_16x16x32_bf16 v[42:45], v[160:163], v[192:195], v[42:45]
	v_mfma_f32_16x16x32_bf16 v[30:33], v[152:155], v[200:203], v[30:33]
	v_mfma_f32_16x16x32_bf16 v[26:29], v[160:163], v[200:203], v[26:29]
	v_mfma_f32_16x16x32_bf16 v[14:17], v[152:155], v[208:211], v[14:17]
	v_mfma_f32_16x16x32_bf16 v[10:13], v[160:163], v[208:211], v[10:13]
	v_mfma_f32_16x16x32_bf16 v[54:57], v[164:167], v[180:183], v[54:57]
	v_mfma_f32_16x16x32_bf16 v[50:53], v[172:175], v[180:183], v[50:53]
	v_mfma_f32_16x16x32_bf16 v[38:41], v[164:167], v[188:191], v[38:41]
	v_mfma_f32_16x16x32_bf16 v[34:37], v[172:175], v[188:191], v[34:37]
	v_mfma_f32_16x16x32_bf16 v[22:25], v[164:167], v[196:199], v[22:25]
	v_mfma_f32_16x16x32_bf16 v[18:21], v[172:175], v[196:199], v[18:21]
	v_mfma_f32_16x16x32_bf16 v[6:9], v[164:167], v[204:207], v[6:9]
	v_mfma_f32_16x16x32_bf16 v[2:5], v[172:175], v[204:207], v[2:5]
	v_mfma_f32_16x16x32_bf16 v[54:57], v[168:171], v[184:187], v[54:57]
	v_mfma_f32_16x16x32_bf16 v[50:53], v[176:179], v[184:187], v[50:53]
	v_mfma_f32_16x16x32_bf16 v[38:41], v[168:171], v[192:195], v[38:41]
	v_mfma_f32_16x16x32_bf16 v[34:37], v[176:179], v[192:195], v[34:37]
	v_mfma_f32_16x16x32_bf16 v[22:25], v[168:171], v[200:203], v[22:25]
	v_mfma_f32_16x16x32_bf16 v[18:21], v[176:179], v[200:203], v[18:21]
	s_setprio 2
	s_barrier
	v_mfma_f32_16x16x32_bf16 v[6:9], v[168:171], v[208:211], v[6:9]
	v_mfma_f32_16x16x32_bf16 v[2:5], v[176:179], v[208:211], v[2:5]
	s_setprio 0
	ds_read_b128 v[148:151], v146
	ds_read_b128 v[152:155], v146 offset:1024
	ds_read_b128 v[156:159], v146 offset:2048
	ds_read_b128 v[160:163], v146 offset:3072
	ds_read_b128 v[164:167], v147
	ds_read_b128 v[168:171], v147 offset:1024
	ds_read_b128 v[172:175], v147 offset:2048
	ds_read_b128 v[176:179], v147 offset:3072
	ds_read_b128 v[180:183], v145 offset:32768
	ds_read_b128 v[184:187], v145 offset:33792
	ds_read_b128 v[188:191], v145 offset:34816
	ds_read_b128 v[192:195], v145 offset:35840
	ds_read_b128 v[196:199], v145 offset:36864
	ds_read_b128 v[200:203], v145 offset:37888
	ds_read_b128 v[204:207], v145 offset:38912
	ds_read_b128 v[208:211], v145 offset:39936
	s_mov_b32 s78, m0
	s_mov_b32 m0, s31
	s_nop 0
	global_load_lds_dwordx4 v138, s[22:23]
	s_mov_b32 m0, s78
	s_nop 0
	s_mov_b32 s78, m0
	s_mov_b32 m0, s41
	s_nop 0
	global_load_lds_dwordx4 v140, s[22:23]
	s_mov_b32 m0, s78
	s_add_u32 s22, s22, 0x80000
	s_addc_u32 s23, s23, 0
	s_mov_b32 s78, m0
	s_mov_b32 m0, s42
	s_nop 0
	global_load_lds_dwordx4 v138, s[22:23]
	s_mov_b32 m0, s78
	s_nop 0
	s_mov_b32 s78, m0
	s_mov_b32 m0, s43
	s_nop 0
	global_load_lds_dwordx4 v140, s[22:23]
	s_mov_b32 m0, s78
	s_waitcnt vmcnt(8)
	s_waitcnt lgkmcnt(0)
	s_barrier
	s_setprio 1
	v_mfma_f32_16x16x32_bf16 v[126:129], v[148:151], v[180:183], v[126:129]
	v_mfma_f32_16x16x32_bf16 v[122:125], v[156:159], v[180:183], v[122:125]
	v_mfma_f32_16x16x32_bf16 v[110:113], v[148:151], v[188:191], v[110:113]
	v_mfma_f32_16x16x32_bf16 v[106:109], v[156:159], v[188:191], v[106:109]
	v_mfma_f32_16x16x32_bf16 v[94:97], v[148:151], v[196:199], v[94:97]
	v_mfma_f32_16x16x32_bf16 v[90:93], v[156:159], v[196:199], v[90:93]
	v_mfma_f32_16x16x32_bf16 v[78:81], v[148:151], v[204:207], v[78:81]
	v_mfma_f32_16x16x32_bf16 v[74:77], v[156:159], v[204:207], v[74:77]
	v_mfma_f32_16x16x32_bf16 v[126:129], v[152:155], v[184:187], v[126:129]
	v_mfma_f32_16x16x32_bf16 v[122:125], v[160:163], v[184:187], v[122:125]
	v_mfma_f32_16x16x32_bf16 v[110:113], v[152:155], v[192:195], v[110:113]
	v_mfma_f32_16x16x32_bf16 v[106:109], v[160:163], v[192:195], v[106:109]
	v_mfma_f32_16x16x32_bf16 v[94:97], v[152:155], v[200:203], v[94:97]
	v_mfma_f32_16x16x32_bf16 v[90:93], v[160:163], v[200:203], v[90:93]
	v_mfma_f32_16x16x32_bf16 v[78:81], v[152:155], v[208:211], v[78:81]
	v_mfma_f32_16x16x32_bf16 v[74:77], v[160:163], v[208:211], v[74:77]
	v_mfma_f32_16x16x32_bf16 v[118:121], v[164:167], v[180:183], v[118:121]
	v_mfma_f32_16x16x32_bf16 v[114:117], v[172:175], v[180:183], v[114:117]
	v_mfma_f32_16x16x32_bf16 v[102:105], v[164:167], v[188:191], v[102:105]
	v_mfma_f32_16x16x32_bf16 v[98:101], v[172:175], v[188:191], v[98:101]
	v_mfma_f32_16x16x32_bf16 v[86:89], v[164:167], v[196:199], v[86:89]
	v_mfma_f32_16x16x32_bf16 v[82:85], v[172:175], v[196:199], v[82:85]
	v_mfma_f32_16x16x32_bf16 v[70:73], v[164:167], v[204:207], v[70:73]
	v_mfma_f32_16x16x32_bf16 v[66:69], v[172:175], v[204:207], v[66:69]
	v_mfma_f32_16x16x32_bf16 v[118:121], v[168:171], v[184:187], v[118:121]
	v_mfma_f32_16x16x32_bf16 v[114:117], v[176:179], v[184:187], v[114:117]
	v_mfma_f32_16x16x32_bf16 v[102:105], v[168:171], v[192:195], v[102:105]
	v_mfma_f32_16x16x32_bf16 v[98:101], v[176:179], v[192:195], v[98:101]
	v_mfma_f32_16x16x32_bf16 v[86:89], v[168:171], v[200:203], v[86:89]
	v_mfma_f32_16x16x32_bf16 v[82:85], v[176:179], v[200:203], v[82:85]
	s_setprio 2
	s_barrier
	v_mfma_f32_16x16x32_bf16 v[70:73], v[168:171], v[208:211], v[70:73]
	v_mfma_f32_16x16x32_bf16 v[66:69], v[176:179], v[208:211], v[66:69]
	s_setprio 0
	ds_read_b128 v[180:183], v145 offset:49152
	ds_read_b128 v[184:187], v145 offset:50176
	ds_read_b128 v[188:191], v145 offset:51200
	ds_read_b128 v[192:195], v145 offset:52224
	ds_read_b128 v[196:199], v145 offset:53248
	ds_read_b128 v[200:203], v145 offset:54272
	ds_read_b128 v[204:207], v145 offset:55296
	ds_read_b128 v[208:211], v145 offset:56320
	s_add_u32 s22, s20, 0x80
	s_addc_u32 s23, s21, 0
	s_mov_b32 s78, m0
	s_mov_b32 m0, s46
	s_nop 0
	global_load_lds_dwordx4 v139, s[22:23]
	s_mov_b32 m0, s78
	s_add_u32 s20, s20, 0x80080
	s_mov_b32 s78, m0
	s_mov_b32 m0, s47
	s_nop 0
	global_load_lds_dwordx4 v141, s[22:23]
	s_mov_b32 m0, s78
	s_addc_u32 s21, s21, 0
	s_mov_b32 s22, m0
	s_mov_b32 m0, s48
	s_nop 0
	global_load_lds_dwordx4 v139, s[20:21]
	s_mov_b32 m0, s22
	s_nop 0
	s_mov_b32 s22, m0
	s_mov_b32 m0, s49
	s_nop 0
	global_load_lds_dwordx4 v141, s[20:21]
	s_mov_b32 m0, s22
	s_waitcnt vmcnt(4)
	s_waitcnt lgkmcnt(0)
	s_barrier
	s_setprio 1
	v_mfma_f32_16x16x32_bf16 v[62:65], v[148:151], v[180:183], v[62:65]
	v_mfma_f32_16x16x32_bf16 v[58:61], v[156:159], v[180:183], v[58:61]
	v_mfma_f32_16x16x32_bf16 v[46:49], v[148:151], v[188:191], v[46:49]
	v_mfma_f32_16x16x32_bf16 v[42:45], v[156:159], v[188:191], v[42:45]
	v_mfma_f32_16x16x32_bf16 v[30:33], v[148:151], v[196:199], v[30:33]
	v_mfma_f32_16x16x32_bf16 v[26:29], v[156:159], v[196:199], v[26:29]
	v_mfma_f32_16x16x32_bf16 v[14:17], v[148:151], v[204:207], v[14:17]
	v_mfma_f32_16x16x32_bf16 v[10:13], v[156:159], v[204:207], v[10:13]
	v_mfma_f32_16x16x32_bf16 v[62:65], v[152:155], v[184:187], v[62:65]
	v_mfma_f32_16x16x32_bf16 v[58:61], v[160:163], v[184:187], v[58:61]
	v_mfma_f32_16x16x32_bf16 v[46:49], v[152:155], v[192:195], v[46:49]
	v_mfma_f32_16x16x32_bf16 v[42:45], v[160:163], v[192:195], v[42:45]
	v_mfma_f32_16x16x32_bf16 v[30:33], v[152:155], v[200:203], v[30:33]
	v_mfma_f32_16x16x32_bf16 v[26:29], v[160:163], v[200:203], v[26:29]
	v_mfma_f32_16x16x32_bf16 v[14:17], v[152:155], v[208:211], v[14:17]
	v_mfma_f32_16x16x32_bf16 v[10:13], v[160:163], v[208:211], v[10:13]
	v_mfma_f32_16x16x32_bf16 v[54:57], v[164:167], v[180:183], v[54:57]
	v_mfma_f32_16x16x32_bf16 v[50:53], v[172:175], v[180:183], v[50:53]
	v_mfma_f32_16x16x32_bf16 v[38:41], v[164:167], v[188:191], v[38:41]
	v_mfma_f32_16x16x32_bf16 v[34:37], v[172:175], v[188:191], v[34:37]
	v_mfma_f32_16x16x32_bf16 v[22:25], v[164:167], v[196:199], v[22:25]
	v_mfma_f32_16x16x32_bf16 v[18:21], v[172:175], v[196:199], v[18:21]
	v_mfma_f32_16x16x32_bf16 v[6:9], v[164:167], v[204:207], v[6:9]
	v_mfma_f32_16x16x32_bf16 v[2:5], v[172:175], v[204:207], v[2:5]
	v_mfma_f32_16x16x32_bf16 v[54:57], v[168:171], v[184:187], v[54:57]
	v_mfma_f32_16x16x32_bf16 v[50:53], v[176:179], v[184:187], v[50:53]
	v_mfma_f32_16x16x32_bf16 v[38:41], v[168:171], v[192:195], v[38:41]
	v_mfma_f32_16x16x32_bf16 v[34:37], v[176:179], v[192:195], v[34:37]
	v_mfma_f32_16x16x32_bf16 v[22:25], v[168:171], v[200:203], v[22:25]
	v_mfma_f32_16x16x32_bf16 v[18:21], v[176:179], v[200:203], v[18:21]
	s_setprio 2
	s_barrier
	v_mfma_f32_16x16x32_bf16 v[6:9], v[168:171], v[208:211], v[6:9]
	v_mfma_f32_16x16x32_bf16 v[2:5], v[176:179], v[208:211], v[2:5]
	s_setprio 0
	s_add_i32 s77, s77, 2
	s_add_u32 s73, s73, 0x100
	s_addc_u32 s74, s74, 0
	s_add_u32 s18, s18, 0x100
	s_addc_u32 s19, s19, 0
	s_add_u32 s75, s75, 0x100
	s_addc_u32 s76, s76, 0
	s_cmp_gt_u32 s77, 29
	s_cbranch_scc0 .LBB0_1224
	s_and_b64 vcc, exec, s[6:7]
	s_cbranch_vccz .LBB0_1227
	s_barrier

.LBB0_1357:
	ds_read_b128 v[130:133], v181
	ds_read_b128 v[134:137], v181 offset:1024
	ds_read_b128 v[138:141], v181 offset:2048
	ds_read_b128 v[142:145], v181 offset:3072
	ds_read_b128 v[150:153], v182
	ds_read_b128 v[154:157], v182 offset:1024
	ds_read_b128 v[158:161], v182 offset:2048
	ds_read_b128 v[162:165], v182 offset:3072
	s_cmpk_eq_i32 s78, 0x52
	s_cselect_b32 s23, s11, s75
	s_cselect_b32 s22, s73, s74
	s_cselect_b32 s25, s13, s77
	s_cselect_b32 s24, s67, s76
	ds_read_b128 v[166:169], v183
	ds_read_b128 v[170:173], v183 offset:1024
	ds_read_b128 v[186:189], v183 offset:2048
	ds_read_b128 v[190:193], v183 offset:3072
	ds_read_b128 v[194:197], v183 offset:4096
	ds_read_b128 v[198:201], v183 offset:5120
	ds_read_b128 v[202:205], v183 offset:6144
	ds_read_b128 v[206:209], v183 offset:7168
	s_add_u32 s80, s20, 0xffffc000
	s_addc_u32 s81, s21, -1
	s_mov_b32 s79, m0
	s_mov_b32 m0, s58
	s_nop 0
	global_load_lds_dwordx4 v1, s[80:81]
	s_mov_b32 m0, s79
	s_nop 0
	s_mov_b32 s79, m0
	s_mov_b32 m0, s64
	s_nop 0
	global_load_lds_dwordx4 v177, s[80:81]
	s_mov_b32 m0, s79
	s_nop 0
	s_mov_b32 s79, m0
	s_mov_b32 m0, s59
	s_nop 0
	global_load_lds_dwordx4 v1, s[20:21]
	s_mov_b32 m0, s79
	s_nop 0
	s_mov_b32 s79, m0
	s_mov_b32 m0, s65
	s_nop 0
	global_load_lds_dwordx4 v177, s[20:21]
	s_mov_b32 m0, s79
	s_waitcnt vmcnt(8)
	s_waitcnt lgkmcnt(0)
	s_barrier
	s_setprio 1
	v_mfma_f32_16x16x32_bf16 v[126:129], v[130:133], v[166:169], v[126:129]
	v_mfma_f32_16x16x32_bf16 v[122:125], v[138:141], v[166:169], v[122:125]
	v_mfma_f32_16x16x32_bf16 v[118:121], v[130:133], v[186:189], v[118:121]
	v_mfma_f32_16x16x32_bf16 v[110:113], v[138:141], v[186:189], v[110:113]
	v_mfma_f32_16x16x32_bf16 v[94:97], v[130:133], v[194:197], v[94:97]
	v_mfma_f32_16x16x32_bf16 v[90:93], v[138:141], v[194:197], v[90:93]
	v_mfma_f32_16x16x32_bf16 v[86:89], v[130:133], v[202:205], v[86:89]
	v_mfma_f32_16x16x32_bf16 v[78:81], v[138:141], v[202:205], v[78:81]
	v_mfma_f32_16x16x32_bf16 v[126:129], v[134:137], v[170:173], v[126:129]
	v_mfma_f32_16x16x32_bf16 v[122:125], v[142:145], v[170:173], v[122:125]
	v_mfma_f32_16x16x32_bf16 v[118:121], v[134:137], v[190:193], v[118:121]
	v_mfma_f32_16x16x32_bf16 v[110:113], v[142:145], v[190:193], v[110:113]
	v_mfma_f32_16x16x32_bf16 v[94:97], v[134:137], v[198:201], v[94:97]
	v_mfma_f32_16x16x32_bf16 v[90:93], v[142:145], v[198:201], v[90:93]
	v_mfma_f32_16x16x32_bf16 v[86:89], v[134:137], v[206:209], v[86:89]
	v_mfma_f32_16x16x32_bf16 v[78:81], v[142:145], v[206:209], v[78:81]
	v_mfma_f32_16x16x32_bf16 v[114:117], v[150:153], v[166:169], v[114:117]
	v_mfma_f32_16x16x32_bf16 v[106:109], v[158:161], v[166:169], v[106:109]
	v_mfma_f32_16x16x32_bf16 v[102:105], v[150:153], v[186:189], v[102:105]
	v_mfma_f32_16x16x32_bf16 v[98:101], v[158:161], v[186:189], v[98:101]
	v_mfma_f32_16x16x32_bf16 v[82:85], v[150:153], v[194:197], v[82:85]
	v_mfma_f32_16x16x32_bf16 v[74:77], v[158:161], v[194:197], v[74:77]
	v_mfma_f32_16x16x32_bf16 v[70:73], v[150:153], v[202:205], v[70:73]
	v_mfma_f32_16x16x32_bf16 v[66:69], v[158:161], v[202:205], v[66:69]
	v_mfma_f32_16x16x32_bf16 v[114:117], v[154:157], v[170:173], v[114:117]
	v_mfma_f32_16x16x32_bf16 v[106:109], v[162:165], v[170:173], v[106:109]
	v_mfma_f32_16x16x32_bf16 v[102:105], v[154:157], v[190:193], v[102:105]
	v_mfma_f32_16x16x32_bf16 v[98:101], v[162:165], v[190:193], v[98:101]
	v_mfma_f32_16x16x32_bf16 v[82:85], v[154:157], v[198:201], v[82:85]
	v_mfma_f32_16x16x32_bf16 v[74:77], v[162:165], v[198:201], v[74:77]
	s_setprio 2
	s_barrier
	v_mfma_f32_16x16x32_bf16 v[70:73], v[154:157], v[206:209], v[70:73]
	v_mfma_f32_16x16x32_bf16 v[66:69], v[162:165], v[206:209], v[66:69]
	s_setprio 0
	ds_read_b128 v[166:169], v183 offset:16384
	ds_read_b128 v[170:173], v183 offset:17408
	ds_read_b128 v[186:189], v183 offset:18432
	ds_read_b128 v[190:193], v183 offset:19456
	ds_read_b128 v[194:197], v183 offset:20480
	ds_read_b128 v[198:201], v183 offset:21504
	ds_read_b128 v[202:205], v183 offset:22528
	ds_read_b128 v[206:209], v183 offset:23552
	s_mov_b32 s79, m0
	s_mov_b32 m0, s35
	s_nop 0
	global_load_lds_dwordx4 v176, s[22:23]
	s_mov_b32 m0, s79
	s_add_u32 s80, s22, 0x4000
	s_mov_b32 s79, m0
	s_mov_b32 m0, s36
	s_nop 0
	global_load_lds_dwordx4 v178, s[22:23]
	s_mov_b32 m0, s79
	s_addc_u32 s81, s23, 0
	s_mov_b32 s79, m0
	s_mov_b32 m0, s37
	s_nop 0
	global_load_lds_dwordx4 v176, s[80:81]
	s_mov_b32 m0, s79
	s_nop 0
	s_mov_b32 s79, m0
	s_mov_b32 m0, s40
	s_nop 0
	global_load_lds_dwordx4 v178, s[80:81]
	s_mov_b32 m0, s79
	s_waitcnt vmcnt(4)
	s_waitcnt lgkmcnt(0)
	s_barrier
	s_setprio 1
	v_mfma_f32_16x16x32_bf16 v[62:65], v[130:133], v[166:169], v[62:65]
	v_mfma_f32_16x16x32_bf16 v[58:61], v[138:141], v[166:169], v[58:61]
	v_mfma_f32_16x16x32_bf16 v[46:49], v[130:133], v[186:189], v[46:49]
	v_mfma_f32_16x16x32_bf16 v[42:45], v[138:141], v[186:189], v[42:45]
	v_mfma_f32_16x16x32_bf16 v[30:33], v[130:133], v[194:197], v[30:33]
	v_mfma_f32_16x16x32_bf16 v[26:29], v[138:141], v[194:197], v[26:29]
	v_mfma_f32_16x16x32_bf16 v[14:17], v[130:133], v[202:205], v[14:17]
	v_mfma_f32_16x16x32_bf16 v[10:13], v[138:141], v[202:205], v[10:13]
	v_mfma_f32_16x16x32_bf16 v[62:65], v[134:137], v[170:173], v[62:65]
	v_mfma_f32_16x16x32_bf16 v[58:61], v[142:145], v[170:173], v[58:61]
	v_mfma_f32_16x16x32_bf16 v[46:49], v[134:137], v[190:193], v[46:49]
	v_mfma_f32_16x16x32_bf16 v[42:45], v[142:145], v[190:193], v[42:45]
	v_mfma_f32_16x16x32_bf16 v[30:33], v[134:137], v[198:201], v[30:33]
	v_mfma_f32_16x16x32_bf16 v[26:29], v[142:145], v[198:201], v[26:29]
	v_mfma_f32_16x16x32_bf16 v[14:17], v[134:137], v[206:209], v[14:17]
	v_mfma_f32_16x16x32_bf16 v[10:13], v[142:145], v[206:209], v[10:13]
	v_mfma_f32_16x16x32_bf16 v[54:57], v[150:153], v[166:169], v[54:57]
	v_mfma_f32_16x16x32_bf16 v[50:53], v[158:161], v[166:169], v[50:53]
	v_mfma_f32_16x16x32_bf16 v[38:41], v[150:153], v[186:189], v[38:41]
	v_mfma_f32_16x16x32_bf16 v[34:37], v[158:161], v[186:189], v[34:37]
	v_mfma_f32_16x16x32_bf16 v[22:25], v[150:153], v[194:197], v[22:25]
	v_mfma_f32_16x16x32_bf16 v[18:21], v[158:161], v[194:197], v[18:21]
	v_mfma_f32_16x16x32_bf16 v[6:9], v[150:153], v[202:205], v[6:9]
	v_mfma_f32_16x16x32_bf16 v[2:5], v[158:161], v[202:205], v[2:5]
	v_mfma_f32_16x16x32_bf16 v[54:57], v[154:157], v[170:173], v[54:57]
	v_mfma_f32_16x16x32_bf16 v[50:53], v[162:165], v[170:173], v[50:53]
	v_mfma_f32_16x16x32_bf16 v[38:41], v[154:157], v[190:193], v[38:41]
	v_mfma_f32_16x16x32_bf16 v[34:37], v[162:165], v[190:193], v[34:37]
	v_mfma_f32_16x16x32_bf16 v[22:25], v[154:157], v[198:201], v[22:25]
	v_mfma_f32_16x16x32_bf16 v[18:21], v[162:165], v[198:201], v[18:21]
	s_setprio 2
	s_barrier
	v_mfma_f32_16x16x32_bf16 v[6:9], v[154:157], v[206:209], v[6:9]
	v_mfma_f32_16x16x32_bf16 v[2:5], v[162:165], v[206:209], v[2:5]
	s_setprio 0
	ds_read_b128 v[130:133], v184
	ds_read_b128 v[134:137], v184 offset:1024
	ds_read_b128 v[138:141], v184 offset:2048
	ds_read_b128 v[142:145], v184 offset:3072
	ds_read_b128 v[150:153], v185
	ds_read_b128 v[154:157], v185 offset:1024
	ds_read_b128 v[158:161], v185 offset:2048
	ds_read_b128 v[162:165], v185 offset:3072
	ds_read_b128 v[166:169], v183 offset:32768
	ds_read_b128 v[170:173], v183 offset:33792
	ds_read_b128 v[186:189], v183 offset:34816
	ds_read_b128 v[190:193], v183 offset:35840
	ds_read_b128 v[194:197], v183 offset:36864
	ds_read_b128 v[198:201], v183 offset:37888
	ds_read_b128 v[202:205], v183 offset:38912
	ds_read_b128 v[206:209], v183 offset:39936
	s_mov_b32 s79, m0
	s_mov_b32 m0, s34
	s_nop 0
	global_load_lds_dwordx4 v1, s[24:25]
	s_mov_b32 m0, s79
	s_nop 0
	s_mov_b32 s79, m0
	s_mov_b32 m0, s41
	s_nop 0
	global_load_lds_dwordx4 v177, s[24:25]
	s_mov_b32 m0, s79
	s_add_u32 s24, s24, 0x4000
	s_addc_u32 s25, s25, 0
	s_mov_b32 s79, m0
	s_mov_b32 m0, s42
	s_nop 0
	global_load_lds_dwordx4 v1, s[24:25]
	s_mov_b32 m0, s79
	s_nop 0
	s_mov_b32 s79, m0
	s_mov_b32 m0, s43
	s_nop 0
	global_load_lds_dwordx4 v177, s[24:25]
	s_mov_b32 m0, s79
	s_waitcnt vmcnt(8)
	s_waitcnt lgkmcnt(0)
	s_barrier
	s_setprio 1
	v_mfma_f32_16x16x32_bf16 v[126:129], v[130:133], v[166:169], v[126:129]
	v_mfma_f32_16x16x32_bf16 v[122:125], v[138:141], v[166:169], v[122:125]
	v_mfma_f32_16x16x32_bf16 v[118:121], v[130:133], v[186:189], v[118:121]
	v_mfma_f32_16x16x32_bf16 v[110:113], v[138:141], v[186:189], v[110:113]
	v_mfma_f32_16x16x32_bf16 v[94:97], v[130:133], v[194:197], v[94:97]
	v_mfma_f32_16x16x32_bf16 v[90:93], v[138:141], v[194:197], v[90:93]
	v_mfma_f32_16x16x32_bf16 v[86:89], v[130:133], v[202:205], v[86:89]
	v_mfma_f32_16x16x32_bf16 v[78:81], v[138:141], v[202:205], v[78:81]
	v_mfma_f32_16x16x32_bf16 v[126:129], v[134:137], v[170:173], v[126:129]
	v_mfma_f32_16x16x32_bf16 v[122:125], v[142:145], v[170:173], v[122:125]
	v_mfma_f32_16x16x32_bf16 v[118:121], v[134:137], v[190:193], v[118:121]
	v_mfma_f32_16x16x32_bf16 v[110:113], v[142:145], v[190:193], v[110:113]
	v_mfma_f32_16x16x32_bf16 v[94:97], v[134:137], v[198:201], v[94:97]
	v_mfma_f32_16x16x32_bf16 v[90:93], v[142:145], v[198:201], v[90:93]
	v_mfma_f32_16x16x32_bf16 v[86:89], v[134:137], v[206:209], v[86:89]
	v_mfma_f32_16x16x32_bf16 v[78:81], v[142:145], v[206:209], v[78:81]
	v_mfma_f32_16x16x32_bf16 v[114:117], v[150:153], v[166:169], v[114:117]
	v_mfma_f32_16x16x32_bf16 v[106:109], v[158:161], v[166:169], v[106:109]
	v_mfma_f32_16x16x32_bf16 v[102:105], v[150:153], v[186:189], v[102:105]
	v_mfma_f32_16x16x32_bf16 v[98:101], v[158:161], v[186:189], v[98:101]
	v_mfma_f32_16x16x32_bf16 v[82:85], v[150:153], v[194:197], v[82:85]
	v_mfma_f32_16x16x32_bf16 v[74:77], v[158:161], v[194:197], v[74:77]
	v_mfma_f32_16x16x32_bf16 v[70:73], v[150:153], v[202:205], v[70:73]
	v_mfma_f32_16x16x32_bf16 v[66:69], v[158:161], v[202:205], v[66:69]
	v_mfma_f32_16x16x32_bf16 v[114:117], v[154:157], v[170:173], v[114:117]
	v_mfma_f32_16x16x32_bf16 v[106:109], v[162:165], v[170:173], v[106:109]
	v_mfma_f32_16x16x32_bf16 v[102:105], v[154:157], v[190:193], v[102:105]
	v_mfma_f32_16x16x32_bf16 v[98:101], v[162:165], v[190:193], v[98:101]
	v_mfma_f32_16x16x32_bf16 v[82:85], v[154:157], v[198:201], v[82:85]
	v_mfma_f32_16x16x32_bf16 v[74:77], v[162:165], v[198:201], v[74:77]
	s_setprio 2
	s_barrier
	v_mfma_f32_16x16x32_bf16 v[70:73], v[154:157], v[206:209], v[70:73]
	v_mfma_f32_16x16x32_bf16 v[66:69], v[162:165], v[206:209], v[66:69]
	s_setprio 0
	ds_read_b128 v[166:169], v183 offset:49152
	ds_read_b128 v[170:173], v183 offset:50176
	ds_read_b128 v[186:189], v183 offset:51200
	ds_read_b128 v[190:193], v183 offset:52224
	ds_read_b128 v[194:197], v183 offset:53248
	ds_read_b128 v[198:201], v183 offset:54272
	ds_read_b128 v[202:205], v183 offset:55296
	ds_read_b128 v[206:209], v183 offset:56320
	s_add_u32 s24, s22, 0x40000
	s_addc_u32 s25, s23, 0
	s_mov_b32 s79, m0
	s_mov_b32 m0, s46
	s_nop 0
	global_load_lds_dwordx4 v176, s[24:25]
	s_mov_b32 m0, s79
	s_add_u32 s22, s22, 0x44000
	s_mov_b32 s79, m0
	s_mov_b32 m0, s47
	s_nop 0
	global_load_lds_dwordx4 v178, s[24:25]
	s_mov_b32 m0, s79
	s_addc_u32 s23, s23, 0
	s_mov_b32 s24, m0
	s_mov_b32 m0, s48
	s_nop 0
	global_load_lds_dwordx4 v176, s[22:23]
	s_mov_b32 m0, s24
	s_nop 0
	s_mov_b32 s24, m0
	s_mov_b32 m0, s49
	s_nop 0
	global_load_lds_dwordx4 v178, s[22:23]
	s_mov_b32 m0, s24
	s_waitcnt vmcnt(4)
	s_waitcnt lgkmcnt(0)
	s_barrier
	s_setprio 1
	v_mfma_f32_16x16x32_bf16 v[62:65], v[130:133], v[166:169], v[62:65]
	v_mfma_f32_16x16x32_bf16 v[58:61], v[138:141], v[166:169], v[58:61]
	v_mfma_f32_16x16x32_bf16 v[46:49], v[130:133], v[186:189], v[46:49]
	v_mfma_f32_16x16x32_bf16 v[42:45], v[138:141], v[186:189], v[42:45]
	v_mfma_f32_16x16x32_bf16 v[30:33], v[130:133], v[194:197], v[30:33]
	v_mfma_f32_16x16x32_bf16 v[26:29], v[138:141], v[194:197], v[26:29]
	v_mfma_f32_16x16x32_bf16 v[14:17], v[130:133], v[202:205], v[14:17]
	v_mfma_f32_16x16x32_bf16 v[10:13], v[138:141], v[202:205], v[10:13]
	v_mfma_f32_16x16x32_bf16 v[62:65], v[134:137], v[170:173], v[62:65]
	v_mfma_f32_16x16x32_bf16 v[58:61], v[142:145], v[170:173], v[58:61]
	v_mfma_f32_16x16x32_bf16 v[46:49], v[134:137], v[190:193], v[46:49]
	v_mfma_f32_16x16x32_bf16 v[42:45], v[142:145], v[190:193], v[42:45]
	v_mfma_f32_16x16x32_bf16 v[30:33], v[134:137], v[198:201], v[30:33]
	v_mfma_f32_16x16x32_bf16 v[26:29], v[142:145], v[198:201], v[26:29]
	v_mfma_f32_16x16x32_bf16 v[14:17], v[134:137], v[206:209], v[14:17]
	v_mfma_f32_16x16x32_bf16 v[10:13], v[142:145], v[206:209], v[10:13]
	v_mfma_f32_16x16x32_bf16 v[54:57], v[150:153], v[166:169], v[54:57]
	v_mfma_f32_16x16x32_bf16 v[50:53], v[158:161], v[166:169], v[50:53]
	v_mfma_f32_16x16x32_bf16 v[38:41], v[150:153], v[186:189], v[38:41]
	v_mfma_f32_16x16x32_bf16 v[34:37], v[158:161], v[186:189], v[34:37]
	v_mfma_f32_16x16x32_bf16 v[22:25], v[150:153], v[194:197], v[22:25]
	v_mfma_f32_16x16x32_bf16 v[18:21], v[158:161], v[194:197], v[18:21]
	v_mfma_f32_16x16x32_bf16 v[6:9], v[150:153], v[202:205], v[6:9]
	v_mfma_f32_16x16x32_bf16 v[2:5], v[158:161], v[202:205], v[2:5]
	v_mfma_f32_16x16x32_bf16 v[54:57], v[154:157], v[170:173], v[54:57]
	v_mfma_f32_16x16x32_bf16 v[50:53], v[162:165], v[170:173], v[50:53]
	v_mfma_f32_16x16x32_bf16 v[38:41], v[154:157], v[190:193], v[38:41]
	v_mfma_f32_16x16x32_bf16 v[34:37], v[162:165], v[190:193], v[34:37]
	v_mfma_f32_16x16x32_bf16 v[22:25], v[154:157], v[198:201], v[22:25]
	v_mfma_f32_16x16x32_bf16 v[18:21], v[162:165], v[198:201], v[18:21]
	s_setprio 2
	s_barrier
	v_mfma_f32_16x16x32_bf16 v[6:9], v[154:157], v[206:209], v[6:9]
	v_mfma_f32_16x16x32_bf16 v[2:5], v[162:165], v[206:209], v[2:5]
	s_setprio 0
	s_add_i32 s78, s78, 2
	s_add_u32 s74, s74, 0x80000
	s_addc_u32 s75, s75, 0
	s_add_u32 s20, s20, 0x400000
	s_addc_u32 s21, s21, 0
	s_add_u32 s76, s76, 0x400000
	s_addc_u32 s77, s77, 0
	s_cmpk_gt_u32 s78, 0x53
	s_cbranch_scc0 .LBB0_1357
	s_and_b64 vcc, exec, s[8:9]
	s_cbranch_vccz .LBB0_1360
	s_barrier

.LBB0_1538:
	ds_read_b128 v[46:49], v182
	ds_read_b128 v[54:57], v182 offset:1024
	ds_read_b128 v[58:61], v182 offset:2048
	ds_read_b128 v[62:65], v182 offset:3072
	ds_read_b128 v[146:149], v183
	ds_read_b128 v[150:153], v183 offset:1024
	ds_read_b128 v[154:157], v183 offset:2048
	ds_read_b128 v[158:161], v183 offset:3072
	s_cmp_eq_u32 s83, 28
	s_cselect_b32 s35, s21, s80
	s_cselect_b32 s34, s29, s79
	s_cselect_b32 s37, s7, s82
	s_cselect_b32 s36, s23, s81
	ds_read_b128 v[170:173], v184
	ds_read_b128 v[188:191], v184 offset:1024
	ds_read_b128 v[192:195], v184 offset:2048
	ds_read_b128 v[196:199], v184 offset:3072
	ds_read_b128 v[200:203], v184 offset:4096
	ds_read_b128 v[204:207], v184 offset:5120
	ds_read_b128 v[208:211], v184 offset:6144
	ds_read_b128 v[212:215], v184 offset:7168
	s_add_u32 s86, s30, 0xfff80000
	s_addc_u32 s87, s31, -1
	s_mov_b32 s92, m0
	s_mov_b32 m0, s73
	s_nop 0
	global_load_lds_dwordx4 v176, s[86:87]
	s_mov_b32 m0, s92
	s_nop 0
	s_mov_b32 s92, m0
	s_mov_b32 m0, s75
	s_nop 0
	global_load_lds_dwordx4 v178, s[86:87]
	s_mov_b32 m0, s92
	s_mov_b32 s86, m0
	s_mov_b32 m0, s74
	s_nop 0
	global_load_lds_dwordx4 v176, s[30:31]
	s_mov_b32 m0, s86
	s_nop 0
	s_mov_b32 s86, m0
	s_mov_b32 m0, s76
	s_nop 0
	global_load_lds_dwordx4 v178, s[30:31]
	s_mov_b32 m0, s86
	s_waitcnt vmcnt(8)
	s_waitcnt lgkmcnt(0)
	s_barrier
	s_setprio 1
	v_mfma_f32_16x16x32_bf16 v[142:145], v[46:49], v[170:173], v[142:145]
	v_mfma_f32_16x16x32_bf16 v[138:141], v[58:61], v[170:173], v[138:141]
	v_mfma_f32_16x16x32_bf16 v[126:129], v[46:49], v[192:195], v[126:129]
	v_mfma_f32_16x16x32_bf16 v[122:125], v[58:61], v[192:195], v[122:125]
	v_mfma_f32_16x16x32_bf16 v[110:113], v[46:49], v[200:203], v[110:113]
	v_mfma_f32_16x16x32_bf16 v[106:109], v[58:61], v[200:203], v[106:109]
	v_mfma_f32_16x16x32_bf16 v[94:97], v[46:49], v[208:211], v[94:97]
	v_mfma_f32_16x16x32_bf16 v[90:93], v[58:61], v[208:211], v[90:93]
	v_mfma_f32_16x16x32_bf16 v[142:145], v[54:57], v[188:191], v[142:145]
	v_mfma_f32_16x16x32_bf16 v[138:141], v[62:65], v[188:191], v[138:141]
	v_mfma_f32_16x16x32_bf16 v[126:129], v[54:57], v[196:199], v[126:129]
	v_mfma_f32_16x16x32_bf16 v[122:125], v[62:65], v[196:199], v[122:125]
	v_mfma_f32_16x16x32_bf16 v[110:113], v[54:57], v[204:207], v[110:113]
	v_mfma_f32_16x16x32_bf16 v[106:109], v[62:65], v[204:207], v[106:109]
	v_mfma_f32_16x16x32_bf16 v[94:97], v[54:57], v[212:215], v[94:97]
	v_mfma_f32_16x16x32_bf16 v[90:93], v[62:65], v[212:215], v[90:93]
	v_mfma_f32_16x16x32_bf16 v[134:137], v[146:149], v[170:173], v[134:137]
	v_mfma_f32_16x16x32_bf16 v[130:133], v[154:157], v[170:173], v[130:133]
	v_mfma_f32_16x16x32_bf16 v[118:121], v[146:149], v[192:195], v[118:121]
	v_mfma_f32_16x16x32_bf16 v[114:117], v[154:157], v[192:195], v[114:117]
	v_mfma_f32_16x16x32_bf16 v[102:105], v[146:149], v[200:203], v[102:105]
	v_mfma_f32_16x16x32_bf16 v[98:101], v[154:157], v[200:203], v[98:101]
	v_mfma_f32_16x16x32_bf16 v[86:89], v[146:149], v[208:211], v[86:89]
	v_mfma_f32_16x16x32_bf16 v[82:85], v[154:157], v[208:211], v[82:85]
	v_mfma_f32_16x16x32_bf16 v[134:137], v[150:153], v[188:191], v[134:137]
	v_mfma_f32_16x16x32_bf16 v[130:133], v[158:161], v[188:191], v[130:133]
	v_mfma_f32_16x16x32_bf16 v[118:121], v[150:153], v[196:199], v[118:121]
	v_mfma_f32_16x16x32_bf16 v[114:117], v[158:161], v[196:199], v[114:117]
	v_mfma_f32_16x16x32_bf16 v[102:105], v[150:153], v[204:207], v[102:105]
	v_mfma_f32_16x16x32_bf16 v[98:101], v[158:161], v[204:207], v[98:101]
	s_setprio 2
	s_barrier
	v_mfma_f32_16x16x32_bf16 v[86:89], v[150:153], v[212:215], v[86:89]
	v_mfma_f32_16x16x32_bf16 v[82:85], v[158:161], v[212:215], v[82:85]
	s_setprio 0
	ds_read_b128 v[170:173], v184 offset:16384
	ds_read_b128 v[188:191], v184 offset:17408
	ds_read_b128 v[192:195], v184 offset:18432
	ds_read_b128 v[196:199], v184 offset:19456
	ds_read_b128 v[200:203], v184 offset:20480
	ds_read_b128 v[204:207], v184 offset:21504
	ds_read_b128 v[208:211], v184 offset:22528
	ds_read_b128 v[212:215], v184 offset:23552
	s_mov_b32 s86, m0
	s_mov_b32 m0, s49
	s_nop 0
	global_load_lds_dwordx4 v177, s[34:35]
	s_mov_b32 m0, s86
	s_nop 0
	s_mov_b32 s86, m0
	s_mov_b32 m0, s56
	s_nop 0
	global_load_lds_dwordx4 v179, s[34:35]
	s_mov_b32 m0, s86
	s_add_u32 s86, s34, 0x80000
	s_addc_u32 s87, s35, 0
	s_mov_b32 s92, m0
	s_mov_b32 m0, s57
	s_nop 0
	global_load_lds_dwordx4 v177, s[86:87]
	s_mov_b32 m0, s92
	s_nop 0
	s_mov_b32 s92, m0
	s_mov_b32 m0, s58
	s_nop 0
	global_load_lds_dwordx4 v179, s[86:87]
	s_mov_b32 m0, s92
	s_waitcnt vmcnt(4)
	s_waitcnt lgkmcnt(0)
	s_barrier
	s_setprio 1
	v_mfma_f32_16x16x32_bf16 v[78:81], v[46:49], v[170:173], v[78:81]
	v_mfma_f32_16x16x32_bf16 v[74:77], v[58:61], v[170:173], v[74:77]
	v_mfma_f32_16x16x32_bf16 v[50:53], v[46:49], v[192:195], v[50:53]
	v_mfma_f32_16x16x32_bf16 v[42:45], v[58:61], v[192:195], v[42:45]
	v_mfma_f32_16x16x32_bf16 v[30:33], v[46:49], v[200:203], v[30:33]
	v_mfma_f32_16x16x32_bf16 v[26:29], v[58:61], v[200:203], v[26:29]
	v_mfma_f32_16x16x32_bf16 v[14:17], v[46:49], v[208:211], v[14:17]
	v_mfma_f32_16x16x32_bf16 v[10:13], v[58:61], v[208:211], v[10:13]
	v_mfma_f32_16x16x32_bf16 v[78:81], v[54:57], v[188:191], v[78:81]
	v_mfma_f32_16x16x32_bf16 v[74:77], v[62:65], v[188:191], v[74:77]
	v_mfma_f32_16x16x32_bf16 v[50:53], v[54:57], v[196:199], v[50:53]
	v_mfma_f32_16x16x32_bf16 v[42:45], v[62:65], v[196:199], v[42:45]
	v_mfma_f32_16x16x32_bf16 v[30:33], v[54:57], v[204:207], v[30:33]
	v_mfma_f32_16x16x32_bf16 v[26:29], v[62:65], v[204:207], v[26:29]
	v_mfma_f32_16x16x32_bf16 v[14:17], v[54:57], v[212:215], v[14:17]
	v_mfma_f32_16x16x32_bf16 v[10:13], v[62:65], v[212:215], v[10:13]
	v_mfma_f32_16x16x32_bf16 v[38:41], v[146:149], v[192:195], v[38:41]
	v_mfma_f32_16x16x32_bf16 v[34:37], v[154:157], v[192:195], v[34:37]
	v_mfma_f32_16x16x32_bf16 v[22:25], v[146:149], v[200:203], v[22:25]
	v_mfma_f32_16x16x32_bf16 v[18:21], v[154:157], v[200:203], v[18:21]
	v_mfma_f32_16x16x32_bf16 v[6:9], v[146:149], v[208:211], v[6:9]
	v_mfma_f32_16x16x32_bf16 v[2:5], v[154:157], v[208:211], v[2:5]
	v_mfma_f32_16x16x32_bf16 v[46:49], v[146:149], v[170:173], v[70:73]
	v_mfma_f32_16x16x32_bf16 v[54:57], v[154:157], v[170:173], v[66:69]
	v_mfma_f32_16x16x32_bf16 v[38:41], v[150:153], v[196:199], v[38:41]
	v_mfma_f32_16x16x32_bf16 v[34:37], v[158:161], v[196:199], v[34:37]
	v_mfma_f32_16x16x32_bf16 v[22:25], v[150:153], v[204:207], v[22:25]
	v_mfma_f32_16x16x32_bf16 v[18:21], v[158:161], v[204:207], v[18:21]
	v_mfma_f32_16x16x32_bf16 v[6:9], v[150:153], v[212:215], v[6:9]
	v_mfma_f32_16x16x32_bf16 v[2:5], v[158:161], v[212:215], v[2:5]
	s_setprio 2
	s_barrier
	v_mfma_f32_16x16x32_bf16 v[46:49], v[150:153], v[188:191], v[46:49]
	v_mfma_f32_16x16x32_bf16 v[54:57], v[158:161], v[188:191], v[54:57]
	s_setprio 0
	ds_read_b128 v[58:61], v185
	ds_read_b128 v[62:65], v185 offset:1024
	ds_read_b128 v[66:69], v185 offset:2048
	ds_read_b128 v[70:73], v185 offset:3072
	ds_read_b128 v[146:149], v186
	ds_read_b128 v[150:153], v186 offset:1024
	ds_read_b128 v[154:157], v186 offset:2048
	ds_read_b128 v[158:161], v186 offset:3072
	ds_read_b128 v[170:173], v184 offset:32768
	ds_read_b128 v[188:191], v184 offset:33792
	ds_read_b128 v[192:195], v184 offset:34816
	ds_read_b128 v[196:199], v184 offset:35840
	ds_read_b128 v[200:203], v184 offset:36864
	ds_read_b128 v[204:207], v184 offset:37888
	ds_read_b128 v[208:211], v184 offset:38912
	ds_read_b128 v[212:215], v184 offset:39936
	s_mov_b32 s86, m0
	s_mov_b32 m0, s48
	s_nop 0
	global_load_lds_dwordx4 v176, s[36:37]
	s_mov_b32 m0, s86
	s_nop 0
	s_mov_b32 s86, m0
	s_mov_b32 m0, s59
	s_nop 0
	global_load_lds_dwordx4 v178, s[36:37]
	s_mov_b32 m0, s86
	s_add_u32 s36, s36, 0x80000
	s_addc_u32 s37, s37, 0
	s_mov_b32 s86, m0
	s_mov_b32 m0, s62
	s_nop 0
	global_load_lds_dwordx4 v176, s[36:37]
	s_mov_b32 m0, s86
	s_nop 0
	s_mov_b32 s86, m0
	s_mov_b32 m0, s63
	s_nop 0
	global_load_lds_dwordx4 v178, s[36:37]
	s_mov_b32 m0, s86
	s_waitcnt vmcnt(8)
	s_waitcnt lgkmcnt(0)
	s_barrier
	s_setprio 1
	v_mfma_f32_16x16x32_bf16 v[142:145], v[58:61], v[170:173], v[142:145]
	v_mfma_f32_16x16x32_bf16 v[138:141], v[66:69], v[170:173], v[138:141]
	v_mfma_f32_16x16x32_bf16 v[126:129], v[58:61], v[192:195], v[126:129]
	v_mfma_f32_16x16x32_bf16 v[122:125], v[66:69], v[192:195], v[122:125]
	v_mfma_f32_16x16x32_bf16 v[110:113], v[58:61], v[200:203], v[110:113]
	v_mfma_f32_16x16x32_bf16 v[106:109], v[66:69], v[200:203], v[106:109]
	v_mfma_f32_16x16x32_bf16 v[94:97], v[58:61], v[208:211], v[94:97]
	v_mfma_f32_16x16x32_bf16 v[90:93], v[66:69], v[208:211], v[90:93]
	v_mfma_f32_16x16x32_bf16 v[142:145], v[62:65], v[188:191], v[142:145]
	v_mfma_f32_16x16x32_bf16 v[138:141], v[70:73], v[188:191], v[138:141]
	v_mfma_f32_16x16x32_bf16 v[126:129], v[62:65], v[196:199], v[126:129]
	v_mfma_f32_16x16x32_bf16 v[122:125], v[70:73], v[196:199], v[122:125]
	v_mfma_f32_16x16x32_bf16 v[110:113], v[62:65], v[204:207], v[110:113]
	v_mfma_f32_16x16x32_bf16 v[106:109], v[70:73], v[204:207], v[106:109]
	v_mfma_f32_16x16x32_bf16 v[94:97], v[62:65], v[212:215], v[94:97]
	v_mfma_f32_16x16x32_bf16 v[90:93], v[70:73], v[212:215], v[90:93]
	v_mfma_f32_16x16x32_bf16 v[134:137], v[146:149], v[170:173], v[134:137]
	v_mfma_f32_16x16x32_bf16 v[130:133], v[154:157], v[170:173], v[130:133]
	v_mfma_f32_16x16x32_bf16 v[118:121], v[146:149], v[192:195], v[118:121]
	v_mfma_f32_16x16x32_bf16 v[114:117], v[154:157], v[192:195], v[114:117]
	v_mfma_f32_16x16x32_bf16 v[102:105], v[146:149], v[200:203], v[102:105]
	v_mfma_f32_16x16x32_bf16 v[98:101], v[154:157], v[200:203], v[98:101]
	v_mfma_f32_16x16x32_bf16 v[86:89], v[146:149], v[208:211], v[86:89]
	v_mfma_f32_16x16x32_bf16 v[82:85], v[154:157], v[208:211], v[82:85]
	v_mfma_f32_16x16x32_bf16 v[134:137], v[150:153], v[188:191], v[134:137]
	v_mfma_f32_16x16x32_bf16 v[130:133], v[158:161], v[188:191], v[130:133]
	v_mfma_f32_16x16x32_bf16 v[118:121], v[150:153], v[196:199], v[118:121]
	v_mfma_f32_16x16x32_bf16 v[114:117], v[158:161], v[196:199], v[114:117]
	v_mfma_f32_16x16x32_bf16 v[102:105], v[150:153], v[204:207], v[102:105]
	v_mfma_f32_16x16x32_bf16 v[98:101], v[158:161], v[204:207], v[98:101]
	s_setprio 2
	s_barrier
	v_mfma_f32_16x16x32_bf16 v[86:89], v[150:153], v[212:215], v[86:89]
	v_mfma_f32_16x16x32_bf16 v[82:85], v[158:161], v[212:215], v[82:85]
	s_setprio 0
	ds_read_b128 v[170:173], v184 offset:49152
	ds_read_b128 v[188:191], v184 offset:50176
	ds_read_b128 v[192:195], v184 offset:51200
	ds_read_b128 v[196:199], v184 offset:52224
	ds_read_b128 v[200:203], v184 offset:53248
	ds_read_b128 v[204:207], v184 offset:54272
	ds_read_b128 v[208:211], v184 offset:55296
	ds_read_b128 v[212:215], v184 offset:56320
	s_add_u32 s36, s34, 0x80
	s_addc_u32 s37, s35, 0
	s_mov_b32 s86, m0
	s_mov_b32 m0, s64
	s_nop 0
	global_load_lds_dwordx4 v177, s[36:37]
	s_mov_b32 m0, s86
	s_add_u32 s34, s34, 0x80080
	s_mov_b32 s86, m0
	s_mov_b32 m0, s65
	s_nop 0
	global_load_lds_dwordx4 v179, s[36:37]
	s_mov_b32 m0, s86
	s_addc_u32 s35, s35, 0
	s_mov_b32 s36, m0
	s_mov_b32 m0, s66
	s_nop 0
	global_load_lds_dwordx4 v177, s[34:35]
	s_mov_b32 m0, s36
	s_nop 0
	s_mov_b32 s36, m0
	s_mov_b32 m0, s67
	s_nop 0
	global_load_lds_dwordx4 v179, s[34:35]
	s_mov_b32 m0, s36
	s_waitcnt vmcnt(4)
	s_waitcnt lgkmcnt(0)
	s_barrier
	s_setprio 1
	v_mfma_f32_16x16x32_bf16 v[78:81], v[58:61], v[170:173], v[78:81]
	v_mfma_f32_16x16x32_bf16 v[74:77], v[66:69], v[170:173], v[74:77]
	v_mfma_f32_16x16x32_bf16 v[50:53], v[58:61], v[192:195], v[50:53]
	v_mfma_f32_16x16x32_bf16 v[42:45], v[66:69], v[192:195], v[42:45]
	v_mfma_f32_16x16x32_bf16 v[30:33], v[58:61], v[200:203], v[30:33]
	v_mfma_f32_16x16x32_bf16 v[26:29], v[66:69], v[200:203], v[26:29]
	v_mfma_f32_16x16x32_bf16 v[14:17], v[58:61], v[208:211], v[14:17]
	v_mfma_f32_16x16x32_bf16 v[10:13], v[66:69], v[208:211], v[10:13]
	v_mfma_f32_16x16x32_bf16 v[78:81], v[62:65], v[188:191], v[78:81]
	v_mfma_f32_16x16x32_bf16 v[74:77], v[70:73], v[188:191], v[74:77]
	v_mfma_f32_16x16x32_bf16 v[50:53], v[62:65], v[196:199], v[50:53]
	v_mfma_f32_16x16x32_bf16 v[42:45], v[70:73], v[196:199], v[42:45]
	v_mfma_f32_16x16x32_bf16 v[30:33], v[62:65], v[204:207], v[30:33]
	v_mfma_f32_16x16x32_bf16 v[26:29], v[70:73], v[204:207], v[26:29]
	v_mfma_f32_16x16x32_bf16 v[14:17], v[62:65], v[212:215], v[14:17]
	v_mfma_f32_16x16x32_bf16 v[10:13], v[70:73], v[212:215], v[10:13]
	v_mfma_f32_16x16x32_bf16 v[46:49], v[146:149], v[170:173], v[46:49]
	v_mfma_f32_16x16x32_bf16 v[70:73], v[150:153], v[188:191], v[46:49]
	v_mfma_f32_16x16x32_bf16 v[46:49], v[154:157], v[170:173], v[54:57]
	v_mfma_f32_16x16x32_bf16 v[38:41], v[146:149], v[192:195], v[38:41]
	v_mfma_f32_16x16x32_bf16 v[34:37], v[154:157], v[192:195], v[34:37]
	v_mfma_f32_16x16x32_bf16 v[22:25], v[146:149], v[200:203], v[22:25]
	v_mfma_f32_16x16x32_bf16 v[18:21], v[154:157], v[200:203], v[18:21]
	v_mfma_f32_16x16x32_bf16 v[6:9], v[146:149], v[208:211], v[6:9]
	v_mfma_f32_16x16x32_bf16 v[2:5], v[154:157], v[208:211], v[2:5]
	v_mfma_f32_16x16x32_bf16 v[66:69], v[158:161], v[188:191], v[46:49]
	v_mfma_f32_16x16x32_bf16 v[38:41], v[150:153], v[196:199], v[38:41]
	v_mfma_f32_16x16x32_bf16 v[34:37], v[158:161], v[196:199], v[34:37]
	v_mfma_f32_16x16x32_bf16 v[22:25], v[150:153], v[204:207], v[22:25]
	v_mfma_f32_16x16x32_bf16 v[18:21], v[158:161], v[204:207], v[18:21]
	s_setprio 2
	s_barrier
	v_mfma_f32_16x16x32_bf16 v[6:9], v[150:153], v[212:215], v[6:9]
	v_mfma_f32_16x16x32_bf16 v[2:5], v[158:161], v[212:215], v[2:5]
	s_setprio 0
	s_add_i32 s83, s83, 2
	s_add_u32 s79, s79, 0x100
	s_addc_u32 s80, s80, 0
	s_add_u32 s30, s30, 0x100
	s_addc_u32 s31, s31, 0
	s_add_u32 s81, s81, 0x100
	s_addc_u32 s82, s82, 0
	s_cmp_gt_u32 s83, 29
	s_cbranch_scc0 .LBB0_1538
	s_and_b64 vcc, exec, s[16:17]
	s_cbranch_vccz .LBB0_1541
	s_barrier

.LBB0_1785:
	ds_read_b128 v[148:151], v143
	ds_read_b128 v[152:155], v143 offset:1024
	ds_read_b128 v[156:159], v143 offset:2048
	ds_read_b128 v[160:163], v143 offset:3072
	ds_read_b128 v[164:167], v144
	ds_read_b128 v[168:171], v144 offset:1024
	ds_read_b128 v[172:175], v144 offset:2048
	ds_read_b128 v[176:179], v144 offset:3072
	s_cmp_eq_u32 s73, 28
	s_cselect_b32 s21, s9, s67
	s_cselect_b32 s20, s65, s66
	s_cselect_b32 s23, s11, s71
	s_cselect_b32 s22, s64, s70
	ds_read_b128 v[180:183], v145
	ds_read_b128 v[184:187], v145 offset:1024
	ds_read_b128 v[188:191], v145 offset:2048
	ds_read_b128 v[192:195], v145 offset:3072
	ds_read_b128 v[196:199], v145 offset:4096
	ds_read_b128 v[200:203], v145 offset:5120
	ds_read_b128 v[204:207], v145 offset:6144
	ds_read_b128 v[208:211], v145 offset:7168
	s_add_u32 s74, s18, 0xfff80000
	s_addc_u32 s75, s19, -1
	s_mov_b32 s76, m0
	s_mov_b32 m0, s56
	s_nop 0
	global_load_lds_dwordx4 v138, s[74:75]
	s_mov_b32 m0, s76
	s_nop 0
	s_mov_b32 s76, m0
	s_mov_b32 m0, s59
	s_nop 0
	global_load_lds_dwordx4 v140, s[74:75]
	s_mov_b32 m0, s76
	s_mov_b32 s74, m0
	s_mov_b32 m0, s57
	s_nop 0
	global_load_lds_dwordx4 v138, s[18:19]
	s_mov_b32 m0, s74
	s_nop 0
	s_mov_b32 s74, m0
	s_mov_b32 m0, s62
	s_nop 0
	global_load_lds_dwordx4 v140, s[18:19]
	s_mov_b32 m0, s74
	s_waitcnt vmcnt(8)
	s_waitcnt lgkmcnt(0)
	s_barrier
	s_setprio 1
	v_mfma_f32_16x16x32_bf16 v[126:129], v[148:151], v[180:183], v[126:129]
	v_mfma_f32_16x16x32_bf16 v[122:125], v[156:159], v[180:183], v[122:125]
	v_mfma_f32_16x16x32_bf16 v[110:113], v[148:151], v[188:191], v[110:113]
	v_mfma_f32_16x16x32_bf16 v[106:109], v[156:159], v[188:191], v[106:109]
	v_mfma_f32_16x16x32_bf16 v[94:97], v[148:151], v[196:199], v[94:97]
	v_mfma_f32_16x16x32_bf16 v[90:93], v[156:159], v[196:199], v[90:93]
	v_mfma_f32_16x16x32_bf16 v[78:81], v[148:151], v[204:207], v[78:81]
	v_mfma_f32_16x16x32_bf16 v[74:77], v[156:159], v[204:207], v[74:77]
	v_mfma_f32_16x16x32_bf16 v[126:129], v[152:155], v[184:187], v[126:129]
	v_mfma_f32_16x16x32_bf16 v[122:125], v[160:163], v[184:187], v[122:125]
	v_mfma_f32_16x16x32_bf16 v[110:113], v[152:155], v[192:195], v[110:113]
	v_mfma_f32_16x16x32_bf16 v[106:109], v[160:163], v[192:195], v[106:109]
	v_mfma_f32_16x16x32_bf16 v[94:97], v[152:155], v[200:203], v[94:97]
	v_mfma_f32_16x16x32_bf16 v[90:93], v[160:163], v[200:203], v[90:93]
	v_mfma_f32_16x16x32_bf16 v[78:81], v[152:155], v[208:211], v[78:81]
	v_mfma_f32_16x16x32_bf16 v[74:77], v[160:163], v[208:211], v[74:77]
	v_mfma_f32_16x16x32_bf16 v[118:121], v[164:167], v[180:183], v[118:121]
	v_mfma_f32_16x16x32_bf16 v[114:117], v[172:175], v[180:183], v[114:117]
	v_mfma_f32_16x16x32_bf16 v[102:105], v[164:167], v[188:191], v[102:105]
	v_mfma_f32_16x16x32_bf16 v[98:101], v[172:175], v[188:191], v[98:101]
	v_mfma_f32_16x16x32_bf16 v[86:89], v[164:167], v[196:199], v[86:89]
	v_mfma_f32_16x16x32_bf16 v[82:85], v[172:175], v[196:199], v[82:85]
	v_mfma_f32_16x16x32_bf16 v[70:73], v[164:167], v[204:207], v[70:73]
	v_mfma_f32_16x16x32_bf16 v[66:69], v[172:175], v[204:207], v[66:69]
	v_mfma_f32_16x16x32_bf16 v[118:121], v[168:171], v[184:187], v[118:121]
	v_mfma_f32_16x16x32_bf16 v[114:117], v[176:179], v[184:187], v[114:117]
	v_mfma_f32_16x16x32_bf16 v[102:105], v[168:171], v[192:195], v[102:105]
	v_mfma_f32_16x16x32_bf16 v[98:101], v[176:179], v[192:195], v[98:101]
	v_mfma_f32_16x16x32_bf16 v[86:89], v[168:171], v[200:203], v[86:89]
	v_mfma_f32_16x16x32_bf16 v[82:85], v[176:179], v[200:203], v[82:85]
	s_setprio 2
	s_barrier
	v_mfma_f32_16x16x32_bf16 v[70:73], v[168:171], v[208:211], v[70:73]
	v_mfma_f32_16x16x32_bf16 v[66:69], v[176:179], v[208:211], v[66:69]
	s_setprio 0
	ds_read_b128 v[180:183], v145 offset:16384
	ds_read_b128 v[184:187], v145 offset:17408
	ds_read_b128 v[188:191], v145 offset:18432
	ds_read_b128 v[192:195], v145 offset:19456
	ds_read_b128 v[196:199], v145 offset:20480
	ds_read_b128 v[200:203], v145 offset:21504
	ds_read_b128 v[204:207], v145 offset:22528
	ds_read_b128 v[208:211], v145 offset:23552
	s_mov_b32 s74, m0
	s_mov_b32 m0, s35
	s_nop 0
	global_load_lds_dwordx4 v139, s[20:21]
	s_mov_b32 m0, s74
	s_nop 0
	s_mov_b32 s74, m0
	s_mov_b32 m0, s36
	s_nop 0
	global_load_lds_dwordx4 v141, s[20:21]
	s_mov_b32 m0, s74
	s_add_u32 s74, s20, 0x80000
	s_addc_u32 s75, s21, 0
	s_mov_b32 s76, m0
	s_mov_b32 m0, s37
	s_nop 0
	global_load_lds_dwordx4 v139, s[74:75]
	s_mov_b32 m0, s76
	s_nop 0
	s_mov_b32 s76, m0
	s_mov_b32 m0, s40
	s_nop 0
	global_load_lds_dwordx4 v141, s[74:75]
	s_mov_b32 m0, s76
	s_waitcnt vmcnt(4)
	s_waitcnt lgkmcnt(0)
	s_barrier
	s_setprio 1
	v_mfma_f32_16x16x32_bf16 v[62:65], v[148:151], v[180:183], v[62:65]
	v_mfma_f32_16x16x32_bf16 v[58:61], v[156:159], v[180:183], v[58:61]
	v_mfma_f32_16x16x32_bf16 v[46:49], v[148:151], v[188:191], v[46:49]
	v_mfma_f32_16x16x32_bf16 v[42:45], v[156:159], v[188:191], v[42:45]
	v_mfma_f32_16x16x32_bf16 v[30:33], v[148:151], v[196:199], v[30:33]
	v_mfma_f32_16x16x32_bf16 v[26:29], v[156:159], v[196:199], v[26:29]
	v_mfma_f32_16x16x32_bf16 v[14:17], v[148:151], v[204:207], v[14:17]
	v_mfma_f32_16x16x32_bf16 v[10:13], v[156:159], v[204:207], v[10:13]
	v_mfma_f32_16x16x32_bf16 v[62:65], v[152:155], v[184:187], v[62:65]
	v_mfma_f32_16x16x32_bf16 v[58:61], v[160:163], v[184:187], v[58:61]
	v_mfma_f32_16x16x32_bf16 v[46:49], v[152:155], v[192:195], v[46:49]
	v_mfma_f32_16x16x32_bf16 v[42:45], v[160:163], v[192:195], v[42:45]
	v_mfma_f32_16x16x32_bf16 v[30:33], v[152:155], v[200:203], v[30:33]
	v_mfma_f32_16x16x32_bf16 v[26:29], v[160:163], v[200:203], v[26:29]
	v_mfma_f32_16x16x32_bf16 v[14:17], v[152:155], v[208:211], v[14:17]
	v_mfma_f32_16x16x32_bf16 v[10:13], v[160:163], v[208:211], v[10:13]
	v_mfma_f32_16x16x32_bf16 v[54:57], v[164:167], v[180:183], v[54:57]
	v_mfma_f32_16x16x32_bf16 v[50:53], v[172:175], v[180:183], v[50:53]
	v_mfma_f32_16x16x32_bf16 v[38:41], v[164:167], v[188:191], v[38:41]
	v_mfma_f32_16x16x32_bf16 v[34:37], v[172:175], v[188:191], v[34:37]
	v_mfma_f32_16x16x32_bf16 v[22:25], v[164:167], v[196:199], v[22:25]
	v_mfma_f32_16x16x32_bf16 v[18:21], v[172:175], v[196:199], v[18:21]
	v_mfma_f32_16x16x32_bf16 v[6:9], v[164:167], v[204:207], v[6:9]
	v_mfma_f32_16x16x32_bf16 v[2:5], v[172:175], v[204:207], v[2:5]
	v_mfma_f32_16x16x32_bf16 v[54:57], v[168:171], v[184:187], v[54:57]
	v_mfma_f32_16x16x32_bf16 v[50:53], v[176:179], v[184:187], v[50:53]
	v_mfma_f32_16x16x32_bf16 v[38:41], v[168:171], v[192:195], v[38:41]
	v_mfma_f32_16x16x32_bf16 v[34:37], v[176:179], v[192:195], v[34:37]
	v_mfma_f32_16x16x32_bf16 v[22:25], v[168:171], v[200:203], v[22:25]
	v_mfma_f32_16x16x32_bf16 v[18:21], v[176:179], v[200:203], v[18:21]
	s_setprio 2
	s_barrier
	v_mfma_f32_16x16x32_bf16 v[6:9], v[168:171], v[208:211], v[6:9]
	v_mfma_f32_16x16x32_bf16 v[2:5], v[176:179], v[208:211], v[2:5]
	s_setprio 0
	ds_read_b128 v[148:151], v146
	ds_read_b128 v[152:155], v146 offset:1024
	ds_read_b128 v[156:159], v146 offset:2048
	ds_read_b128 v[160:163], v146 offset:3072
	ds_read_b128 v[164:167], v147
	ds_read_b128 v[168:171], v147 offset:1024
	ds_read_b128 v[172:175], v147 offset:2048
	ds_read_b128 v[176:179], v147 offset:3072
	ds_read_b128 v[180:183], v145 offset:32768
	ds_read_b128 v[184:187], v145 offset:33792
	ds_read_b128 v[188:191], v145 offset:34816
	ds_read_b128 v[192:195], v145 offset:35840
	ds_read_b128 v[196:199], v145 offset:36864
	ds_read_b128 v[200:203], v145 offset:37888
	ds_read_b128 v[204:207], v145 offset:38912
	ds_read_b128 v[208:211], v145 offset:39936
	s_mov_b32 s74, m0
	s_mov_b32 m0, s31
	s_nop 0
	global_load_lds_dwordx4 v138, s[22:23]
	s_mov_b32 m0, s74
	s_nop 0
	s_mov_b32 s74, m0
	s_mov_b32 m0, s41
	s_nop 0
	global_load_lds_dwordx4 v140, s[22:23]
	s_mov_b32 m0, s74
	s_add_u32 s22, s22, 0x80000
	s_addc_u32 s23, s23, 0
	s_mov_b32 s74, m0
	s_mov_b32 m0, s42
	s_nop 0
	global_load_lds_dwordx4 v138, s[22:23]
	s_mov_b32 m0, s74
	s_nop 0
	s_mov_b32 s74, m0
	s_mov_b32 m0, s43
	s_nop 0
	global_load_lds_dwordx4 v140, s[22:23]
	s_mov_b32 m0, s74
	s_waitcnt vmcnt(8)
	s_waitcnt lgkmcnt(0)
	s_barrier
	s_setprio 1
	v_mfma_f32_16x16x32_bf16 v[126:129], v[148:151], v[180:183], v[126:129]
	v_mfma_f32_16x16x32_bf16 v[122:125], v[156:159], v[180:183], v[122:125]
	v_mfma_f32_16x16x32_bf16 v[110:113], v[148:151], v[188:191], v[110:113]
	v_mfma_f32_16x16x32_bf16 v[106:109], v[156:159], v[188:191], v[106:109]
	v_mfma_f32_16x16x32_bf16 v[94:97], v[148:151], v[196:199], v[94:97]
	v_mfma_f32_16x16x32_bf16 v[90:93], v[156:159], v[196:199], v[90:93]
	v_mfma_f32_16x16x32_bf16 v[78:81], v[148:151], v[204:207], v[78:81]
	v_mfma_f32_16x16x32_bf16 v[74:77], v[156:159], v[204:207], v[74:77]
	v_mfma_f32_16x16x32_bf16 v[126:129], v[152:155], v[184:187], v[126:129]
	v_mfma_f32_16x16x32_bf16 v[122:125], v[160:163], v[184:187], v[122:125]
	v_mfma_f32_16x16x32_bf16 v[110:113], v[152:155], v[192:195], v[110:113]
	v_mfma_f32_16x16x32_bf16 v[106:109], v[160:163], v[192:195], v[106:109]
	v_mfma_f32_16x16x32_bf16 v[94:97], v[152:155], v[200:203], v[94:97]
	v_mfma_f32_16x16x32_bf16 v[90:93], v[160:163], v[200:203], v[90:93]
	v_mfma_f32_16x16x32_bf16 v[78:81], v[152:155], v[208:211], v[78:81]
	v_mfma_f32_16x16x32_bf16 v[74:77], v[160:163], v[208:211], v[74:77]
	v_mfma_f32_16x16x32_bf16 v[118:121], v[164:167], v[180:183], v[118:121]
	v_mfma_f32_16x16x32_bf16 v[114:117], v[172:175], v[180:183], v[114:117]
	v_mfma_f32_16x16x32_bf16 v[102:105], v[164:167], v[188:191], v[102:105]
	v_mfma_f32_16x16x32_bf16 v[98:101], v[172:175], v[188:191], v[98:101]
	v_mfma_f32_16x16x32_bf16 v[86:89], v[164:167], v[196:199], v[86:89]
	v_mfma_f32_16x16x32_bf16 v[82:85], v[172:175], v[196:199], v[82:85]
	v_mfma_f32_16x16x32_bf16 v[70:73], v[164:167], v[204:207], v[70:73]
	v_mfma_f32_16x16x32_bf16 v[66:69], v[172:175], v[204:207], v[66:69]
	v_mfma_f32_16x16x32_bf16 v[118:121], v[168:171], v[184:187], v[118:121]
	v_mfma_f32_16x16x32_bf16 v[114:117], v[176:179], v[184:187], v[114:117]
	v_mfma_f32_16x16x32_bf16 v[102:105], v[168:171], v[192:195], v[102:105]
	v_mfma_f32_16x16x32_bf16 v[98:101], v[176:179], v[192:195], v[98:101]
	v_mfma_f32_16x16x32_bf16 v[86:89], v[168:171], v[200:203], v[86:89]
	v_mfma_f32_16x16x32_bf16 v[82:85], v[176:179], v[200:203], v[82:85]
	s_setprio 2
	s_barrier
	v_mfma_f32_16x16x32_bf16 v[70:73], v[168:171], v[208:211], v[70:73]
	v_mfma_f32_16x16x32_bf16 v[66:69], v[176:179], v[208:211], v[66:69]
	s_setprio 0
	ds_read_b128 v[180:183], v145 offset:49152
	ds_read_b128 v[184:187], v145 offset:50176
	ds_read_b128 v[188:191], v145 offset:51200
	ds_read_b128 v[192:195], v145 offset:52224
	ds_read_b128 v[196:199], v145 offset:53248
	ds_read_b128 v[200:203], v145 offset:54272
	ds_read_b128 v[204:207], v145 offset:55296
	ds_read_b128 v[208:211], v145 offset:56320
	s_add_u32 s22, s20, 0x80
	s_addc_u32 s23, s21, 0
	s_mov_b32 s74, m0
	s_mov_b32 m0, s46
	s_nop 0
	global_load_lds_dwordx4 v139, s[22:23]
	s_mov_b32 m0, s74
	s_add_u32 s20, s20, 0x80080
	s_mov_b32 s74, m0
	s_mov_b32 m0, s47
	s_nop 0
	global_load_lds_dwordx4 v141, s[22:23]
	s_mov_b32 m0, s74
	s_addc_u32 s21, s21, 0
	s_mov_b32 s22, m0
	s_mov_b32 m0, s48
	s_nop 0
	global_load_lds_dwordx4 v139, s[20:21]
	s_mov_b32 m0, s22
	s_nop 0
	s_mov_b32 s22, m0
	s_mov_b32 m0, s49
	s_nop 0
	global_load_lds_dwordx4 v141, s[20:21]
	s_mov_b32 m0, s22
	s_waitcnt vmcnt(4)
	s_waitcnt lgkmcnt(0)
	s_barrier
	s_setprio 1
	v_mfma_f32_16x16x32_bf16 v[62:65], v[148:151], v[180:183], v[62:65]
	v_mfma_f32_16x16x32_bf16 v[58:61], v[156:159], v[180:183], v[58:61]
	v_mfma_f32_16x16x32_bf16 v[46:49], v[148:151], v[188:191], v[46:49]
	v_mfma_f32_16x16x32_bf16 v[42:45], v[156:159], v[188:191], v[42:45]
	v_mfma_f32_16x16x32_bf16 v[30:33], v[148:151], v[196:199], v[30:33]
	v_mfma_f32_16x16x32_bf16 v[26:29], v[156:159], v[196:199], v[26:29]
	v_mfma_f32_16x16x32_bf16 v[14:17], v[148:151], v[204:207], v[14:17]
	v_mfma_f32_16x16x32_bf16 v[10:13], v[156:159], v[204:207], v[10:13]
	v_mfma_f32_16x16x32_bf16 v[62:65], v[152:155], v[184:187], v[62:65]
	v_mfma_f32_16x16x32_bf16 v[58:61], v[160:163], v[184:187], v[58:61]
	v_mfma_f32_16x16x32_bf16 v[46:49], v[152:155], v[192:195], v[46:49]
	v_mfma_f32_16x16x32_bf16 v[42:45], v[160:163], v[192:195], v[42:45]
	v_mfma_f32_16x16x32_bf16 v[30:33], v[152:155], v[200:203], v[30:33]
	v_mfma_f32_16x16x32_bf16 v[26:29], v[160:163], v[200:203], v[26:29]
	v_mfma_f32_16x16x32_bf16 v[14:17], v[152:155], v[208:211], v[14:17]
	v_mfma_f32_16x16x32_bf16 v[10:13], v[160:163], v[208:211], v[10:13]
	v_mfma_f32_16x16x32_bf16 v[54:57], v[164:167], v[180:183], v[54:57]
	v_mfma_f32_16x16x32_bf16 v[50:53], v[172:175], v[180:183], v[50:53]
	v_mfma_f32_16x16x32_bf16 v[38:41], v[164:167], v[188:191], v[38:41]
	v_mfma_f32_16x16x32_bf16 v[34:37], v[172:175], v[188:191], v[34:37]
	v_mfma_f32_16x16x32_bf16 v[22:25], v[164:167], v[196:199], v[22:25]
	v_mfma_f32_16x16x32_bf16 v[18:21], v[172:175], v[196:199], v[18:21]
	v_mfma_f32_16x16x32_bf16 v[6:9], v[164:167], v[204:207], v[6:9]
	v_mfma_f32_16x16x32_bf16 v[2:5], v[172:175], v[204:207], v[2:5]
	v_mfma_f32_16x16x32_bf16 v[54:57], v[168:171], v[184:187], v[54:57]
	v_mfma_f32_16x16x32_bf16 v[50:53], v[176:179], v[184:187], v[50:53]
	v_mfma_f32_16x16x32_bf16 v[38:41], v[168:171], v[192:195], v[38:41]
	v_mfma_f32_16x16x32_bf16 v[34:37], v[176:179], v[192:195], v[34:37]
	v_mfma_f32_16x16x32_bf16 v[22:25], v[168:171], v[200:203], v[22:25]
	v_mfma_f32_16x16x32_bf16 v[18:21], v[176:179], v[200:203], v[18:21]
	s_setprio 2
	s_barrier
	v_mfma_f32_16x16x32_bf16 v[6:9], v[168:171], v[208:211], v[6:9]
	v_mfma_f32_16x16x32_bf16 v[2:5], v[176:179], v[208:211], v[2:5]
	s_setprio 0
	s_add_i32 s73, s73, 2
	s_add_u32 s66, s66, 0x100
	s_addc_u32 s67, s67, 0
	s_add_u32 s18, s18, 0x100
	s_addc_u32 s19, s19, 0
	s_add_u32 s70, s70, 0x100
	s_addc_u32 s71, s71, 0
	s_cmp_gt_u32 s73, 29
	s_cbranch_scc0 .LBB0_1785
	s_and_b64 vcc, exec, s[6:7]
	s_cbranch_vccz .LBB0_1788
	s_barrier

.LBB0_1952:
	ds_read_b128 v[130:133], v181
	ds_read_b128 v[134:137], v181 offset:1024
	ds_read_b128 v[138:141], v181 offset:2048
	ds_read_b128 v[142:145], v181 offset:3072
	ds_read_b128 v[150:153], v182
	ds_read_b128 v[154:157], v182 offset:1024
	ds_read_b128 v[158:161], v182 offset:2048
	ds_read_b128 v[162:165], v182 offset:3072
	s_cmpk_eq_i32 s74, 0x52
	s_cselect_b32 s23, s11, s70
	s_cselect_b32 s22, s66, s67
	s_cselect_b32 s25, s13, s73
	s_cselect_b32 s24, s65, s71
	ds_read_b128 v[166:169], v183
	ds_read_b128 v[170:173], v183 offset:1024
	ds_read_b128 v[186:189], v183 offset:2048
	ds_read_b128 v[190:193], v183 offset:3072
	ds_read_b128 v[194:197], v183 offset:4096
	ds_read_b128 v[198:201], v183 offset:5120
	ds_read_b128 v[202:205], v183 offset:6144
	ds_read_b128 v[206:209], v183 offset:7168
	s_add_u32 s76, s20, 0xffffc000
	s_addc_u32 s77, s21, -1
	s_mov_b32 s75, m0
	s_mov_b32 m0, s58
	s_nop 0
	global_load_lds_dwordx4 v1, s[76:77]
	s_mov_b32 m0, s75
	s_nop 0
	s_mov_b32 s75, m0
	s_mov_b32 m0, s62
	s_nop 0
	global_load_lds_dwordx4 v177, s[76:77]
	s_mov_b32 m0, s75
	s_nop 0
	s_mov_b32 s75, m0
	s_mov_b32 m0, s59
	s_nop 0
	global_load_lds_dwordx4 v1, s[20:21]
	s_mov_b32 m0, s75
	s_nop 0
	s_mov_b32 s75, m0
	s_mov_b32 m0, s63
	s_nop 0
	global_load_lds_dwordx4 v177, s[20:21]
	s_mov_b32 m0, s75
	s_waitcnt vmcnt(8)
	s_waitcnt lgkmcnt(0)
	s_barrier
	s_setprio 1
	v_mfma_f32_16x16x32_bf16 v[126:129], v[130:133], v[166:169], v[126:129]
	v_mfma_f32_16x16x32_bf16 v[122:125], v[138:141], v[166:169], v[122:125]
	v_mfma_f32_16x16x32_bf16 v[118:121], v[130:133], v[186:189], v[118:121]
	v_mfma_f32_16x16x32_bf16 v[110:113], v[138:141], v[186:189], v[110:113]
	v_mfma_f32_16x16x32_bf16 v[94:97], v[130:133], v[194:197], v[94:97]
	v_mfma_f32_16x16x32_bf16 v[90:93], v[138:141], v[194:197], v[90:93]
	v_mfma_f32_16x16x32_bf16 v[86:89], v[130:133], v[202:205], v[86:89]
	v_mfma_f32_16x16x32_bf16 v[78:81], v[138:141], v[202:205], v[78:81]
	v_mfma_f32_16x16x32_bf16 v[126:129], v[134:137], v[170:173], v[126:129]
	v_mfma_f32_16x16x32_bf16 v[122:125], v[142:145], v[170:173], v[122:125]
	v_mfma_f32_16x16x32_bf16 v[118:121], v[134:137], v[190:193], v[118:121]
	v_mfma_f32_16x16x32_bf16 v[110:113], v[142:145], v[190:193], v[110:113]
	v_mfma_f32_16x16x32_bf16 v[94:97], v[134:137], v[198:201], v[94:97]
	v_mfma_f32_16x16x32_bf16 v[90:93], v[142:145], v[198:201], v[90:93]
	v_mfma_f32_16x16x32_bf16 v[86:89], v[134:137], v[206:209], v[86:89]
	v_mfma_f32_16x16x32_bf16 v[78:81], v[142:145], v[206:209], v[78:81]
	v_mfma_f32_16x16x32_bf16 v[114:117], v[150:153], v[166:169], v[114:117]
	v_mfma_f32_16x16x32_bf16 v[106:109], v[158:161], v[166:169], v[106:109]
	v_mfma_f32_16x16x32_bf16 v[102:105], v[150:153], v[186:189], v[102:105]
	v_mfma_f32_16x16x32_bf16 v[98:101], v[158:161], v[186:189], v[98:101]
	v_mfma_f32_16x16x32_bf16 v[82:85], v[150:153], v[194:197], v[82:85]
	v_mfma_f32_16x16x32_bf16 v[74:77], v[158:161], v[194:197], v[74:77]
	v_mfma_f32_16x16x32_bf16 v[70:73], v[150:153], v[202:205], v[70:73]
	v_mfma_f32_16x16x32_bf16 v[66:69], v[158:161], v[202:205], v[66:69]
	v_mfma_f32_16x16x32_bf16 v[114:117], v[154:157], v[170:173], v[114:117]
	v_mfma_f32_16x16x32_bf16 v[106:109], v[162:165], v[170:173], v[106:109]
	v_mfma_f32_16x16x32_bf16 v[102:105], v[154:157], v[190:193], v[102:105]
	v_mfma_f32_16x16x32_bf16 v[98:101], v[162:165], v[190:193], v[98:101]
	v_mfma_f32_16x16x32_bf16 v[82:85], v[154:157], v[198:201], v[82:85]
	v_mfma_f32_16x16x32_bf16 v[74:77], v[162:165], v[198:201], v[74:77]
	s_setprio 2
	s_barrier
	v_mfma_f32_16x16x32_bf16 v[70:73], v[154:157], v[206:209], v[70:73]
	v_mfma_f32_16x16x32_bf16 v[66:69], v[162:165], v[206:209], v[66:69]
	s_setprio 0
	ds_read_b128 v[166:169], v183 offset:16384
	ds_read_b128 v[170:173], v183 offset:17408
	ds_read_b128 v[186:189], v183 offset:18432
	ds_read_b128 v[190:193], v183 offset:19456
	ds_read_b128 v[194:197], v183 offset:20480
	ds_read_b128 v[198:201], v183 offset:21504
	ds_read_b128 v[202:205], v183 offset:22528
	ds_read_b128 v[206:209], v183 offset:23552
	s_mov_b32 s75, m0
	s_mov_b32 m0, s35
	s_nop 0
	global_load_lds_dwordx4 v176, s[22:23]
	s_mov_b32 m0, s75
	s_add_u32 s76, s22, 0x4000
	s_mov_b32 s75, m0
	s_mov_b32 m0, s36
	s_nop 0
	global_load_lds_dwordx4 v178, s[22:23]
	s_mov_b32 m0, s75
	s_addc_u32 s77, s23, 0
	s_mov_b32 s75, m0
	s_mov_b32 m0, s37
	s_nop 0
	global_load_lds_dwordx4 v176, s[76:77]
	s_mov_b32 m0, s75
	s_nop 0
	s_mov_b32 s75, m0
	s_mov_b32 m0, s40
	s_nop 0
	global_load_lds_dwordx4 v178, s[76:77]
	s_mov_b32 m0, s75
	s_waitcnt vmcnt(4)
	s_waitcnt lgkmcnt(0)
	s_barrier
	s_setprio 1
	v_mfma_f32_16x16x32_bf16 v[62:65], v[130:133], v[166:169], v[62:65]
	v_mfma_f32_16x16x32_bf16 v[58:61], v[138:141], v[166:169], v[58:61]
	v_mfma_f32_16x16x32_bf16 v[46:49], v[130:133], v[186:189], v[46:49]
	v_mfma_f32_16x16x32_bf16 v[42:45], v[138:141], v[186:189], v[42:45]
	v_mfma_f32_16x16x32_bf16 v[30:33], v[130:133], v[194:197], v[30:33]
	v_mfma_f32_16x16x32_bf16 v[26:29], v[138:141], v[194:197], v[26:29]
	v_mfma_f32_16x16x32_bf16 v[14:17], v[130:133], v[202:205], v[14:17]
	v_mfma_f32_16x16x32_bf16 v[10:13], v[138:141], v[202:205], v[10:13]
	v_mfma_f32_16x16x32_bf16 v[62:65], v[134:137], v[170:173], v[62:65]
	v_mfma_f32_16x16x32_bf16 v[58:61], v[142:145], v[170:173], v[58:61]
	v_mfma_f32_16x16x32_bf16 v[46:49], v[134:137], v[190:193], v[46:49]
	v_mfma_f32_16x16x32_bf16 v[42:45], v[142:145], v[190:193], v[42:45]
	v_mfma_f32_16x16x32_bf16 v[30:33], v[134:137], v[198:201], v[30:33]
	v_mfma_f32_16x16x32_bf16 v[26:29], v[142:145], v[198:201], v[26:29]
	v_mfma_f32_16x16x32_bf16 v[14:17], v[134:137], v[206:209], v[14:17]
	v_mfma_f32_16x16x32_bf16 v[10:13], v[142:145], v[206:209], v[10:13]
	v_mfma_f32_16x16x32_bf16 v[54:57], v[150:153], v[166:169], v[54:57]
	v_mfma_f32_16x16x32_bf16 v[50:53], v[158:161], v[166:169], v[50:53]
	v_mfma_f32_16x16x32_bf16 v[38:41], v[150:153], v[186:189], v[38:41]
	v_mfma_f32_16x16x32_bf16 v[34:37], v[158:161], v[186:189], v[34:37]
	v_mfma_f32_16x16x32_bf16 v[22:25], v[150:153], v[194:197], v[22:25]
	v_mfma_f32_16x16x32_bf16 v[18:21], v[158:161], v[194:197], v[18:21]
	v_mfma_f32_16x16x32_bf16 v[6:9], v[150:153], v[202:205], v[6:9]
	v_mfma_f32_16x16x32_bf16 v[2:5], v[158:161], v[202:205], v[2:5]
	v_mfma_f32_16x16x32_bf16 v[54:57], v[154:157], v[170:173], v[54:57]
	v_mfma_f32_16x16x32_bf16 v[50:53], v[162:165], v[170:173], v[50:53]
	v_mfma_f32_16x16x32_bf16 v[38:41], v[154:157], v[190:193], v[38:41]
	v_mfma_f32_16x16x32_bf16 v[34:37], v[162:165], v[190:193], v[34:37]
	v_mfma_f32_16x16x32_bf16 v[22:25], v[154:157], v[198:201], v[22:25]
	v_mfma_f32_16x16x32_bf16 v[18:21], v[162:165], v[198:201], v[18:21]
	s_setprio 2
	s_barrier
	v_mfma_f32_16x16x32_bf16 v[6:9], v[154:157], v[206:209], v[6:9]
	v_mfma_f32_16x16x32_bf16 v[2:5], v[162:165], v[206:209], v[2:5]
	s_setprio 0
	ds_read_b128 v[130:133], v184
	ds_read_b128 v[134:137], v184 offset:1024
	ds_read_b128 v[138:141], v184 offset:2048
	ds_read_b128 v[142:145], v184 offset:3072
	ds_read_b128 v[150:153], v185
	ds_read_b128 v[154:157], v185 offset:1024
	ds_read_b128 v[158:161], v185 offset:2048
	ds_read_b128 v[162:165], v185 offset:3072
	ds_read_b128 v[166:169], v183 offset:32768
	ds_read_b128 v[170:173], v183 offset:33792
	ds_read_b128 v[186:189], v183 offset:34816
	ds_read_b128 v[190:193], v183 offset:35840
	ds_read_b128 v[194:197], v183 offset:36864
	ds_read_b128 v[198:201], v183 offset:37888
	ds_read_b128 v[202:205], v183 offset:38912
	ds_read_b128 v[206:209], v183 offset:39936
	s_mov_b32 s75, m0
	s_mov_b32 m0, s34
	s_nop 0
	global_load_lds_dwordx4 v1, s[24:25]
	s_mov_b32 m0, s75
	s_nop 0
	s_mov_b32 s75, m0
	s_mov_b32 m0, s41
	s_nop 0
	global_load_lds_dwordx4 v177, s[24:25]
	s_mov_b32 m0, s75
	s_add_u32 s24, s24, 0x4000
	s_addc_u32 s25, s25, 0
	s_mov_b32 s75, m0
	s_mov_b32 m0, s42
	s_nop 0
	global_load_lds_dwordx4 v1, s[24:25]
	s_mov_b32 m0, s75
	s_nop 0
	s_mov_b32 s75, m0
	s_mov_b32 m0, s43
	s_nop 0
	global_load_lds_dwordx4 v177, s[24:25]
	s_mov_b32 m0, s75
	s_waitcnt vmcnt(8)
	s_waitcnt lgkmcnt(0)
	s_barrier
	s_setprio 1
	v_mfma_f32_16x16x32_bf16 v[126:129], v[130:133], v[166:169], v[126:129]
	v_mfma_f32_16x16x32_bf16 v[122:125], v[138:141], v[166:169], v[122:125]
	v_mfma_f32_16x16x32_bf16 v[118:121], v[130:133], v[186:189], v[118:121]
	v_mfma_f32_16x16x32_bf16 v[110:113], v[138:141], v[186:189], v[110:113]
	v_mfma_f32_16x16x32_bf16 v[94:97], v[130:133], v[194:197], v[94:97]
	v_mfma_f32_16x16x32_bf16 v[90:93], v[138:141], v[194:197], v[90:93]
	v_mfma_f32_16x16x32_bf16 v[86:89], v[130:133], v[202:205], v[86:89]
	v_mfma_f32_16x16x32_bf16 v[78:81], v[138:141], v[202:205], v[78:81]
	v_mfma_f32_16x16x32_bf16 v[126:129], v[134:137], v[170:173], v[126:129]
	v_mfma_f32_16x16x32_bf16 v[122:125], v[142:145], v[170:173], v[122:125]
	v_mfma_f32_16x16x32_bf16 v[118:121], v[134:137], v[190:193], v[118:121]
	v_mfma_f32_16x16x32_bf16 v[110:113], v[142:145], v[190:193], v[110:113]
	v_mfma_f32_16x16x32_bf16 v[94:97], v[134:137], v[198:201], v[94:97]
	v_mfma_f32_16x16x32_bf16 v[90:93], v[142:145], v[198:201], v[90:93]
	v_mfma_f32_16x16x32_bf16 v[86:89], v[134:137], v[206:209], v[86:89]
	v_mfma_f32_16x16x32_bf16 v[78:81], v[142:145], v[206:209], v[78:81]
	v_mfma_f32_16x16x32_bf16 v[114:117], v[150:153], v[166:169], v[114:117]
	v_mfma_f32_16x16x32_bf16 v[106:109], v[158:161], v[166:169], v[106:109]
	v_mfma_f32_16x16x32_bf16 v[102:105], v[150:153], v[186:189], v[102:105]
	v_mfma_f32_16x16x32_bf16 v[98:101], v[158:161], v[186:189], v[98:101]
	v_mfma_f32_16x16x32_bf16 v[82:85], v[150:153], v[194:197], v[82:85]
	v_mfma_f32_16x16x32_bf16 v[74:77], v[158:161], v[194:197], v[74:77]
	v_mfma_f32_16x16x32_bf16 v[70:73], v[150:153], v[202:205], v[70:73]
	v_mfma_f32_16x16x32_bf16 v[66:69], v[158:161], v[202:205], v[66:69]
	v_mfma_f32_16x16x32_bf16 v[114:117], v[154:157], v[170:173], v[114:117]
	v_mfma_f32_16x16x32_bf16 v[106:109], v[162:165], v[170:173], v[106:109]
	v_mfma_f32_16x16x32_bf16 v[102:105], v[154:157], v[190:193], v[102:105]
	v_mfma_f32_16x16x32_bf16 v[98:101], v[162:165], v[190:193], v[98:101]
	v_mfma_f32_16x16x32_bf16 v[82:85], v[154:157], v[198:201], v[82:85]
	v_mfma_f32_16x16x32_bf16 v[74:77], v[162:165], v[198:201], v[74:77]
	s_setprio 2
	s_barrier
	v_mfma_f32_16x16x32_bf16 v[70:73], v[154:157], v[206:209], v[70:73]
	v_mfma_f32_16x16x32_bf16 v[66:69], v[162:165], v[206:209], v[66:69]
	s_setprio 0
	ds_read_b128 v[166:169], v183 offset:49152
	ds_read_b128 v[170:173], v183 offset:50176
	ds_read_b128 v[186:189], v183 offset:51200
	ds_read_b128 v[190:193], v183 offset:52224
	ds_read_b128 v[194:197], v183 offset:53248
	ds_read_b128 v[198:201], v183 offset:54272
	ds_read_b128 v[202:205], v183 offset:55296
	ds_read_b128 v[206:209], v183 offset:56320
	s_add_u32 s24, s22, 0x40000
	s_addc_u32 s25, s23, 0
	s_mov_b32 s75, m0
	s_mov_b32 m0, s46
	s_nop 0
	global_load_lds_dwordx4 v176, s[24:25]
	s_mov_b32 m0, s75
	s_add_u32 s22, s22, 0x44000
	s_mov_b32 s75, m0
	s_mov_b32 m0, s47
	s_nop 0
	global_load_lds_dwordx4 v178, s[24:25]
	s_mov_b32 m0, s75
	s_addc_u32 s23, s23, 0
	s_mov_b32 s24, m0
	s_mov_b32 m0, s48
	s_nop 0
	global_load_lds_dwordx4 v176, s[22:23]
	s_mov_b32 m0, s24
	s_nop 0
	s_mov_b32 s24, m0
	s_mov_b32 m0, s49
	s_nop 0
	global_load_lds_dwordx4 v178, s[22:23]
	s_mov_b32 m0, s24
	s_waitcnt vmcnt(4)
	s_waitcnt lgkmcnt(0)
	s_barrier
	s_setprio 1
	v_mfma_f32_16x16x32_bf16 v[62:65], v[130:133], v[166:169], v[62:65]
	v_mfma_f32_16x16x32_bf16 v[58:61], v[138:141], v[166:169], v[58:61]
	v_mfma_f32_16x16x32_bf16 v[46:49], v[130:133], v[186:189], v[46:49]
	v_mfma_f32_16x16x32_bf16 v[42:45], v[138:141], v[186:189], v[42:45]
	v_mfma_f32_16x16x32_bf16 v[30:33], v[130:133], v[194:197], v[30:33]
	v_mfma_f32_16x16x32_bf16 v[26:29], v[138:141], v[194:197], v[26:29]
	v_mfma_f32_16x16x32_bf16 v[14:17], v[130:133], v[202:205], v[14:17]
	v_mfma_f32_16x16x32_bf16 v[10:13], v[138:141], v[202:205], v[10:13]
	v_mfma_f32_16x16x32_bf16 v[62:65], v[134:137], v[170:173], v[62:65]
	v_mfma_f32_16x16x32_bf16 v[58:61], v[142:145], v[170:173], v[58:61]
	v_mfma_f32_16x16x32_bf16 v[46:49], v[134:137], v[190:193], v[46:49]
	v_mfma_f32_16x16x32_bf16 v[42:45], v[142:145], v[190:193], v[42:45]
	v_mfma_f32_16x16x32_bf16 v[30:33], v[134:137], v[198:201], v[30:33]
	v_mfma_f32_16x16x32_bf16 v[26:29], v[142:145], v[198:201], v[26:29]
	v_mfma_f32_16x16x32_bf16 v[14:17], v[134:137], v[206:209], v[14:17]
	v_mfma_f32_16x16x32_bf16 v[10:13], v[142:145], v[206:209], v[10:13]
	v_mfma_f32_16x16x32_bf16 v[54:57], v[150:153], v[166:169], v[54:57]
	v_mfma_f32_16x16x32_bf16 v[50:53], v[158:161], v[166:169], v[50:53]
	v_mfma_f32_16x16x32_bf16 v[38:41], v[150:153], v[186:189], v[38:41]
	v_mfma_f32_16x16x32_bf16 v[34:37], v[158:161], v[186:189], v[34:37]
	v_mfma_f32_16x16x32_bf16 v[22:25], v[150:153], v[194:197], v[22:25]
	v_mfma_f32_16x16x32_bf16 v[18:21], v[158:161], v[194:197], v[18:21]
	v_mfma_f32_16x16x32_bf16 v[6:9], v[150:153], v[202:205], v[6:9]
	v_mfma_f32_16x16x32_bf16 v[2:5], v[158:161], v[202:205], v[2:5]
	v_mfma_f32_16x16x32_bf16 v[54:57], v[154:157], v[170:173], v[54:57]
	v_mfma_f32_16x16x32_bf16 v[50:53], v[162:165], v[170:173], v[50:53]
	v_mfma_f32_16x16x32_bf16 v[38:41], v[154:157], v[190:193], v[38:41]
	v_mfma_f32_16x16x32_bf16 v[34:37], v[162:165], v[190:193], v[34:37]
	v_mfma_f32_16x16x32_bf16 v[22:25], v[154:157], v[198:201], v[22:25]
	v_mfma_f32_16x16x32_bf16 v[18:21], v[162:165], v[198:201], v[18:21]
	s_setprio 2
	s_barrier
	v_mfma_f32_16x16x32_bf16 v[6:9], v[154:157], v[206:209], v[6:9]
	v_mfma_f32_16x16x32_bf16 v[2:5], v[162:165], v[206:209], v[2:5]
	s_setprio 0
	s_add_i32 s74, s74, 2
	s_add_u32 s67, s67, 0x80000
	s_addc_u32 s70, s70, 0
	s_add_u32 s20, s20, 0x400000
	s_addc_u32 s21, s21, 0
	s_add_u32 s71, s71, 0x400000
	s_addc_u32 s73, s73, 0
	s_cmpk_gt_u32 s74, 0x53
	s_cbranch_scc0 .LBB0_1952
	s_and_b64 vcc, exec, s[8:9]
	s_cbranch_vccz .LBB0_1955
	s_barrier

.LBB0_2146:
	ds_read_b128 v[42:45], v181
	ds_read_b128 v[46:49], v181 offset:1024
	ds_read_b128 v[58:61], v181 offset:2048
	ds_read_b128 v[62:65], v181 offset:3072
	ds_read_b128 v[146:149], v182
	ds_read_b128 v[150:153], v182 offset:1024
	ds_read_b128 v[154:157], v182 offset:2048
	ds_read_b128 v[158:161], v182 offset:3072
	s_cmp_eq_u32 s81, 28
	s_cselect_b32 s37, s23, s78
	s_cselect_b32 s36, s31, s77
	s_cselect_b32 s41, s5, s80
	s_cselect_b32 s40, s25, s79
	ds_read_b128 v[170:173], v183
	ds_read_b128 v[188:191], v183 offset:1024
	ds_read_b128 v[192:195], v183 offset:2048
	ds_read_b128 v[196:199], v183 offset:3072
	ds_read_b128 v[200:203], v183 offset:4096
	ds_read_b128 v[204:207], v183 offset:5120
	ds_read_b128 v[208:211], v183 offset:6144
	ds_read_b128 v[212:215], v183 offset:7168
	s_add_u32 s82, s34, 0xfff80000
	s_addc_u32 s83, s35, -1
	s_mov_b32 s86, m0
	s_mov_b32 m0, s70
	s_nop 0
	global_load_lds_dwordx4 v1, s[82:83]
	s_mov_b32 m0, s86
	s_nop 0
	s_mov_b32 s86, m0
	s_mov_b32 m0, s73
	s_nop 0
	global_load_lds_dwordx4 v177, s[82:83]
	s_mov_b32 m0, s86
	s_mov_b32 s82, m0
	s_mov_b32 m0, s71
	s_nop 0
	global_load_lds_dwordx4 v1, s[34:35]
	s_mov_b32 m0, s82
	s_nop 0
	s_mov_b32 s82, m0
	s_mov_b32 m0, s74
	s_nop 0
	global_load_lds_dwordx4 v177, s[34:35]
	s_mov_b32 m0, s82
	s_waitcnt vmcnt(8)
	s_waitcnt lgkmcnt(0)
	s_barrier
	s_setprio 1
	v_mfma_f32_16x16x32_bf16 v[142:145], v[42:45], v[170:173], v[142:145]
	v_mfma_f32_16x16x32_bf16 v[138:141], v[58:61], v[170:173], v[138:141]
	v_mfma_f32_16x16x32_bf16 v[126:129], v[42:45], v[192:195], v[126:129]
	v_mfma_f32_16x16x32_bf16 v[122:125], v[58:61], v[192:195], v[122:125]
	v_mfma_f32_16x16x32_bf16 v[110:113], v[42:45], v[200:203], v[110:113]
	v_mfma_f32_16x16x32_bf16 v[106:109], v[58:61], v[200:203], v[106:109]
	v_mfma_f32_16x16x32_bf16 v[94:97], v[42:45], v[208:211], v[94:97]
	v_mfma_f32_16x16x32_bf16 v[90:93], v[58:61], v[208:211], v[90:93]
	v_mfma_f32_16x16x32_bf16 v[142:145], v[46:49], v[188:191], v[142:145]
	v_mfma_f32_16x16x32_bf16 v[138:141], v[62:65], v[188:191], v[138:141]
	v_mfma_f32_16x16x32_bf16 v[126:129], v[46:49], v[196:199], v[126:129]
	v_mfma_f32_16x16x32_bf16 v[122:125], v[62:65], v[196:199], v[122:125]
	v_mfma_f32_16x16x32_bf16 v[110:113], v[46:49], v[204:207], v[110:113]
	v_mfma_f32_16x16x32_bf16 v[106:109], v[62:65], v[204:207], v[106:109]
	v_mfma_f32_16x16x32_bf16 v[94:97], v[46:49], v[212:215], v[94:97]
	v_mfma_f32_16x16x32_bf16 v[90:93], v[62:65], v[212:215], v[90:93]
	v_mfma_f32_16x16x32_bf16 v[134:137], v[146:149], v[170:173], v[134:137]
	v_mfma_f32_16x16x32_bf16 v[130:133], v[154:157], v[170:173], v[130:133]
	v_mfma_f32_16x16x32_bf16 v[118:121], v[146:149], v[192:195], v[118:121]
	v_mfma_f32_16x16x32_bf16 v[114:117], v[154:157], v[192:195], v[114:117]
	v_mfma_f32_16x16x32_bf16 v[102:105], v[146:149], v[200:203], v[102:105]
	v_mfma_f32_16x16x32_bf16 v[98:101], v[154:157], v[200:203], v[98:101]
	v_mfma_f32_16x16x32_bf16 v[86:89], v[146:149], v[208:211], v[86:89]
	v_mfma_f32_16x16x32_bf16 v[82:85], v[154:157], v[208:211], v[82:85]
	v_mfma_f32_16x16x32_bf16 v[134:137], v[150:153], v[188:191], v[134:137]
	v_mfma_f32_16x16x32_bf16 v[130:133], v[158:161], v[188:191], v[130:133]
	v_mfma_f32_16x16x32_bf16 v[118:121], v[150:153], v[196:199], v[118:121]
	v_mfma_f32_16x16x32_bf16 v[114:117], v[158:161], v[196:199], v[114:117]
	v_mfma_f32_16x16x32_bf16 v[102:105], v[150:153], v[204:207], v[102:105]
	v_mfma_f32_16x16x32_bf16 v[98:101], v[158:161], v[204:207], v[98:101]
	s_setprio 2
	s_barrier
	v_mfma_f32_16x16x32_bf16 v[86:89], v[150:153], v[212:215], v[86:89]
	v_mfma_f32_16x16x32_bf16 v[82:85], v[158:161], v[212:215], v[82:85]
	s_setprio 0
	ds_read_b128 v[170:173], v183 offset:16384
	ds_read_b128 v[188:191], v183 offset:17408
	ds_read_b128 v[192:195], v183 offset:18432
	ds_read_b128 v[196:199], v183 offset:19456
	ds_read_b128 v[200:203], v183 offset:20480
	ds_read_b128 v[204:207], v183 offset:21504
	ds_read_b128 v[208:211], v183 offset:22528
	ds_read_b128 v[212:215], v183 offset:23552
	s_mov_b32 s82, m0
	s_mov_b32 m0, s49
	s_nop 0
	global_load_lds_dwordx4 v176, s[36:37]
	s_mov_b32 m0, s82
	s_nop 0
	s_mov_b32 s82, m0
	s_mov_b32 m0, s56
	s_nop 0
	global_load_lds_dwordx4 v178, s[36:37]
	s_mov_b32 m0, s82
	s_add_u32 s82, s36, 0x80000
	s_addc_u32 s83, s37, 0
	s_mov_b32 s86, m0
	s_mov_b32 m0, s57
	s_nop 0
	global_load_lds_dwordx4 v176, s[82:83]
	s_mov_b32 m0, s86
	s_nop 0
	s_mov_b32 s86, m0
	s_mov_b32 m0, s58
	s_nop 0
	global_load_lds_dwordx4 v178, s[82:83]
	s_mov_b32 m0, s86
	s_waitcnt vmcnt(4)
	s_waitcnt lgkmcnt(0)
	s_barrier
	s_setprio 1
	v_mfma_f32_16x16x32_bf16 v[78:81], v[42:45], v[170:173], v[78:81]
	v_mfma_f32_16x16x32_bf16 v[74:77], v[58:61], v[170:173], v[74:77]
	v_mfma_f32_16x16x32_bf16 v[54:57], v[42:45], v[192:195], v[54:57]
	v_mfma_f32_16x16x32_bf16 v[50:53], v[58:61], v[192:195], v[50:53]
	v_mfma_f32_16x16x32_bf16 v[30:33], v[42:45], v[200:203], v[30:33]
	v_mfma_f32_16x16x32_bf16 v[26:29], v[58:61], v[200:203], v[26:29]
	v_mfma_f32_16x16x32_bf16 v[14:17], v[42:45], v[208:211], v[14:17]
	v_mfma_f32_16x16x32_bf16 v[10:13], v[58:61], v[208:211], v[10:13]
	v_mfma_f32_16x16x32_bf16 v[78:81], v[46:49], v[188:191], v[78:81]
	v_mfma_f32_16x16x32_bf16 v[74:77], v[62:65], v[188:191], v[74:77]
	v_mfma_f32_16x16x32_bf16 v[54:57], v[46:49], v[196:199], v[54:57]
	v_mfma_f32_16x16x32_bf16 v[50:53], v[62:65], v[196:199], v[50:53]
	v_mfma_f32_16x16x32_bf16 v[30:33], v[46:49], v[204:207], v[30:33]
	v_mfma_f32_16x16x32_bf16 v[26:29], v[62:65], v[204:207], v[26:29]
	v_mfma_f32_16x16x32_bf16 v[14:17], v[46:49], v[212:215], v[14:17]
	v_mfma_f32_16x16x32_bf16 v[10:13], v[62:65], v[212:215], v[10:13]
	v_mfma_f32_16x16x32_bf16 v[38:41], v[146:149], v[192:195], v[38:41]
	v_mfma_f32_16x16x32_bf16 v[34:37], v[154:157], v[192:195], v[34:37]
	v_mfma_f32_16x16x32_bf16 v[22:25], v[146:149], v[200:203], v[22:25]
	v_mfma_f32_16x16x32_bf16 v[18:21], v[154:157], v[200:203], v[18:21]
	v_mfma_f32_16x16x32_bf16 v[6:9], v[146:149], v[208:211], v[6:9]
	v_mfma_f32_16x16x32_bf16 v[2:5], v[154:157], v[208:211], v[2:5]
	v_mfma_f32_16x16x32_bf16 v[42:45], v[146:149], v[170:173], v[70:73]
	v_mfma_f32_16x16x32_bf16 v[46:49], v[154:157], v[170:173], v[66:69]
	v_mfma_f32_16x16x32_bf16 v[38:41], v[150:153], v[196:199], v[38:41]
	v_mfma_f32_16x16x32_bf16 v[34:37], v[158:161], v[196:199], v[34:37]
	v_mfma_f32_16x16x32_bf16 v[22:25], v[150:153], v[204:207], v[22:25]
	v_mfma_f32_16x16x32_bf16 v[18:21], v[158:161], v[204:207], v[18:21]
	v_mfma_f32_16x16x32_bf16 v[6:9], v[150:153], v[212:215], v[6:9]
	v_mfma_f32_16x16x32_bf16 v[2:5], v[158:161], v[212:215], v[2:5]
	s_setprio 2
	s_barrier
	v_mfma_f32_16x16x32_bf16 v[42:45], v[150:153], v[188:191], v[42:45]
	v_mfma_f32_16x16x32_bf16 v[46:49], v[158:161], v[188:191], v[46:49]
	s_setprio 0
	ds_read_b128 v[58:61], v184
	ds_read_b128 v[62:65], v184 offset:1024
	ds_read_b128 v[66:69], v184 offset:2048
	ds_read_b128 v[70:73], v184 offset:3072
	ds_read_b128 v[146:149], v185
	ds_read_b128 v[150:153], v185 offset:1024
	ds_read_b128 v[154:157], v185 offset:2048
	ds_read_b128 v[158:161], v185 offset:3072
	ds_read_b128 v[170:173], v183 offset:32768
	ds_read_b128 v[188:191], v183 offset:33792
	ds_read_b128 v[192:195], v183 offset:34816
	ds_read_b128 v[196:199], v183 offset:35840
	ds_read_b128 v[200:203], v183 offset:36864
	ds_read_b128 v[204:207], v183 offset:37888
	ds_read_b128 v[208:211], v183 offset:38912
	ds_read_b128 v[212:215], v183 offset:39936
	s_mov_b32 s82, m0
	s_mov_b32 m0, s48
	s_nop 0
	global_load_lds_dwordx4 v1, s[40:41]
	s_mov_b32 m0, s82
	s_nop 0
	s_mov_b32 s82, m0
	s_mov_b32 m0, s59
	s_nop 0
	global_load_lds_dwordx4 v177, s[40:41]
	s_mov_b32 m0, s82
	s_add_u32 s40, s40, 0x80000
	s_addc_u32 s41, s41, 0
	s_mov_b32 s82, m0
	s_mov_b32 m0, s62
	s_nop 0
	global_load_lds_dwordx4 v1, s[40:41]
	s_mov_b32 m0, s82
	s_nop 0
	s_mov_b32 s82, m0
	s_mov_b32 m0, s63
	s_nop 0
	global_load_lds_dwordx4 v177, s[40:41]
	s_mov_b32 m0, s82
	s_waitcnt vmcnt(8)
	s_waitcnt lgkmcnt(0)
	s_barrier
	s_setprio 1
	v_mfma_f32_16x16x32_bf16 v[142:145], v[58:61], v[170:173], v[142:145]
	v_mfma_f32_16x16x32_bf16 v[138:141], v[66:69], v[170:173], v[138:141]
	v_mfma_f32_16x16x32_bf16 v[126:129], v[58:61], v[192:195], v[126:129]
	v_mfma_f32_16x16x32_bf16 v[122:125], v[66:69], v[192:195], v[122:125]
	v_mfma_f32_16x16x32_bf16 v[110:113], v[58:61], v[200:203], v[110:113]
	v_mfma_f32_16x16x32_bf16 v[106:109], v[66:69], v[200:203], v[106:109]
	v_mfma_f32_16x16x32_bf16 v[94:97], v[58:61], v[208:211], v[94:97]
	v_mfma_f32_16x16x32_bf16 v[90:93], v[66:69], v[208:211], v[90:93]
	v_mfma_f32_16x16x32_bf16 v[142:145], v[62:65], v[188:191], v[142:145]
	v_mfma_f32_16x16x32_bf16 v[138:141], v[70:73], v[188:191], v[138:141]
	v_mfma_f32_16x16x32_bf16 v[126:129], v[62:65], v[196:199], v[126:129]
	v_mfma_f32_16x16x32_bf16 v[122:125], v[70:73], v[196:199], v[122:125]
	v_mfma_f32_16x16x32_bf16 v[110:113], v[62:65], v[204:207], v[110:113]
	v_mfma_f32_16x16x32_bf16 v[106:109], v[70:73], v[204:207], v[106:109]
	v_mfma_f32_16x16x32_bf16 v[94:97], v[62:65], v[212:215], v[94:97]
	v_mfma_f32_16x16x32_bf16 v[90:93], v[70:73], v[212:215], v[90:93]
	v_mfma_f32_16x16x32_bf16 v[134:137], v[146:149], v[170:173], v[134:137]
	v_mfma_f32_16x16x32_bf16 v[130:133], v[154:157], v[170:173], v[130:133]
	v_mfma_f32_16x16x32_bf16 v[118:121], v[146:149], v[192:195], v[118:121]
	v_mfma_f32_16x16x32_bf16 v[114:117], v[154:157], v[192:195], v[114:117]
	v_mfma_f32_16x16x32_bf16 v[102:105], v[146:149], v[200:203], v[102:105]
	v_mfma_f32_16x16x32_bf16 v[98:101], v[154:157], v[200:203], v[98:101]
	v_mfma_f32_16x16x32_bf16 v[86:89], v[146:149], v[208:211], v[86:89]
	v_mfma_f32_16x16x32_bf16 v[82:85], v[154:157], v[208:211], v[82:85]
	v_mfma_f32_16x16x32_bf16 v[134:137], v[150:153], v[188:191], v[134:137]
	v_mfma_f32_16x16x32_bf16 v[130:133], v[158:161], v[188:191], v[130:133]
	v_mfma_f32_16x16x32_bf16 v[118:121], v[150:153], v[196:199], v[118:121]
	v_mfma_f32_16x16x32_bf16 v[114:117], v[158:161], v[196:199], v[114:117]
	v_mfma_f32_16x16x32_bf16 v[102:105], v[150:153], v[204:207], v[102:105]
	v_mfma_f32_16x16x32_bf16 v[98:101], v[158:161], v[204:207], v[98:101]
	s_setprio 2
	s_barrier
	v_mfma_f32_16x16x32_bf16 v[86:89], v[150:153], v[212:215], v[86:89]
	v_mfma_f32_16x16x32_bf16 v[82:85], v[158:161], v[212:215], v[82:85]
	s_setprio 0
	ds_read_b128 v[170:173], v183 offset:49152
	ds_read_b128 v[188:191], v183 offset:50176
	ds_read_b128 v[192:195], v183 offset:51200
	ds_read_b128 v[196:199], v183 offset:52224
	ds_read_b128 v[200:203], v183 offset:53248
	ds_read_b128 v[204:207], v183 offset:54272
	ds_read_b128 v[208:211], v183 offset:55296
	ds_read_b128 v[212:215], v183 offset:56320
	s_add_u32 s40, s36, 0x80
	s_addc_u32 s41, s37, 0
	s_mov_b32 s82, m0
	s_mov_b32 m0, s64
	s_nop 0
	global_load_lds_dwordx4 v176, s[40:41]
	s_mov_b32 m0, s82
	s_add_u32 s36, s36, 0x80080
	s_mov_b32 s82, m0
	s_mov_b32 m0, s65
	s_nop 0
	global_load_lds_dwordx4 v178, s[40:41]
	s_mov_b32 m0, s82
	s_addc_u32 s37, s37, 0
	s_mov_b32 s40, m0
	s_mov_b32 m0, s66
	s_nop 0
	global_load_lds_dwordx4 v176, s[36:37]
	s_mov_b32 m0, s40
	s_nop 0
	s_mov_b32 s40, m0
	s_mov_b32 m0, s67
	s_nop 0
	global_load_lds_dwordx4 v178, s[36:37]
	s_mov_b32 m0, s40
	s_waitcnt vmcnt(4)
	s_waitcnt lgkmcnt(0)
	s_barrier
	s_setprio 1
	v_mfma_f32_16x16x32_bf16 v[78:81], v[58:61], v[170:173], v[78:81]
	v_mfma_f32_16x16x32_bf16 v[74:77], v[66:69], v[170:173], v[74:77]
	v_mfma_f32_16x16x32_bf16 v[54:57], v[58:61], v[192:195], v[54:57]
	v_mfma_f32_16x16x32_bf16 v[50:53], v[66:69], v[192:195], v[50:53]
	v_mfma_f32_16x16x32_bf16 v[30:33], v[58:61], v[200:203], v[30:33]
	v_mfma_f32_16x16x32_bf16 v[26:29], v[66:69], v[200:203], v[26:29]
	v_mfma_f32_16x16x32_bf16 v[14:17], v[58:61], v[208:211], v[14:17]
	v_mfma_f32_16x16x32_bf16 v[10:13], v[66:69], v[208:211], v[10:13]
	v_mfma_f32_16x16x32_bf16 v[78:81], v[62:65], v[188:191], v[78:81]
	v_mfma_f32_16x16x32_bf16 v[74:77], v[70:73], v[188:191], v[74:77]
	v_mfma_f32_16x16x32_bf16 v[54:57], v[62:65], v[196:199], v[54:57]
	v_mfma_f32_16x16x32_bf16 v[50:53], v[70:73], v[196:199], v[50:53]
	v_mfma_f32_16x16x32_bf16 v[30:33], v[62:65], v[204:207], v[30:33]
	v_mfma_f32_16x16x32_bf16 v[26:29], v[70:73], v[204:207], v[26:29]
	v_mfma_f32_16x16x32_bf16 v[14:17], v[62:65], v[212:215], v[14:17]
	v_mfma_f32_16x16x32_bf16 v[10:13], v[70:73], v[212:215], v[10:13]
	v_mfma_f32_16x16x32_bf16 v[42:45], v[146:149], v[170:173], v[42:45]
	v_mfma_f32_16x16x32_bf16 v[70:73], v[150:153], v[188:191], v[42:45]
	v_mfma_f32_16x16x32_bf16 v[42:45], v[154:157], v[170:173], v[46:49]
	v_mfma_f32_16x16x32_bf16 v[38:41], v[146:149], v[192:195], v[38:41]
	v_mfma_f32_16x16x32_bf16 v[34:37], v[154:157], v[192:195], v[34:37]
	v_mfma_f32_16x16x32_bf16 v[22:25], v[146:149], v[200:203], v[22:25]
	v_mfma_f32_16x16x32_bf16 v[18:21], v[154:157], v[200:203], v[18:21]
	v_mfma_f32_16x16x32_bf16 v[6:9], v[146:149], v[208:211], v[6:9]
	v_mfma_f32_16x16x32_bf16 v[2:5], v[154:157], v[208:211], v[2:5]
	v_mfma_f32_16x16x32_bf16 v[66:69], v[158:161], v[188:191], v[42:45]
	v_mfma_f32_16x16x32_bf16 v[38:41], v[150:153], v[196:199], v[38:41]
	v_mfma_f32_16x16x32_bf16 v[34:37], v[158:161], v[196:199], v[34:37]
	v_mfma_f32_16x16x32_bf16 v[22:25], v[150:153], v[204:207], v[22:25]
	v_mfma_f32_16x16x32_bf16 v[18:21], v[158:161], v[204:207], v[18:21]
	s_setprio 2
	s_barrier
	v_mfma_f32_16x16x32_bf16 v[6:9], v[150:153], v[212:215], v[6:9]
	v_mfma_f32_16x16x32_bf16 v[2:5], v[158:161], v[212:215], v[2:5]
	s_setprio 0
	s_add_i32 s81, s81, 2
	s_add_u32 s77, s77, 0x100
	s_addc_u32 s78, s78, 0
	s_add_u32 s34, s34, 0x100
	s_addc_u32 s35, s35, 0
	s_add_u32 s79, s79, 0x100
	s_addc_u32 s80, s80, 0
	s_cmp_gt_u32 s81, 29
	s_cbranch_scc0 .LBB0_2146
	s_and_b64 vcc, exec, s[14:15]
	s_cbranch_vccz .LBB0_2149
	s_barrier

.LBB0_2410:
	ds_read_b128 v[130:133], v181
	ds_read_b128 v[134:137], v181 offset:1024
	ds_read_b128 v[138:141], v181 offset:2048
	ds_read_b128 v[142:145], v181 offset:3072
	ds_read_b128 v[146:149], v182
	ds_read_b128 v[150:153], v182 offset:1024
	ds_read_b128 v[154:157], v182 offset:2048
	ds_read_b128 v[158:161], v182 offset:3072
	s_cmp_eq_u32 s78, 28
	s_cselect_b32 s27, s15, s75
	s_cselect_b32 s26, s73, s74
	s_cselect_b32 s29, s17, s77
	s_cselect_b32 s28, s71, s76
	ds_read_b128 v[166:169], v183
	ds_read_b128 v[170:173], v183 offset:1024
	ds_read_b128 v[186:189], v183 offset:2048
	ds_read_b128 v[190:193], v183 offset:3072
	ds_read_b128 v[194:197], v183 offset:4096
	ds_read_b128 v[198:201], v183 offset:5120
	ds_read_b128 v[202:205], v183 offset:6144
	ds_read_b128 v[206:209], v183 offset:7168
	s_add_u32 s80, s24, 0xfff80000
	s_addc_u32 s81, s25, -1
	s_mov_b32 s79, m0
	s_mov_b32 m0, s64
	s_nop 0
	global_load_lds_dwordx4 v1, s[80:81]
	s_mov_b32 m0, s79
	s_nop 0
	s_mov_b32 s79, m0
	s_mov_b32 m0, s66
	s_nop 0
	global_load_lds_dwordx4 v177, s[80:81]
	s_mov_b32 m0, s79
	s_nop 0
	s_mov_b32 s79, m0
	s_mov_b32 m0, s65
	s_nop 0
	global_load_lds_dwordx4 v1, s[24:25]
	s_mov_b32 m0, s79
	s_nop 0
	s_mov_b32 s79, m0
	s_mov_b32 m0, s67
	s_nop 0
	global_load_lds_dwordx4 v177, s[24:25]
	s_mov_b32 m0, s79
	s_waitcnt vmcnt(8)
	s_waitcnt lgkmcnt(0)
	s_barrier
	s_setprio 1
	v_mfma_f32_16x16x32_bf16 v[126:129], v[130:133], v[166:169], v[126:129]
	v_mfma_f32_16x16x32_bf16 v[122:125], v[138:141], v[166:169], v[122:125]
	v_mfma_f32_16x16x32_bf16 v[118:121], v[130:133], v[186:189], v[118:121]
	v_mfma_f32_16x16x32_bf16 v[114:117], v[138:141], v[186:189], v[114:117]
	v_mfma_f32_16x16x32_bf16 v[94:97], v[130:133], v[194:197], v[94:97]
	v_mfma_f32_16x16x32_bf16 v[90:93], v[138:141], v[194:197], v[90:93]
	v_mfma_f32_16x16x32_bf16 v[86:89], v[130:133], v[202:205], v[86:89]
	v_mfma_f32_16x16x32_bf16 v[78:81], v[138:141], v[202:205], v[78:81]
	v_mfma_f32_16x16x32_bf16 v[126:129], v[134:137], v[170:173], v[126:129]
	v_mfma_f32_16x16x32_bf16 v[122:125], v[142:145], v[170:173], v[122:125]
	v_mfma_f32_16x16x32_bf16 v[118:121], v[134:137], v[190:193], v[118:121]
	v_mfma_f32_16x16x32_bf16 v[114:117], v[142:145], v[190:193], v[114:117]
	v_mfma_f32_16x16x32_bf16 v[94:97], v[134:137], v[198:201], v[94:97]
	v_mfma_f32_16x16x32_bf16 v[90:93], v[142:145], v[198:201], v[90:93]
	v_mfma_f32_16x16x32_bf16 v[86:89], v[134:137], v[206:209], v[86:89]
	v_mfma_f32_16x16x32_bf16 v[78:81], v[142:145], v[206:209], v[78:81]
	v_mfma_f32_16x16x32_bf16 v[110:113], v[146:149], v[166:169], v[110:113]
	v_mfma_f32_16x16x32_bf16 v[106:109], v[154:157], v[166:169], v[106:109]
	v_mfma_f32_16x16x32_bf16 v[102:105], v[146:149], v[186:189], v[102:105]
	v_mfma_f32_16x16x32_bf16 v[98:101], v[154:157], v[186:189], v[98:101]
	v_mfma_f32_16x16x32_bf16 v[82:85], v[146:149], v[194:197], v[82:85]
	v_mfma_f32_16x16x32_bf16 v[74:77], v[154:157], v[194:197], v[74:77]
	v_mfma_f32_16x16x32_bf16 v[70:73], v[146:149], v[202:205], v[70:73]
	v_mfma_f32_16x16x32_bf16 v[66:69], v[154:157], v[202:205], v[66:69]
	v_mfma_f32_16x16x32_bf16 v[110:113], v[150:153], v[170:173], v[110:113]
	v_mfma_f32_16x16x32_bf16 v[106:109], v[158:161], v[170:173], v[106:109]
	v_mfma_f32_16x16x32_bf16 v[102:105], v[150:153], v[190:193], v[102:105]
	v_mfma_f32_16x16x32_bf16 v[98:101], v[158:161], v[190:193], v[98:101]
	v_mfma_f32_16x16x32_bf16 v[82:85], v[150:153], v[198:201], v[82:85]
	v_mfma_f32_16x16x32_bf16 v[74:77], v[158:161], v[198:201], v[74:77]
	s_setprio 2
	s_barrier
	v_mfma_f32_16x16x32_bf16 v[70:73], v[150:153], v[206:209], v[70:73]
	v_mfma_f32_16x16x32_bf16 v[66:69], v[158:161], v[206:209], v[66:69]
	s_setprio 0
	ds_read_b128 v[166:169], v183 offset:16384
	ds_read_b128 v[170:173], v183 offset:17408
	ds_read_b128 v[186:189], v183 offset:18432
	ds_read_b128 v[190:193], v183 offset:19456
	ds_read_b128 v[194:197], v183 offset:20480
	ds_read_b128 v[198:201], v183 offset:21504
	ds_read_b128 v[202:205], v183 offset:22528
	ds_read_b128 v[206:209], v183 offset:23552
	s_mov_b32 s79, m0
	s_mov_b32 m0, s41
	s_nop 0
	global_load_lds_dwordx4 v176, s[26:27]
	s_mov_b32 m0, s79
	s_add_u32 s80, s26, 0x80000
	s_mov_b32 s79, m0
	s_mov_b32 m0, s42
	s_nop 0
	global_load_lds_dwordx4 v178, s[26:27]
	s_mov_b32 m0, s79
	s_addc_u32 s81, s27, 0
	s_mov_b32 s79, m0
	s_mov_b32 m0, s43
	s_nop 0
	global_load_lds_dwordx4 v176, s[80:81]
	s_mov_b32 m0, s79
	s_nop 0
	s_mov_b32 s79, m0
	s_mov_b32 m0, s46
	s_nop 0
	global_load_lds_dwordx4 v178, s[80:81]
	s_mov_b32 m0, s79
	s_waitcnt vmcnt(4)
	s_waitcnt lgkmcnt(0)
	s_barrier
	s_setprio 1
	v_mfma_f32_16x16x32_bf16 v[62:65], v[130:133], v[166:169], v[62:65]
	v_mfma_f32_16x16x32_bf16 v[58:61], v[138:141], v[166:169], v[58:61]
	v_mfma_f32_16x16x32_bf16 v[46:49], v[130:133], v[186:189], v[46:49]
	v_mfma_f32_16x16x32_bf16 v[42:45], v[138:141], v[186:189], v[42:45]
	v_mfma_f32_16x16x32_bf16 v[30:33], v[130:133], v[194:197], v[30:33]
	v_mfma_f32_16x16x32_bf16 v[26:29], v[138:141], v[194:197], v[26:29]
	v_mfma_f32_16x16x32_bf16 v[14:17], v[130:133], v[202:205], v[14:17]
	v_mfma_f32_16x16x32_bf16 v[10:13], v[138:141], v[202:205], v[10:13]
	v_mfma_f32_16x16x32_bf16 v[62:65], v[134:137], v[170:173], v[62:65]
	v_mfma_f32_16x16x32_bf16 v[58:61], v[142:145], v[170:173], v[58:61]
	v_mfma_f32_16x16x32_bf16 v[46:49], v[134:137], v[190:193], v[46:49]
	v_mfma_f32_16x16x32_bf16 v[42:45], v[142:145], v[190:193], v[42:45]
	v_mfma_f32_16x16x32_bf16 v[30:33], v[134:137], v[198:201], v[30:33]
	v_mfma_f32_16x16x32_bf16 v[26:29], v[142:145], v[198:201], v[26:29]
	v_mfma_f32_16x16x32_bf16 v[14:17], v[134:137], v[206:209], v[14:17]
	v_mfma_f32_16x16x32_bf16 v[10:13], v[142:145], v[206:209], v[10:13]
	v_mfma_f32_16x16x32_bf16 v[54:57], v[146:149], v[166:169], v[54:57]
	v_mfma_f32_16x16x32_bf16 v[50:53], v[154:157], v[166:169], v[50:53]
	v_mfma_f32_16x16x32_bf16 v[38:41], v[146:149], v[186:189], v[38:41]
	v_mfma_f32_16x16x32_bf16 v[34:37], v[154:157], v[186:189], v[34:37]
	v_mfma_f32_16x16x32_bf16 v[22:25], v[146:149], v[194:197], v[22:25]
	v_mfma_f32_16x16x32_bf16 v[18:21], v[154:157], v[194:197], v[18:21]
	v_mfma_f32_16x16x32_bf16 v[6:9], v[146:149], v[202:205], v[6:9]
	v_mfma_f32_16x16x32_bf16 v[2:5], v[154:157], v[202:205], v[2:5]
	v_mfma_f32_16x16x32_bf16 v[54:57], v[150:153], v[170:173], v[54:57]
	v_mfma_f32_16x16x32_bf16 v[50:53], v[158:161], v[170:173], v[50:53]
	v_mfma_f32_16x16x32_bf16 v[38:41], v[150:153], v[190:193], v[38:41]
	v_mfma_f32_16x16x32_bf16 v[34:37], v[158:161], v[190:193], v[34:37]
	v_mfma_f32_16x16x32_bf16 v[22:25], v[150:153], v[198:201], v[22:25]
	v_mfma_f32_16x16x32_bf16 v[18:21], v[158:161], v[198:201], v[18:21]
	s_setprio 2
	s_barrier
	v_mfma_f32_16x16x32_bf16 v[6:9], v[150:153], v[206:209], v[6:9]
	v_mfma_f32_16x16x32_bf16 v[2:5], v[158:161], v[206:209], v[2:5]
	s_setprio 0
	ds_read_b128 v[130:133], v184
	ds_read_b128 v[134:137], v184 offset:1024
	ds_read_b128 v[138:141], v184 offset:2048
	ds_read_b128 v[142:145], v184 offset:3072
	ds_read_b128 v[146:149], v185
	ds_read_b128 v[150:153], v185 offset:1024
	ds_read_b128 v[154:157], v185 offset:2048
	ds_read_b128 v[158:161], v185 offset:3072
	ds_read_b128 v[166:169], v183 offset:32768
	ds_read_b128 v[170:173], v183 offset:33792
	ds_read_b128 v[186:189], v183 offset:34816
	ds_read_b128 v[190:193], v183 offset:35840
	ds_read_b128 v[194:197], v183 offset:36864
	ds_read_b128 v[198:201], v183 offset:37888
	ds_read_b128 v[202:205], v183 offset:38912
	ds_read_b128 v[206:209], v183 offset:39936
	s_mov_b32 s79, m0
	s_mov_b32 m0, s40
	s_nop 0
	global_load_lds_dwordx4 v1, s[28:29]
	s_mov_b32 m0, s79
	s_nop 0
	s_mov_b32 s79, m0
	s_mov_b32 m0, s47
	s_nop 0
	global_load_lds_dwordx4 v177, s[28:29]
	s_mov_b32 m0, s79
	s_add_u32 s28, s28, 0x80000
	s_addc_u32 s29, s29, 0
	s_mov_b32 s79, m0
	s_mov_b32 m0, s48
	s_nop 0
	global_load_lds_dwordx4 v1, s[28:29]
	s_mov_b32 m0, s79
	s_nop 0
	s_mov_b32 s79, m0
	s_mov_b32 m0, s49
	s_nop 0
	global_load_lds_dwordx4 v177, s[28:29]
	s_mov_b32 m0, s79
	s_waitcnt vmcnt(8)
	s_waitcnt lgkmcnt(0)
	s_barrier
	s_setprio 1
	v_mfma_f32_16x16x32_bf16 v[126:129], v[130:133], v[166:169], v[126:129]
	v_mfma_f32_16x16x32_bf16 v[122:125], v[138:141], v[166:169], v[122:125]
	v_mfma_f32_16x16x32_bf16 v[118:121], v[130:133], v[186:189], v[118:121]
	v_mfma_f32_16x16x32_bf16 v[114:117], v[138:141], v[186:189], v[114:117]
	v_mfma_f32_16x16x32_bf16 v[94:97], v[130:133], v[194:197], v[94:97]
	v_mfma_f32_16x16x32_bf16 v[90:93], v[138:141], v[194:197], v[90:93]
	v_mfma_f32_16x16x32_bf16 v[86:89], v[130:133], v[202:205], v[86:89]
	v_mfma_f32_16x16x32_bf16 v[78:81], v[138:141], v[202:205], v[78:81]
	v_mfma_f32_16x16x32_bf16 v[126:129], v[134:137], v[170:173], v[126:129]
	v_mfma_f32_16x16x32_bf16 v[122:125], v[142:145], v[170:173], v[122:125]
	v_mfma_f32_16x16x32_bf16 v[118:121], v[134:137], v[190:193], v[118:121]
	v_mfma_f32_16x16x32_bf16 v[114:117], v[142:145], v[190:193], v[114:117]
	v_mfma_f32_16x16x32_bf16 v[94:97], v[134:137], v[198:201], v[94:97]
	v_mfma_f32_16x16x32_bf16 v[90:93], v[142:145], v[198:201], v[90:93]
	v_mfma_f32_16x16x32_bf16 v[86:89], v[134:137], v[206:209], v[86:89]
	v_mfma_f32_16x16x32_bf16 v[78:81], v[142:145], v[206:209], v[78:81]
	v_mfma_f32_16x16x32_bf16 v[110:113], v[146:149], v[166:169], v[110:113]
	v_mfma_f32_16x16x32_bf16 v[106:109], v[154:157], v[166:169], v[106:109]
	v_mfma_f32_16x16x32_bf16 v[102:105], v[146:149], v[186:189], v[102:105]
	v_mfma_f32_16x16x32_bf16 v[98:101], v[154:157], v[186:189], v[98:101]
	v_mfma_f32_16x16x32_bf16 v[82:85], v[146:149], v[194:197], v[82:85]
	v_mfma_f32_16x16x32_bf16 v[74:77], v[154:157], v[194:197], v[74:77]
	v_mfma_f32_16x16x32_bf16 v[70:73], v[146:149], v[202:205], v[70:73]
	v_mfma_f32_16x16x32_bf16 v[66:69], v[154:157], v[202:205], v[66:69]
	v_mfma_f32_16x16x32_bf16 v[110:113], v[150:153], v[170:173], v[110:113]
	v_mfma_f32_16x16x32_bf16 v[106:109], v[158:161], v[170:173], v[106:109]
	v_mfma_f32_16x16x32_bf16 v[102:105], v[150:153], v[190:193], v[102:105]
	v_mfma_f32_16x16x32_bf16 v[98:101], v[158:161], v[190:193], v[98:101]
	v_mfma_f32_16x16x32_bf16 v[82:85], v[150:153], v[198:201], v[82:85]
	v_mfma_f32_16x16x32_bf16 v[74:77], v[158:161], v[198:201], v[74:77]
	s_setprio 2
	s_barrier
	v_mfma_f32_16x16x32_bf16 v[70:73], v[150:153], v[206:209], v[70:73]
	v_mfma_f32_16x16x32_bf16 v[66:69], v[158:161], v[206:209], v[66:69]
	s_setprio 0
	ds_read_b128 v[166:169], v183 offset:49152
	ds_read_b128 v[170:173], v183 offset:50176
	ds_read_b128 v[186:189], v183 offset:51200
	ds_read_b128 v[190:193], v183 offset:52224
	ds_read_b128 v[194:197], v183 offset:53248
	ds_read_b128 v[198:201], v183 offset:54272
	ds_read_b128 v[202:205], v183 offset:55296
	ds_read_b128 v[206:209], v183 offset:56320
	s_add_u32 s28, s26, 0x80
	s_addc_u32 s29, s27, 0
	s_mov_b32 s79, m0
	s_mov_b32 m0, s56
	s_nop 0
	global_load_lds_dwordx4 v176, s[28:29]
	s_mov_b32 m0, s79
	s_add_u32 s26, s26, 0x80080
	s_mov_b32 s79, m0
	s_mov_b32 m0, s57
	s_nop 0
	global_load_lds_dwordx4 v178, s[28:29]
	s_mov_b32 m0, s79
	s_addc_u32 s27, s27, 0
	s_mov_b32 s28, m0
	s_mov_b32 m0, s58
	s_nop 0
	global_load_lds_dwordx4 v176, s[26:27]
	s_mov_b32 m0, s28
	s_nop 0
	s_mov_b32 s28, m0
	s_mov_b32 m0, s59
	s_nop 0
	global_load_lds_dwordx4 v178, s[26:27]
	s_mov_b32 m0, s28
	s_waitcnt vmcnt(4)
	s_waitcnt lgkmcnt(0)
	s_barrier
	s_setprio 1
	v_mfma_f32_16x16x32_bf16 v[62:65], v[130:133], v[166:169], v[62:65]
	v_mfma_f32_16x16x32_bf16 v[58:61], v[138:141], v[166:169], v[58:61]
	v_mfma_f32_16x16x32_bf16 v[46:49], v[130:133], v[186:189], v[46:49]
	v_mfma_f32_16x16x32_bf16 v[42:45], v[138:141], v[186:189], v[42:45]
	v_mfma_f32_16x16x32_bf16 v[30:33], v[130:133], v[194:197], v[30:33]
	v_mfma_f32_16x16x32_bf16 v[26:29], v[138:141], v[194:197], v[26:29]
	v_mfma_f32_16x16x32_bf16 v[14:17], v[130:133], v[202:205], v[14:17]
	v_mfma_f32_16x16x32_bf16 v[10:13], v[138:141], v[202:205], v[10:13]
	v_mfma_f32_16x16x32_bf16 v[62:65], v[134:137], v[170:173], v[62:65]
	v_mfma_f32_16x16x32_bf16 v[58:61], v[142:145], v[170:173], v[58:61]
	v_mfma_f32_16x16x32_bf16 v[46:49], v[134:137], v[190:193], v[46:49]
	v_mfma_f32_16x16x32_bf16 v[42:45], v[142:145], v[190:193], v[42:45]
	v_mfma_f32_16x16x32_bf16 v[30:33], v[134:137], v[198:201], v[30:33]
	v_mfma_f32_16x16x32_bf16 v[26:29], v[142:145], v[198:201], v[26:29]
	v_mfma_f32_16x16x32_bf16 v[14:17], v[134:137], v[206:209], v[14:17]
	v_mfma_f32_16x16x32_bf16 v[10:13], v[142:145], v[206:209], v[10:13]
	v_mfma_f32_16x16x32_bf16 v[54:57], v[146:149], v[166:169], v[54:57]
	v_mfma_f32_16x16x32_bf16 v[50:53], v[154:157], v[166:169], v[50:53]
	v_mfma_f32_16x16x32_bf16 v[38:41], v[146:149], v[186:189], v[38:41]
	v_mfma_f32_16x16x32_bf16 v[34:37], v[154:157], v[186:189], v[34:37]
	v_mfma_f32_16x16x32_bf16 v[22:25], v[146:149], v[194:197], v[22:25]
	v_mfma_f32_16x16x32_bf16 v[18:21], v[154:157], v[194:197], v[18:21]
	v_mfma_f32_16x16x32_bf16 v[6:9], v[146:149], v[202:205], v[6:9]
	v_mfma_f32_16x16x32_bf16 v[2:5], v[154:157], v[202:205], v[2:5]
	v_mfma_f32_16x16x32_bf16 v[54:57], v[150:153], v[170:173], v[54:57]
	v_mfma_f32_16x16x32_bf16 v[50:53], v[158:161], v[170:173], v[50:53]
	v_mfma_f32_16x16x32_bf16 v[38:41], v[150:153], v[190:193], v[38:41]
	v_mfma_f32_16x16x32_bf16 v[34:37], v[158:161], v[190:193], v[34:37]
	v_mfma_f32_16x16x32_bf16 v[22:25], v[150:153], v[198:201], v[22:25]
	v_mfma_f32_16x16x32_bf16 v[18:21], v[158:161], v[198:201], v[18:21]
	s_setprio 2
	s_barrier
	v_mfma_f32_16x16x32_bf16 v[6:9], v[150:153], v[206:209], v[6:9]
	v_mfma_f32_16x16x32_bf16 v[2:5], v[158:161], v[206:209], v[2:5]
	s_setprio 0
	s_add_i32 s78, s78, 2
	s_add_u32 s74, s74, 0x100
	s_addc_u32 s75, s75, 0
	s_add_u32 s24, s24, 0x100
	s_addc_u32 s25, s25, 0
	s_add_u32 s76, s76, 0x100
	s_addc_u32 s77, s77, 0
	s_cmp_gt_u32 s78, 29
	s_cbranch_scc0 .LBB0_2410
	s_and_b64 vcc, exec, s[8:9]
	s_cbranch_vccz .LBB0_2413
	s_barrier

.LBB0_2594:
	ds_read_b128 v[148:151], v143
	ds_read_b128 v[152:155], v143 offset:1024
	ds_read_b128 v[156:159], v143 offset:2048
	ds_read_b128 v[160:163], v143 offset:3072
	ds_read_b128 v[164:167], v144
	ds_read_b128 v[168:171], v144 offset:1024
	ds_read_b128 v[172:175], v144 offset:2048
	ds_read_b128 v[176:179], v144 offset:3072
	s_cmp_eq_u32 s70, 28
	s_cselect_b32 s21, s9, s65
	s_cselect_b32 s20, s63, s64
	s_cselect_b32 s23, s11, s67
	s_cselect_b32 s22, s62, s66
	ds_read_b128 v[180:183], v145
	ds_read_b128 v[184:187], v145 offset:1024
	ds_read_b128 v[188:191], v145 offset:2048
	ds_read_b128 v[192:195], v145 offset:3072
	ds_read_b128 v[196:199], v145 offset:4096
	ds_read_b128 v[200:203], v145 offset:5120
	ds_read_b128 v[204:207], v145 offset:6144
	ds_read_b128 v[208:211], v145 offset:7168
	s_add_u32 s74, s18, 0xfff80000
	s_addc_u32 s75, s19, -1
	s_mov_b32 s71, m0
	s_mov_b32 m0, s48
	s_nop 0
	global_load_lds_dwordx4 v138, s[74:75]
	s_mov_b32 m0, s71
	s_nop 0
	s_mov_b32 s71, m0
	s_mov_b32 m0, s57
	s_nop 0
	global_load_lds_dwordx4 v140, s[74:75]
	s_mov_b32 m0, s71
	s_nop 0
	s_mov_b32 s71, m0
	s_mov_b32 m0, s49
	s_nop 0
	global_load_lds_dwordx4 v138, s[18:19]
	s_mov_b32 m0, s71
	s_nop 0
	s_mov_b32 s71, m0
	s_mov_b32 m0, s58
	s_nop 0
	global_load_lds_dwordx4 v140, s[18:19]
	s_mov_b32 m0, s71
	s_waitcnt vmcnt(8)
	s_waitcnt lgkmcnt(0)
	s_barrier
	s_setprio 1
	v_mfma_f32_16x16x32_bf16 v[126:129], v[148:151], v[180:183], v[126:129]
	v_mfma_f32_16x16x32_bf16 v[122:125], v[156:159], v[180:183], v[122:125]
	v_mfma_f32_16x16x32_bf16 v[110:113], v[148:151], v[188:191], v[110:113]
	v_mfma_f32_16x16x32_bf16 v[106:109], v[156:159], v[188:191], v[106:109]
	v_mfma_f32_16x16x32_bf16 v[94:97], v[148:151], v[196:199], v[94:97]
	v_mfma_f32_16x16x32_bf16 v[90:93], v[156:159], v[196:199], v[90:93]
	v_mfma_f32_16x16x32_bf16 v[78:81], v[148:151], v[204:207], v[78:81]
	v_mfma_f32_16x16x32_bf16 v[74:77], v[156:159], v[204:207], v[74:77]
	v_mfma_f32_16x16x32_bf16 v[126:129], v[152:155], v[184:187], v[126:129]
	v_mfma_f32_16x16x32_bf16 v[122:125], v[160:163], v[184:187], v[122:125]
	v_mfma_f32_16x16x32_bf16 v[110:113], v[152:155], v[192:195], v[110:113]
	v_mfma_f32_16x16x32_bf16 v[106:109], v[160:163], v[192:195], v[106:109]
	v_mfma_f32_16x16x32_bf16 v[94:97], v[152:155], v[200:203], v[94:97]
	v_mfma_f32_16x16x32_bf16 v[90:93], v[160:163], v[200:203], v[90:93]
	v_mfma_f32_16x16x32_bf16 v[78:81], v[152:155], v[208:211], v[78:81]
	v_mfma_f32_16x16x32_bf16 v[74:77], v[160:163], v[208:211], v[74:77]
	v_mfma_f32_16x16x32_bf16 v[118:121], v[164:167], v[180:183], v[118:121]
	v_mfma_f32_16x16x32_bf16 v[114:117], v[172:175], v[180:183], v[114:117]
	v_mfma_f32_16x16x32_bf16 v[102:105], v[164:167], v[188:191], v[102:105]
	v_mfma_f32_16x16x32_bf16 v[98:101], v[172:175], v[188:191], v[98:101]
	v_mfma_f32_16x16x32_bf16 v[86:89], v[164:167], v[196:199], v[86:89]
	v_mfma_f32_16x16x32_bf16 v[82:85], v[172:175], v[196:199], v[82:85]
	v_mfma_f32_16x16x32_bf16 v[70:73], v[164:167], v[204:207], v[70:73]
	v_mfma_f32_16x16x32_bf16 v[66:69], v[172:175], v[204:207], v[66:69]
	v_mfma_f32_16x16x32_bf16 v[118:121], v[168:171], v[184:187], v[118:121]
	v_mfma_f32_16x16x32_bf16 v[114:117], v[176:179], v[184:187], v[114:117]
	v_mfma_f32_16x16x32_bf16 v[102:105], v[168:171], v[192:195], v[102:105]
	v_mfma_f32_16x16x32_bf16 v[98:101], v[176:179], v[192:195], v[98:101]
	v_mfma_f32_16x16x32_bf16 v[86:89], v[168:171], v[200:203], v[86:89]
	v_mfma_f32_16x16x32_bf16 v[82:85], v[176:179], v[200:203], v[82:85]
	s_setprio 2
	s_barrier
	v_mfma_f32_16x16x32_bf16 v[70:73], v[168:171], v[208:211], v[70:73]
	v_mfma_f32_16x16x32_bf16 v[66:69], v[176:179], v[208:211], v[66:69]
	s_setprio 0
	ds_read_b128 v[180:183], v145 offset:16384
	ds_read_b128 v[184:187], v145 offset:17408
	ds_read_b128 v[188:191], v145 offset:18432
	ds_read_b128 v[192:195], v145 offset:19456
	ds_read_b128 v[196:199], v145 offset:20480
	ds_read_b128 v[200:203], v145 offset:21504
	ds_read_b128 v[204:207], v145 offset:22528
	ds_read_b128 v[208:211], v145 offset:23552
	s_mov_b32 s71, m0
	s_mov_b32 m0, s35
	s_nop 0
	global_load_lds_dwordx4 v139, s[20:21]
	s_mov_b32 m0, s71
	s_add_u32 s74, s20, 0x80000
	s_mov_b32 s71, m0
	s_mov_b32 m0, s36
	s_nop 0
	global_load_lds_dwordx4 v141, s[20:21]
	s_mov_b32 m0, s71
	s_addc_u32 s75, s21, 0
	s_mov_b32 s71, m0
	s_mov_b32 m0, s37
	s_nop 0
	global_load_lds_dwordx4 v139, s[74:75]
	s_mov_b32 m0, s71
	s_nop 0
	s_mov_b32 s71, m0
	s_mov_b32 m0, s40
	s_nop 0
	global_load_lds_dwordx4 v141, s[74:75]
	s_mov_b32 m0, s71
	s_waitcnt vmcnt(4)
	s_waitcnt lgkmcnt(0)
	s_barrier
	s_setprio 1
	v_mfma_f32_16x16x32_bf16 v[62:65], v[148:151], v[180:183], v[62:65]
	v_mfma_f32_16x16x32_bf16 v[58:61], v[156:159], v[180:183], v[58:61]
	v_mfma_f32_16x16x32_bf16 v[46:49], v[148:151], v[188:191], v[46:49]
	v_mfma_f32_16x16x32_bf16 v[42:45], v[156:159], v[188:191], v[42:45]
	v_mfma_f32_16x16x32_bf16 v[30:33], v[148:151], v[196:199], v[30:33]
	v_mfma_f32_16x16x32_bf16 v[26:29], v[156:159], v[196:199], v[26:29]
	v_mfma_f32_16x16x32_bf16 v[14:17], v[148:151], v[204:207], v[14:17]
	v_mfma_f32_16x16x32_bf16 v[10:13], v[156:159], v[204:207], v[10:13]
	v_mfma_f32_16x16x32_bf16 v[62:65], v[152:155], v[184:187], v[62:65]
	v_mfma_f32_16x16x32_bf16 v[58:61], v[160:163], v[184:187], v[58:61]
	v_mfma_f32_16x16x32_bf16 v[46:49], v[152:155], v[192:195], v[46:49]
	v_mfma_f32_16x16x32_bf16 v[42:45], v[160:163], v[192:195], v[42:45]
	v_mfma_f32_16x16x32_bf16 v[30:33], v[152:155], v[200:203], v[30:33]
	v_mfma_f32_16x16x32_bf16 v[26:29], v[160:163], v[200:203], v[26:29]
	v_mfma_f32_16x16x32_bf16 v[14:17], v[152:155], v[208:211], v[14:17]
	v_mfma_f32_16x16x32_bf16 v[10:13], v[160:163], v[208:211], v[10:13]
	v_mfma_f32_16x16x32_bf16 v[54:57], v[164:167], v[180:183], v[54:57]
	v_mfma_f32_16x16x32_bf16 v[50:53], v[172:175], v[180:183], v[50:53]
	v_mfma_f32_16x16x32_bf16 v[38:41], v[164:167], v[188:191], v[38:41]
	v_mfma_f32_16x16x32_bf16 v[34:37], v[172:175], v[188:191], v[34:37]
	v_mfma_f32_16x16x32_bf16 v[22:25], v[164:167], v[196:199], v[22:25]
	v_mfma_f32_16x16x32_bf16 v[18:21], v[172:175], v[196:199], v[18:21]
	v_mfma_f32_16x16x32_bf16 v[6:9], v[164:167], v[204:207], v[6:9]
	v_mfma_f32_16x16x32_bf16 v[2:5], v[172:175], v[204:207], v[2:5]
	v_mfma_f32_16x16x32_bf16 v[54:57], v[168:171], v[184:187], v[54:57]
	v_mfma_f32_16x16x32_bf16 v[50:53], v[176:179], v[184:187], v[50:53]
	v_mfma_f32_16x16x32_bf16 v[38:41], v[168:171], v[192:195], v[38:41]
	v_mfma_f32_16x16x32_bf16 v[34:37], v[176:179], v[192:195], v[34:37]
	v_mfma_f32_16x16x32_bf16 v[22:25], v[168:171], v[200:203], v[22:25]
	v_mfma_f32_16x16x32_bf16 v[18:21], v[176:179], v[200:203], v[18:21]
	s_setprio 2
	s_barrier
	v_mfma_f32_16x16x32_bf16 v[6:9], v[168:171], v[208:211], v[6:9]
	v_mfma_f32_16x16x32_bf16 v[2:5], v[176:179], v[208:211], v[2:5]
	s_setprio 0
	ds_read_b128 v[148:151], v146
	ds_read_b128 v[152:155], v146 offset:1024
	ds_read_b128 v[156:159], v146 offset:2048
	ds_read_b128 v[160:163], v146 offset:3072
	ds_read_b128 v[164:167], v147
	ds_read_b128 v[168:171], v147 offset:1024
	ds_read_b128 v[172:175], v147 offset:2048
	ds_read_b128 v[176:179], v147 offset:3072
	ds_read_b128 v[180:183], v145 offset:32768
	ds_read_b128 v[184:187], v145 offset:33792
	ds_read_b128 v[188:191], v145 offset:34816
	ds_read_b128 v[192:195], v145 offset:35840
	ds_read_b128 v[196:199], v145 offset:36864
	ds_read_b128 v[200:203], v145 offset:37888
	ds_read_b128 v[204:207], v145 offset:38912
	ds_read_b128 v[208:211], v145 offset:39936
	s_mov_b32 s71, m0
	s_mov_b32 m0, s31
	s_nop 0
	global_load_lds_dwordx4 v138, s[22:23]
	s_mov_b32 m0, s71
	s_nop 0
	s_mov_b32 s71, m0
	s_mov_b32 m0, s41
	s_nop 0
	global_load_lds_dwordx4 v140, s[22:23]
	s_mov_b32 m0, s71
	s_add_u32 s22, s22, 0x80000
	s_addc_u32 s23, s23, 0
	s_mov_b32 s71, m0
	s_mov_b32 m0, s42
	s_nop 0
	global_load_lds_dwordx4 v138, s[22:23]
	s_mov_b32 m0, s71
	s_nop 0
	s_mov_b32 s71, m0
	s_mov_b32 m0, s43
	s_nop 0
	global_load_lds_dwordx4 v140, s[22:23]
	s_mov_b32 m0, s71
	s_waitcnt vmcnt(8)
	s_waitcnt lgkmcnt(0)
	s_barrier
	s_setprio 1
	v_mfma_f32_16x16x32_bf16 v[126:129], v[148:151], v[180:183], v[126:129]
	v_mfma_f32_16x16x32_bf16 v[122:125], v[156:159], v[180:183], v[122:125]
	v_mfma_f32_16x16x32_bf16 v[110:113], v[148:151], v[188:191], v[110:113]
	v_mfma_f32_16x16x32_bf16 v[106:109], v[156:159], v[188:191], v[106:109]
	v_mfma_f32_16x16x32_bf16 v[94:97], v[148:151], v[196:199], v[94:97]
	v_mfma_f32_16x16x32_bf16 v[90:93], v[156:159], v[196:199], v[90:93]
	v_mfma_f32_16x16x32_bf16 v[78:81], v[148:151], v[204:207], v[78:81]
	v_mfma_f32_16x16x32_bf16 v[74:77], v[156:159], v[204:207], v[74:77]
	v_mfma_f32_16x16x32_bf16 v[126:129], v[152:155], v[184:187], v[126:129]
	v_mfma_f32_16x16x32_bf16 v[122:125], v[160:163], v[184:187], v[122:125]
	v_mfma_f32_16x16x32_bf16 v[110:113], v[152:155], v[192:195], v[110:113]
	v_mfma_f32_16x16x32_bf16 v[106:109], v[160:163], v[192:195], v[106:109]
	v_mfma_f32_16x16x32_bf16 v[94:97], v[152:155], v[200:203], v[94:97]
	v_mfma_f32_16x16x32_bf16 v[90:93], v[160:163], v[200:203], v[90:93]
	v_mfma_f32_16x16x32_bf16 v[78:81], v[152:155], v[208:211], v[78:81]
	v_mfma_f32_16x16x32_bf16 v[74:77], v[160:163], v[208:211], v[74:77]
	v_mfma_f32_16x16x32_bf16 v[118:121], v[164:167], v[180:183], v[118:121]
	v_mfma_f32_16x16x32_bf16 v[114:117], v[172:175], v[180:183], v[114:117]
	v_mfma_f32_16x16x32_bf16 v[102:105], v[164:167], v[188:191], v[102:105]
	v_mfma_f32_16x16x32_bf16 v[98:101], v[172:175], v[188:191], v[98:101]
	v_mfma_f32_16x16x32_bf16 v[86:89], v[164:167], v[196:199], v[86:89]
	v_mfma_f32_16x16x32_bf16 v[82:85], v[172:175], v[196:199], v[82:85]
	v_mfma_f32_16x16x32_bf16 v[70:73], v[164:167], v[204:207], v[70:73]
	v_mfma_f32_16x16x32_bf16 v[66:69], v[172:175], v[204:207], v[66:69]
	v_mfma_f32_16x16x32_bf16 v[118:121], v[168:171], v[184:187], v[118:121]
	v_mfma_f32_16x16x32_bf16 v[114:117], v[176:179], v[184:187], v[114:117]
	v_mfma_f32_16x16x32_bf16 v[102:105], v[168:171], v[192:195], v[102:105]
	v_mfma_f32_16x16x32_bf16 v[98:101], v[176:179], v[192:195], v[98:101]
	v_mfma_f32_16x16x32_bf16 v[86:89], v[168:171], v[200:203], v[86:89]
	v_mfma_f32_16x16x32_bf16 v[82:85], v[176:179], v[200:203], v[82:85]
	s_setprio 2
	s_barrier
	v_mfma_f32_16x16x32_bf16 v[70:73], v[168:171], v[208:211], v[70:73]
	v_mfma_f32_16x16x32_bf16 v[66:69], v[176:179], v[208:211], v[66:69]
	s_setprio 0
	ds_read_b128 v[180:183], v145 offset:49152
	ds_read_b128 v[184:187], v145 offset:50176
	ds_read_b128 v[188:191], v145 offset:51200
	ds_read_b128 v[192:195], v145 offset:52224
	ds_read_b128 v[196:199], v145 offset:53248
	ds_read_b128 v[200:203], v145 offset:54272
	ds_read_b128 v[204:207], v145 offset:55296
	ds_read_b128 v[208:211], v145 offset:56320
	s_add_u32 s22, s20, 0x80
	s_addc_u32 s23, s21, 0
	s_mov_b32 s71, m0
	s_mov_b32 m0, s44
	s_nop 0
	global_load_lds_dwordx4 v139, s[22:23]
	s_mov_b32 m0, s71
	s_add_u32 s20, s20, 0x80080
	s_mov_b32 s71, m0
	s_mov_b32 m0, s45
	s_nop 0
	global_load_lds_dwordx4 v141, s[22:23]
	s_mov_b32 m0, s71
	s_addc_u32 s21, s21, 0
	s_mov_b32 s22, m0
	s_mov_b32 m0, s46
	s_nop 0
	global_load_lds_dwordx4 v139, s[20:21]
	s_mov_b32 m0, s22
	s_nop 0
	s_mov_b32 s22, m0
	s_mov_b32 m0, s47
	s_nop 0
	global_load_lds_dwordx4 v141, s[20:21]
	s_mov_b32 m0, s22
	s_waitcnt vmcnt(4)
	s_waitcnt lgkmcnt(0)
	s_barrier
	s_setprio 1
	v_mfma_f32_16x16x32_bf16 v[62:65], v[148:151], v[180:183], v[62:65]
	v_mfma_f32_16x16x32_bf16 v[58:61], v[156:159], v[180:183], v[58:61]
	v_mfma_f32_16x16x32_bf16 v[46:49], v[148:151], v[188:191], v[46:49]
	v_mfma_f32_16x16x32_bf16 v[42:45], v[156:159], v[188:191], v[42:45]
	v_mfma_f32_16x16x32_bf16 v[30:33], v[148:151], v[196:199], v[30:33]
	v_mfma_f32_16x16x32_bf16 v[26:29], v[156:159], v[196:199], v[26:29]
	v_mfma_f32_16x16x32_bf16 v[14:17], v[148:151], v[204:207], v[14:17]
	v_mfma_f32_16x16x32_bf16 v[10:13], v[156:159], v[204:207], v[10:13]
	v_mfma_f32_16x16x32_bf16 v[62:65], v[152:155], v[184:187], v[62:65]
	v_mfma_f32_16x16x32_bf16 v[58:61], v[160:163], v[184:187], v[58:61]
	v_mfma_f32_16x16x32_bf16 v[46:49], v[152:155], v[192:195], v[46:49]
	v_mfma_f32_16x16x32_bf16 v[42:45], v[160:163], v[192:195], v[42:45]
	v_mfma_f32_16x16x32_bf16 v[30:33], v[152:155], v[200:203], v[30:33]
	v_mfma_f32_16x16x32_bf16 v[26:29], v[160:163], v[200:203], v[26:29]
	v_mfma_f32_16x16x32_bf16 v[14:17], v[152:155], v[208:211], v[14:17]
	v_mfma_f32_16x16x32_bf16 v[10:13], v[160:163], v[208:211], v[10:13]
	v_mfma_f32_16x16x32_bf16 v[54:57], v[164:167], v[180:183], v[54:57]
	v_mfma_f32_16x16x32_bf16 v[50:53], v[172:175], v[180:183], v[50:53]
	v_mfma_f32_16x16x32_bf16 v[38:41], v[164:167], v[188:191], v[38:41]
	v_mfma_f32_16x16x32_bf16 v[34:37], v[172:175], v[188:191], v[34:37]
	v_mfma_f32_16x16x32_bf16 v[22:25], v[164:167], v[196:199], v[22:25]
	v_mfma_f32_16x16x32_bf16 v[18:21], v[172:175], v[196:199], v[18:21]
	v_mfma_f32_16x16x32_bf16 v[6:9], v[164:167], v[204:207], v[6:9]
	v_mfma_f32_16x16x32_bf16 v[2:5], v[172:175], v[204:207], v[2:5]
	v_mfma_f32_16x16x32_bf16 v[54:57], v[168:171], v[184:187], v[54:57]
	v_mfma_f32_16x16x32_bf16 v[50:53], v[176:179], v[184:187], v[50:53]
	v_mfma_f32_16x16x32_bf16 v[38:41], v[168:171], v[192:195], v[38:41]
	v_mfma_f32_16x16x32_bf16 v[34:37], v[176:179], v[192:195], v[34:37]
	v_mfma_f32_16x16x32_bf16 v[22:25], v[168:171], v[200:203], v[22:25]
	v_mfma_f32_16x16x32_bf16 v[18:21], v[176:179], v[200:203], v[18:21]
	s_setprio 2
	s_barrier
	v_mfma_f32_16x16x32_bf16 v[6:9], v[168:171], v[208:211], v[6:9]
	v_mfma_f32_16x16x32_bf16 v[2:5], v[176:179], v[208:211], v[2:5]
	s_setprio 0
	s_add_i32 s70, s70, 2
	s_add_u32 s64, s64, 0x100
	s_addc_u32 s65, s65, 0
	s_add_u32 s18, s18, 0x100
	s_addc_u32 s19, s19, 0
	s_add_u32 s66, s66, 0x100
	s_addc_u32 s67, s67, 0
	s_cmp_gt_u32 s70, 29
	s_cbranch_scc0 .LBB0_2594
	s_and_b64 vcc, exec, s[6:7]
	s_cbranch_vccz .LBB0_2597
	s_barrier

.LBB0_2792:
	ds_read_b128 v[130:133], v181
	ds_read_b128 v[134:137], v181 offset:1024
	ds_read_b128 v[138:141], v181 offset:2048
	ds_read_b128 v[142:145], v181 offset:3072
	ds_read_b128 v[150:153], v182
	ds_read_b128 v[154:157], v182 offset:1024
	ds_read_b128 v[158:161], v182 offset:2048
	ds_read_b128 v[162:165], v182 offset:3072
	s_cmpk_eq_i32 s69, 0x52
	s_cselect_b32 s31, s19, s66
	s_cselect_b32 s30, s64, s65
	s_cselect_b32 s35, s21, s68
	s_cselect_b32 s34, s63, s67
	ds_read_b128 v[166:169], v183
	ds_read_b128 v[170:173], v183 offset:1024
	ds_read_b128 v[186:189], v183 offset:2048
	ds_read_b128 v[190:193], v183 offset:3072
	ds_read_b128 v[194:197], v183 offset:4096
	ds_read_b128 v[198:201], v183 offset:5120
	ds_read_b128 v[202:205], v183 offset:6144
	ds_read_b128 v[206:209], v183 offset:7168
	s_add_u32 s70, s28, 0xffffc000
	s_addc_u32 s71, s29, -1
	s_mov_b32 s73, m0
	s_mov_b32 m0, s57
	s_nop 0
	global_load_lds_dwordx4 v1, s[70:71]
	s_mov_b32 m0, s73
	s_nop 0
	s_mov_b32 s73, m0
	s_mov_b32 m0, s59
	s_nop 0
	global_load_lds_dwordx4 v177, s[70:71]
	s_mov_b32 m0, s73
	s_mov_b32 s70, m0
	s_mov_b32 m0, s58
	s_nop 0
	global_load_lds_dwordx4 v1, s[28:29]
	s_mov_b32 m0, s70
	s_nop 0
	s_mov_b32 s70, m0
	s_mov_b32 m0, s60
	s_nop 0
	global_load_lds_dwordx4 v177, s[28:29]
	s_mov_b32 m0, s70
	s_waitcnt vmcnt(8)
	s_waitcnt lgkmcnt(0)
	s_barrier
	s_setprio 1
	v_mfma_f32_16x16x32_bf16 v[126:129], v[130:133], v[166:169], v[126:129]
	v_mfma_f32_16x16x32_bf16 v[122:125], v[138:141], v[166:169], v[122:125]
	v_mfma_f32_16x16x32_bf16 v[118:121], v[130:133], v[186:189], v[118:121]
	v_mfma_f32_16x16x32_bf16 v[110:113], v[138:141], v[186:189], v[110:113]
	v_mfma_f32_16x16x32_bf16 v[94:97], v[130:133], v[194:197], v[94:97]
	v_mfma_f32_16x16x32_bf16 v[90:93], v[138:141], v[194:197], v[90:93]
	v_mfma_f32_16x16x32_bf16 v[86:89], v[130:133], v[202:205], v[86:89]
	v_mfma_f32_16x16x32_bf16 v[78:81], v[138:141], v[202:205], v[78:81]
	v_mfma_f32_16x16x32_bf16 v[126:129], v[134:137], v[170:173], v[126:129]
	v_mfma_f32_16x16x32_bf16 v[122:125], v[142:145], v[170:173], v[122:125]
	v_mfma_f32_16x16x32_bf16 v[118:121], v[134:137], v[190:193], v[118:121]
	v_mfma_f32_16x16x32_bf16 v[110:113], v[142:145], v[190:193], v[110:113]
	v_mfma_f32_16x16x32_bf16 v[94:97], v[134:137], v[198:201], v[94:97]
	v_mfma_f32_16x16x32_bf16 v[90:93], v[142:145], v[198:201], v[90:93]
	v_mfma_f32_16x16x32_bf16 v[86:89], v[134:137], v[206:209], v[86:89]
	v_mfma_f32_16x16x32_bf16 v[78:81], v[142:145], v[206:209], v[78:81]
	v_mfma_f32_16x16x32_bf16 v[114:117], v[150:153], v[166:169], v[114:117]
	v_mfma_f32_16x16x32_bf16 v[106:109], v[158:161], v[166:169], v[106:109]
	v_mfma_f32_16x16x32_bf16 v[102:105], v[150:153], v[186:189], v[102:105]
	v_mfma_f32_16x16x32_bf16 v[98:101], v[158:161], v[186:189], v[98:101]
	v_mfma_f32_16x16x32_bf16 v[82:85], v[150:153], v[194:197], v[82:85]
	v_mfma_f32_16x16x32_bf16 v[74:77], v[158:161], v[194:197], v[74:77]
	v_mfma_f32_16x16x32_bf16 v[70:73], v[150:153], v[202:205], v[70:73]
	v_mfma_f32_16x16x32_bf16 v[66:69], v[158:161], v[202:205], v[66:69]
	v_mfma_f32_16x16x32_bf16 v[114:117], v[154:157], v[170:173], v[114:117]
	v_mfma_f32_16x16x32_bf16 v[106:109], v[162:165], v[170:173], v[106:109]
	v_mfma_f32_16x16x32_bf16 v[102:105], v[154:157], v[190:193], v[102:105]
	v_mfma_f32_16x16x32_bf16 v[98:101], v[162:165], v[190:193], v[98:101]
	v_mfma_f32_16x16x32_bf16 v[82:85], v[154:157], v[198:201], v[82:85]
	v_mfma_f32_16x16x32_bf16 v[74:77], v[162:165], v[198:201], v[74:77]
	s_setprio 2
	s_barrier
	v_mfma_f32_16x16x32_bf16 v[70:73], v[154:157], v[206:209], v[70:73]
	v_mfma_f32_16x16x32_bf16 v[66:69], v[162:165], v[206:209], v[66:69]
	s_setprio 0
	ds_read_b128 v[166:169], v183 offset:16384
	ds_read_b128 v[170:173], v183 offset:17408
	ds_read_b128 v[186:189], v183 offset:18432
	ds_read_b128 v[190:193], v183 offset:19456
	ds_read_b128 v[194:197], v183 offset:20480
	ds_read_b128 v[198:201], v183 offset:21504
	ds_read_b128 v[202:205], v183 offset:22528
	ds_read_b128 v[206:209], v183 offset:23552
	s_mov_b32 s70, m0
	s_mov_b32 m0, s27
	s_nop 0
	global_load_lds_dwordx4 v176, s[30:31]
	s_mov_b32 m0, s70
	s_nop 0
	s_mov_b32 s70, m0
	s_mov_b32 m0, s45
	s_nop 0
	global_load_lds_dwordx4 v178, s[30:31]
	s_mov_b32 m0, s70
	s_add_u32 s70, s30, 0x4000
	s_addc_u32 s71, s31, 0
	s_mov_b32 s73, m0
	s_mov_b32 m0, s46
	s_nop 0
	global_load_lds_dwordx4 v176, s[70:71]
	s_mov_b32 m0, s73
	s_nop 0
	s_mov_b32 s73, m0
	s_mov_b32 m0, s47
	s_nop 0
	global_load_lds_dwordx4 v178, s[70:71]
	s_mov_b32 m0, s73
	s_waitcnt vmcnt(4)
	s_waitcnt lgkmcnt(0)
	s_barrier
	s_setprio 1
	v_mfma_f32_16x16x32_bf16 v[62:65], v[130:133], v[166:169], v[62:65]
	v_mfma_f32_16x16x32_bf16 v[58:61], v[138:141], v[166:169], v[58:61]
	v_mfma_f32_16x16x32_bf16 v[46:49], v[130:133], v[186:189], v[46:49]
	v_mfma_f32_16x16x32_bf16 v[42:45], v[138:141], v[186:189], v[42:45]
	v_mfma_f32_16x16x32_bf16 v[30:33], v[130:133], v[194:197], v[30:33]
	v_mfma_f32_16x16x32_bf16 v[26:29], v[138:141], v[194:197], v[26:29]
	v_mfma_f32_16x16x32_bf16 v[14:17], v[130:133], v[202:205], v[14:17]
	v_mfma_f32_16x16x32_bf16 v[10:13], v[138:141], v[202:205], v[10:13]
	v_mfma_f32_16x16x32_bf16 v[62:65], v[134:137], v[170:173], v[62:65]
	v_mfma_f32_16x16x32_bf16 v[58:61], v[142:145], v[170:173], v[58:61]
	v_mfma_f32_16x16x32_bf16 v[46:49], v[134:137], v[190:193], v[46:49]
	v_mfma_f32_16x16x32_bf16 v[42:45], v[142:145], v[190:193], v[42:45]
	v_mfma_f32_16x16x32_bf16 v[30:33], v[134:137], v[198:201], v[30:33]
	v_mfma_f32_16x16x32_bf16 v[26:29], v[142:145], v[198:201], v[26:29]
	v_mfma_f32_16x16x32_bf16 v[14:17], v[134:137], v[206:209], v[14:17]
	v_mfma_f32_16x16x32_bf16 v[10:13], v[142:145], v[206:209], v[10:13]
	v_mfma_f32_16x16x32_bf16 v[54:57], v[150:153], v[166:169], v[54:57]
	v_mfma_f32_16x16x32_bf16 v[50:53], v[158:161], v[166:169], v[50:53]
	v_mfma_f32_16x16x32_bf16 v[38:41], v[150:153], v[186:189], v[38:41]
	v_mfma_f32_16x16x32_bf16 v[34:37], v[158:161], v[186:189], v[34:37]
	v_mfma_f32_16x16x32_bf16 v[22:25], v[150:153], v[194:197], v[22:25]
	v_mfma_f32_16x16x32_bf16 v[18:21], v[158:161], v[194:197], v[18:21]
	v_mfma_f32_16x16x32_bf16 v[6:9], v[150:153], v[202:205], v[6:9]
	v_mfma_f32_16x16x32_bf16 v[2:5], v[158:161], v[202:205], v[2:5]
	v_mfma_f32_16x16x32_bf16 v[54:57], v[154:157], v[170:173], v[54:57]
	v_mfma_f32_16x16x32_bf16 v[50:53], v[162:165], v[170:173], v[50:53]
	v_mfma_f32_16x16x32_bf16 v[38:41], v[154:157], v[190:193], v[38:41]
	v_mfma_f32_16x16x32_bf16 v[34:37], v[162:165], v[190:193], v[34:37]
	v_mfma_f32_16x16x32_bf16 v[22:25], v[154:157], v[198:201], v[22:25]
	v_mfma_f32_16x16x32_bf16 v[18:21], v[162:165], v[198:201], v[18:21]
	s_setprio 2
	s_barrier
	v_mfma_f32_16x16x32_bf16 v[6:9], v[154:157], v[206:209], v[6:9]
	v_mfma_f32_16x16x32_bf16 v[2:5], v[162:165], v[206:209], v[2:5]
	s_setprio 0
	ds_read_b128 v[130:133], v184
	ds_read_b128 v[134:137], v184 offset:1024
	ds_read_b128 v[138:141], v184 offset:2048
	ds_read_b128 v[142:145], v184 offset:3072
	ds_read_b128 v[150:153], v185
	ds_read_b128 v[154:157], v185 offset:1024
	ds_read_b128 v[158:161], v185 offset:2048
	ds_read_b128 v[162:165], v185 offset:3072
	ds_read_b128 v[166:169], v183 offset:32768
	ds_read_b128 v[170:173], v183 offset:33792
	ds_read_b128 v[186:189], v183 offset:34816
	ds_read_b128 v[190:193], v183 offset:35840
	ds_read_b128 v[194:197], v183 offset:36864
	ds_read_b128 v[198:201], v183 offset:37888
	ds_read_b128 v[202:205], v183 offset:38912
	ds_read_b128 v[206:209], v183 offset:39936
	s_mov_b32 s70, m0
	s_mov_b32 m0, s44
	s_nop 0
	global_load_lds_dwordx4 v1, s[34:35]
	s_mov_b32 m0, s70
	s_nop 0
	s_mov_b32 s70, m0
	s_mov_b32 m0, s48
	s_nop 0
	global_load_lds_dwordx4 v177, s[34:35]
	s_mov_b32 m0, s70
	s_add_u32 s34, s34, 0x4000
	s_addc_u32 s35, s35, 0
	s_mov_b32 s70, m0
	s_mov_b32 m0, s49
	s_nop 0
	global_load_lds_dwordx4 v1, s[34:35]
	s_mov_b32 m0, s70
	s_nop 0
	s_mov_b32 s70, m0
	s_mov_b32 m0, s50
	s_nop 0
	global_load_lds_dwordx4 v177, s[34:35]
	s_mov_b32 m0, s70
	s_waitcnt vmcnt(8)
	s_waitcnt lgkmcnt(0)
	s_barrier
	s_setprio 1
	v_mfma_f32_16x16x32_bf16 v[126:129], v[130:133], v[166:169], v[126:129]
	v_mfma_f32_16x16x32_bf16 v[122:125], v[138:141], v[166:169], v[122:125]
	v_mfma_f32_16x16x32_bf16 v[118:121], v[130:133], v[186:189], v[118:121]
	v_mfma_f32_16x16x32_bf16 v[110:113], v[138:141], v[186:189], v[110:113]
	v_mfma_f32_16x16x32_bf16 v[94:97], v[130:133], v[194:197], v[94:97]
	v_mfma_f32_16x16x32_bf16 v[90:93], v[138:141], v[194:197], v[90:93]
	v_mfma_f32_16x16x32_bf16 v[86:89], v[130:133], v[202:205], v[86:89]
	v_mfma_f32_16x16x32_bf16 v[78:81], v[138:141], v[202:205], v[78:81]
	v_mfma_f32_16x16x32_bf16 v[126:129], v[134:137], v[170:173], v[126:129]
	v_mfma_f32_16x16x32_bf16 v[122:125], v[142:145], v[170:173], v[122:125]
	v_mfma_f32_16x16x32_bf16 v[118:121], v[134:137], v[190:193], v[118:121]
	v_mfma_f32_16x16x32_bf16 v[110:113], v[142:145], v[190:193], v[110:113]
	v_mfma_f32_16x16x32_bf16 v[94:97], v[134:137], v[198:201], v[94:97]
	v_mfma_f32_16x16x32_bf16 v[90:93], v[142:145], v[198:201], v[90:93]
	v_mfma_f32_16x16x32_bf16 v[86:89], v[134:137], v[206:209], v[86:89]
	v_mfma_f32_16x16x32_bf16 v[78:81], v[142:145], v[206:209], v[78:81]
	v_mfma_f32_16x16x32_bf16 v[114:117], v[150:153], v[166:169], v[114:117]
	v_mfma_f32_16x16x32_bf16 v[106:109], v[158:161], v[166:169], v[106:109]
	v_mfma_f32_16x16x32_bf16 v[102:105], v[150:153], v[186:189], v[102:105]
	v_mfma_f32_16x16x32_bf16 v[98:101], v[158:161], v[186:189], v[98:101]
	v_mfma_f32_16x16x32_bf16 v[82:85], v[150:153], v[194:197], v[82:85]
	v_mfma_f32_16x16x32_bf16 v[74:77], v[158:161], v[194:197], v[74:77]
	v_mfma_f32_16x16x32_bf16 v[70:73], v[150:153], v[202:205], v[70:73]
	v_mfma_f32_16x16x32_bf16 v[66:69], v[158:161], v[202:205], v[66:69]
	v_mfma_f32_16x16x32_bf16 v[114:117], v[154:157], v[170:173], v[114:117]
	v_mfma_f32_16x16x32_bf16 v[106:109], v[162:165], v[170:173], v[106:109]
	v_mfma_f32_16x16x32_bf16 v[102:105], v[154:157], v[190:193], v[102:105]
	v_mfma_f32_16x16x32_bf16 v[98:101], v[162:165], v[190:193], v[98:101]
	v_mfma_f32_16x16x32_bf16 v[82:85], v[154:157], v[198:201], v[82:85]
	v_mfma_f32_16x16x32_bf16 v[74:77], v[162:165], v[198:201], v[74:77]
	s_setprio 2
	s_barrier
	v_mfma_f32_16x16x32_bf16 v[70:73], v[154:157], v[206:209], v[70:73]
	v_mfma_f32_16x16x32_bf16 v[66:69], v[162:165], v[206:209], v[66:69]
	s_setprio 0
	ds_read_b128 v[166:169], v183 offset:49152
	ds_read_b128 v[170:173], v183 offset:50176
	ds_read_b128 v[186:189], v183 offset:51200
	ds_read_b128 v[190:193], v183 offset:52224
	ds_read_b128 v[194:197], v183 offset:53248
	ds_read_b128 v[198:201], v183 offset:54272
	ds_read_b128 v[202:205], v183 offset:55296
	ds_read_b128 v[206:209], v183 offset:56320
	s_add_u32 s34, s30, 0x40000
	s_addc_u32 s35, s31, 0
	s_mov_b32 s70, m0
	s_mov_b32 m0, s51
	s_nop 0
	global_load_lds_dwordx4 v176, s[34:35]
	s_mov_b32 m0, s70
	s_add_u32 s30, s30, 0x44000
	s_mov_b32 s70, m0
	s_mov_b32 m0, s52
	s_nop 0
	global_load_lds_dwordx4 v178, s[34:35]
	s_mov_b32 m0, s70
	s_addc_u32 s31, s31, 0
	s_mov_b32 s34, m0
	s_mov_b32 m0, s53
	s_nop 0
	global_load_lds_dwordx4 v176, s[30:31]
	s_mov_b32 m0, s34
	s_nop 0
	s_mov_b32 s34, m0
	s_mov_b32 m0, s54
	s_nop 0
	global_load_lds_dwordx4 v178, s[30:31]
	s_mov_b32 m0, s34
	s_waitcnt vmcnt(4)
	s_waitcnt lgkmcnt(0)
	s_barrier
	s_setprio 1
	v_mfma_f32_16x16x32_bf16 v[62:65], v[130:133], v[166:169], v[62:65]
	v_mfma_f32_16x16x32_bf16 v[58:61], v[138:141], v[166:169], v[58:61]
	v_mfma_f32_16x16x32_bf16 v[46:49], v[130:133], v[186:189], v[46:49]
	v_mfma_f32_16x16x32_bf16 v[42:45], v[138:141], v[186:189], v[42:45]
	v_mfma_f32_16x16x32_bf16 v[30:33], v[130:133], v[194:197], v[30:33]
	v_mfma_f32_16x16x32_bf16 v[26:29], v[138:141], v[194:197], v[26:29]
	v_mfma_f32_16x16x32_bf16 v[14:17], v[130:133], v[202:205], v[14:17]
	v_mfma_f32_16x16x32_bf16 v[10:13], v[138:141], v[202:205], v[10:13]
	v_mfma_f32_16x16x32_bf16 v[62:65], v[134:137], v[170:173], v[62:65]
	v_mfma_f32_16x16x32_bf16 v[58:61], v[142:145], v[170:173], v[58:61]
	v_mfma_f32_16x16x32_bf16 v[46:49], v[134:137], v[190:193], v[46:49]
	v_mfma_f32_16x16x32_bf16 v[42:45], v[142:145], v[190:193], v[42:45]
	v_mfma_f32_16x16x32_bf16 v[30:33], v[134:137], v[198:201], v[30:33]
	v_mfma_f32_16x16x32_bf16 v[26:29], v[142:145], v[198:201], v[26:29]
	v_mfma_f32_16x16x32_bf16 v[14:17], v[134:137], v[206:209], v[14:17]
	v_mfma_f32_16x16x32_bf16 v[10:13], v[142:145], v[206:209], v[10:13]
	v_mfma_f32_16x16x32_bf16 v[54:57], v[150:153], v[166:169], v[54:57]
	v_mfma_f32_16x16x32_bf16 v[50:53], v[158:161], v[166:169], v[50:53]
	v_mfma_f32_16x16x32_bf16 v[38:41], v[150:153], v[186:189], v[38:41]
	v_mfma_f32_16x16x32_bf16 v[34:37], v[158:161], v[186:189], v[34:37]
	v_mfma_f32_16x16x32_bf16 v[22:25], v[150:153], v[194:197], v[22:25]
	v_mfma_f32_16x16x32_bf16 v[18:21], v[158:161], v[194:197], v[18:21]
	v_mfma_f32_16x16x32_bf16 v[6:9], v[150:153], v[202:205], v[6:9]
	v_mfma_f32_16x16x32_bf16 v[2:5], v[158:161], v[202:205], v[2:5]
	v_mfma_f32_16x16x32_bf16 v[54:57], v[154:157], v[170:173], v[54:57]
	v_mfma_f32_16x16x32_bf16 v[50:53], v[162:165], v[170:173], v[50:53]
	v_mfma_f32_16x16x32_bf16 v[38:41], v[154:157], v[190:193], v[38:41]
	v_mfma_f32_16x16x32_bf16 v[34:37], v[162:165], v[190:193], v[34:37]
	v_mfma_f32_16x16x32_bf16 v[22:25], v[154:157], v[198:201], v[22:25]
	v_mfma_f32_16x16x32_bf16 v[18:21], v[162:165], v[198:201], v[18:21]
	s_setprio 2
	s_barrier
	v_mfma_f32_16x16x32_bf16 v[6:9], v[154:157], v[206:209], v[6:9]
	v_mfma_f32_16x16x32_bf16 v[2:5], v[162:165], v[206:209], v[2:5]
	s_setprio 0
	s_add_i32 s69, s69, 2
	s_add_u32 s65, s65, 0x80000
	s_addc_u32 s66, s66, 0
	s_add_u32 s28, s28, 0x400000
	s_addc_u32 s29, s29, 0
	s_add_u32 s67, s67, 0x400000
	s_addc_u32 s68, s68, 0
	s_cmpk_gt_u32 s69, 0x53
	s_cbranch_scc0 .LBB0_2792
	s_and_b64 vcc, exec, s[8:9]
	s_cbranch_vccz .LBB0_2795
	s_barrier
